# k26 with the early-barrier tail MFMAs at s_setprio 3 instead of 2
# baseline (speedup 1.0000x reference)
;     __device__ bool next(int i, Unit& u) const { if (i >= 2) return false; const int x = c & 7, j = c >> 3; u.pm = 32 * i + 4 * x + (j & 3); u.pn = j >> 2; return true; }
; #define PG8_STAGE(bufoff, gbase, voff) do { _Pragma("unroll") for (int _i = 0; _i < 2; ++_i) \
;         __builtin_amdgcn_global_load_lds((const unsigned*)((const char*)(gbase) + (voff)[_i]), (LAS unsigned*)(lds + (bufoff) + ldsw + _i * 8192), 16, 0, 0); } while (0)
; #define PG8_LDA(dst, b, h) do { _Pragma("unroll") for (int m = 0; m < 4; ++m) _Pragma("unroll") for (int k = 0; k < 2; ++k) dst[m][k] = *(const LAS bf16x8*)(lds + PG8_SA(b, h) + aoff + m * 2048 + k * 1024); } while (0)
; #define PG8_LDB(dst, b, h) do { _Pragma("unroll") for (int n = 0; n < 2; ++n) _Pragma("unroll") for (int k = 0; k < 2; ++k) dst[n][k] = *(const LAS bf16x8*)(lds + PG8_SB(b, h) + boff + n * 2048 + k * 1024); } while (0)
; #define PG8_WAIT_V(n) asm volatile("s_waitcnt vmcnt(" #n ")" ::: "memory")
; #define PG8_WAIT_L(n) asm volatile("s_waitcnt lgkmcnt(" #n ")" ::: "memory")
; #define PG8_BAR __builtin_amdgcn_s_barrier()
; template <class Epi, class Sched, bool ALIGN_EPI = true>
; __device__ __forceinline__ void gemm_phase(LAS unsigned char* lds, const Gemm g, const Sched& S, const Epi& E) {
;     ...
;         const bool has_next = S.next(ui + 1, nxt);
;         const char* nA = has_next ? (const char*)g.A + ((size_t)nxt.pm * BM * g.lda + (size_t)nxt.pn * g.a_pn_off) * 2 : cA; const char* nB = has_next ? (const char*)g.Bt + (size_t)nxt.pn * BM * g.ldb * 2 : cB;
;         for (int t = 0; t < nt; t += 2) {
;             const bool last = (t == nt - 2);
;             const char* a1 = cA + (size_t)(t + 1) * kstep;
;             const char* a2 = last ? nA : cA + (size_t)(t + 2) * kstep; const char* b2 = last ? nB : cB + (size_t)(t + 2) * kstep;
;             const char* a3 = a2 + kstep; const char* b3 = b2 + kstep;
;             PG8_LDB(B0, 0, 0); PG8_LDB(B1, 0, 1); PG8_SCHED; PG8_LDA(At, 0, 0); PG8_STAGE(PG8_SA(1, 1), a1 + hA, voffA);
;             PG8_WAIT_V(8); PG8_WAIT_L(0); PG8_BAR; PG8_MMA(0, 0, At, B0); PG8_MMA(0, 1, At, B1); PG8_BAR; PG8_SCHED;
;             PG8_LDA(At, 0, 1); PG8_STAGE(PG8_SB(0, 0), b2, voffB); PG8_STAGE(PG8_SB(0, 1), b2 + hB, voffB); PG8_STAGE(PG8_SA(0, 0), a2, voffA);
;             PG8_WAIT_V(8); PG8_WAIT_L(0); PG8_BAR; PG8_MMA(1, 0, At, B0); PG8_MMA(1, 1, At, B1); PG8_BAR; PG8_SCHED;
.LBB0_76:
	s_ashr_i32 s15, s14, 31
	s_lshl_b64 s[18:19], s[14:15], 20
	s_add_u32 s38, s46, s18
	s_addc_u32 s39, s47, s19
	s_and_b64 s[18:19], s[4:5], exec
	s_cselect_b32 s15, s39, s7
	s_cselect_b32 s17, s38, s6
	s_ashr_i32 s13, s12, 31
	s_lshl_b64 s[18:19], s[12:13], 20
	s_add_u32 s40, s53, s18
	s_addc_u32 s41, s58, s19
	s_and_b64 s[18:19], s[4:5], exec
	s_cselect_b32 s13, s41, s43
	s_cselect_b32 s18, s40, s42
	s_add_u32 s6, s6, 0x80080
	s_addc_u32 s7, s7, 0
	s_add_u32 s19, s42, 0x100
	s_addc_u32 s24, s43, 0
	s_mov_b32 s25, -2
	s_add_u32 s26, s6, 0xfff80080
	s_addc_u32 s27, s7, -1
	s_add_i32 s30, 0, 0x10000
	s_cmp_eq_u32 s25, 28
	s_cselect_b32 s45, s15, s27
	s_cselect_b32 s44, s17, s26
	s_cselect_b32 s43, s13, s24
	s_cselect_b32 s42, s18, s19
	s_add_i32 s31, 0, 0x14000
	v_add_u32_e32 v144, s30, v166
	v_add_u32_e32 v156, s31, v166
	ds_read_b128 v[132:135], v144
	ds_read_b128 v[136:139], v144 offset:1024
	ds_read_b128 v[140:143], v144 offset:2048
	ds_read_b128 v[144:147], v144 offset:3072
	ds_read_b128 v[170:173], v156
	ds_read_b128 v[174:177], v156 offset:1024
	ds_read_b128 v[178:181], v156 offset:2048
	ds_read_b128 v[182:185], v156 offset:3072
	v_lshl_add_u64 v[156:157], s[6:7], 0, v[152:153]
	s_add_i32 m0, s60, 0xc000
	ds_read_b128 v[186:189], v168
	ds_read_b128 v[190:193], v168 offset:1024
	ds_read_b128 v[194:197], v168 offset:2048
	ds_read_b128 v[204:207], v168 offset:3072
	ds_read_b128 v[208:211], v168 offset:4096
	ds_read_b128 v[212:215], v168 offset:5120
	ds_read_b128 v[216:219], v168 offset:6144
	ds_read_b128 v[220:223], v168 offset:7168
	global_load_lds_dwordx4 v[156:157], off
	v_lshl_add_u64 v[156:157], s[6:7], 0, v[154:155]
	s_add_i32 m0, s60, 0xe000
	s_nop 0
	global_load_lds_dwordx4 v[156:157], off
	s_waitcnt vmcnt(8)
	s_waitcnt lgkmcnt(0)
	s_barrier
	s_setprio 1
	s_waitcnt lgkmcnt(0)
	v_mfma_f32_16x16x32_bf16 v[128:131], v[132:135], v[186:189], 0
	v_mfma_f32_16x16x32_bf16 v[128:131], v[136:139], v[190:193], v[128:131]
	v_mfma_f32_16x16x32_bf16 v[124:127], v[140:143], v[186:189], 0
	v_mfma_f32_16x16x32_bf16 v[124:127], v[144:147], v[190:193], v[124:127]
	v_mfma_f32_16x16x32_bf16 v[116:119], v[132:135], v[194:197], 0
	v_mfma_f32_16x16x32_bf16 v[116:119], v[136:139], v[204:207], v[116:119]
	v_mfma_f32_16x16x32_bf16 v[112:115], v[140:143], v[194:197], 0
	v_mfma_f32_16x16x32_bf16 v[112:115], v[144:147], v[204:207], v[112:115]
	v_mfma_f32_16x16x32_bf16 v[104:107], v[132:135], v[208:211], 0
	v_mfma_f32_16x16x32_bf16 v[104:107], v[136:139], v[212:215], v[104:107]
	v_mfma_f32_16x16x32_bf16 v[96:99], v[140:143], v[208:211], 0
	v_mfma_f32_16x16x32_bf16 v[96:99], v[144:147], v[212:215], v[96:99]
	v_mfma_f32_16x16x32_bf16 v[88:91], v[132:135], v[216:219], 0
	v_mfma_f32_16x16x32_bf16 v[88:91], v[136:139], v[220:223], v[88:91]
	v_mfma_f32_16x16x32_bf16 v[80:83], v[140:143], v[216:219], 0
	v_mfma_f32_16x16x32_bf16 v[80:83], v[144:147], v[220:223], v[80:83]
	v_mfma_f32_16x16x32_bf16 v[120:123], v[170:173], v[186:189], 0
	v_mfma_f32_16x16x32_bf16 v[120:123], v[174:177], v[190:193], v[120:123]
	v_mfma_f32_16x16x32_bf16 v[108:111], v[178:181], v[186:189], 0
	v_mfma_f32_16x16x32_bf16 v[108:111], v[182:185], v[190:193], v[108:111]
	v_mfma_f32_16x16x32_bf16 v[100:103], v[170:173], v[194:197], 0
	v_mfma_f32_16x16x32_bf16 v[100:103], v[174:177], v[204:207], v[100:103]
	v_mfma_f32_16x16x32_bf16 v[92:95], v[178:181], v[194:197], 0
	v_mfma_f32_16x16x32_bf16 v[92:95], v[182:185], v[204:207], v[92:95]
	v_mfma_f32_16x16x32_bf16 v[84:87], v[170:173], v[208:211], 0
	v_mfma_f32_16x16x32_bf16 v[84:87], v[174:177], v[212:215], v[84:87]
	v_mfma_f32_16x16x32_bf16 v[76:79], v[178:181], v[208:211], 0
	v_mfma_f32_16x16x32_bf16 v[76:79], v[182:185], v[212:215], v[76:79]
	v_mfma_f32_16x16x32_bf16 v[72:75], v[170:173], v[216:219], 0
	v_mfma_f32_16x16x32_bf16 v[72:75], v[174:177], v[220:223], v[72:75]
	s_setprio 3
	s_barrier
	v_mfma_f32_16x16x32_bf16 v[68:71], v[178:181], v[216:219], 0
	v_mfma_f32_16x16x32_bf16 v[68:71], v[182:185], v[220:223], v[68:71]
	s_setprio 0
	s_add_i32 s26, s30, s59
	v_lshl_add_u64 v[156:157], s[42:43], 0, v[2:3]
	s_mov_b32 m0, s26
	ds_read_b128 v[186:189], v168 offset:16384
	ds_read_b128 v[190:193], v168 offset:17408
	ds_read_b128 v[194:197], v168 offset:18432
	ds_read_b128 v[204:207], v168 offset:19456
	ds_read_b128 v[208:211], v168 offset:20480
	ds_read_b128 v[212:215], v168 offset:21504
	ds_read_b128 v[216:219], v168 offset:22528
	ds_read_b128 v[220:223], v168 offset:23552
	global_load_lds_dwordx4 v[156:157], off
	s_add_i32 m0, s26, 0x2000
	s_add_u32 s26, s42, 0x80000
	v_lshl_add_u64 v[164:165], s[42:43], 0, v[0:1]
	s_addc_u32 s27, s43, 0
	s_add_i32 s30, s31, s59
	global_load_lds_dwordx4 v[164:165], off
	v_lshl_add_u64 v[224:225], s[26:27], 0, v[2:3]
	s_mov_b32 m0, s30
	v_lshl_add_u64 v[226:227], s[44:45], 0, v[148:149]
	global_load_lds_dwordx4 v[224:225], off
	v_lshl_add_u64 v[224:225], s[26:27], 0, v[0:1]
	s_add_i32 m0, s30, 0x2000
	s_nop 0
	global_load_lds_dwordx4 v[224:225], off
	v_lshl_add_u64 v[224:225], s[44:45], 0, v[150:151]
	s_mov_b32 m0, s60
	s_nop 0
	global_load_lds_dwordx4 v[224:225], off
	s_mov_b32 m0, s61
	s_nop 0
	global_load_lds_dwordx4 v[226:227], off
	s_waitcnt vmcnt(8)
	s_waitcnt lgkmcnt(0)
	s_barrier
; #define PG8_STAGE(bufoff, gbase, voff) do { _Pragma("unroll") for (int _i = 0; _i < 2; ++_i) \
;         __builtin_amdgcn_global_load_lds((const unsigned*)((const char*)(gbase) + (voff)[_i]), (LAS unsigned*)(lds + (bufoff) + ldsw + _i * 8192), 16, 0, 0); } while (0)
; #define PG8_LDA(dst, b, h) do { _Pragma("unroll") for (int m = 0; m < 4; ++m) _Pragma("unroll") for (int k = 0; k < 2; ++k) dst[m][k] = *(const LAS bf16x8*)(lds + PG8_SA(b, h) + aoff + m * 2048 + k * 1024); } while (0)
; #define PG8_LDB(dst, b, h) do { _Pragma("unroll") for (int n = 0; n < 2; ++n) _Pragma("unroll") for (int k = 0; k < 2; ++k) dst[n][k] = *(const LAS bf16x8*)(lds + PG8_SB(b, h) + boff + n * 2048 + k * 1024); } while (0)
; #define PG8_MMA(ai, bj, At, Bt) do { __builtin_amdgcn_s_setprio(1); _Pragma("unroll") for (int m = 0; m < 4; ++m) _Pragma("unroll") for (int n = 0; n < 2; ++n) _Pragma("unroll") for (int k = 0; k < 2; ++k) \
;         acc[ai][bj][m][n] = __builtin_amdgcn_mfma_f32_16x16x32_bf16(Bt[n][k], At[m][k], acc[ai][bj][m][n], 0, 0, 0); __builtin_amdgcn_s_setprio(0); } while (0)
; #define PG8_WAIT_V(n) asm volatile("s_waitcnt vmcnt(" #n ")" ::: "memory")
; #define PG8_WAIT_L(n) asm volatile("s_waitcnt lgkmcnt(" #n ")" ::: "memory")
; #define PG8_BAR __builtin_amdgcn_s_barrier()
; #define PG8_SCHED __builtin_amdgcn_sched_barrier(0)
; template <class Epi, class Sched, bool ALIGN_EPI = true>
; __device__ __forceinline__ void gemm_phase(LAS unsigned char* lds, const Gemm g, const Sched& S, const Epi& E) {
;     ...
;             PG8_WAIT_V(8); PG8_WAIT_L(0); PG8_BAR; PG8_MMA(1, 0, At, B0); PG8_MMA(1, 1, At, B1); PG8_BAR; PG8_SCHED;
;             PG8_LDB(B0, 1, 0); PG8_LDB(B1, 1, 1); PG8_SCHED; PG8_LDA(At, 1, 0); PG8_STAGE(PG8_SA(0, 1), a2 + hA, voffA);
;             PG8_WAIT_V(8); PG8_WAIT_L(0); PG8_BAR; PG8_MMA(0, 0, At, B0); PG8_MMA(0, 1, At, B1); PG8_BAR; PG8_SCHED;
	s_setprio 1
	s_waitcnt lgkmcnt(0)
	v_mfma_f32_16x16x32_bf16 v[64:67], v[132:135], v[186:189], 0
	v_mfma_f32_16x16x32_bf16 v[64:67], v[136:139], v[190:193], v[64:67]
	v_mfma_f32_16x16x32_bf16 v[60:63], v[140:143], v[186:189], 0
	v_mfma_f32_16x16x32_bf16 v[60:63], v[144:147], v[190:193], v[60:63]
	v_mfma_f32_16x16x32_bf16 v[56:59], v[132:135], v[194:197], 0
	v_mfma_f32_16x16x32_bf16 v[56:59], v[136:139], v[204:207], v[56:59]
	v_mfma_f32_16x16x32_bf16 v[48:51], v[140:143], v[194:197], 0
	v_mfma_f32_16x16x32_bf16 v[48:51], v[144:147], v[204:207], v[48:51]
	v_mfma_f32_16x16x32_bf16 v[40:43], v[132:135], v[208:211], 0
	v_mfma_f32_16x16x32_bf16 v[40:43], v[136:139], v[212:215], v[40:43]
	v_mfma_f32_16x16x32_bf16 v[32:35], v[140:143], v[208:211], 0
	v_mfma_f32_16x16x32_bf16 v[32:35], v[144:147], v[212:215], v[32:35]
	v_mfma_f32_16x16x32_bf16 v[24:27], v[132:135], v[216:219], 0
	v_mfma_f32_16x16x32_bf16 v[24:27], v[136:139], v[220:223], v[24:27]
	v_mfma_f32_16x16x32_bf16 v[16:19], v[140:143], v[216:219], 0
	v_mfma_f32_16x16x32_bf16 v[16:19], v[144:147], v[220:223], v[16:19]
	v_mfma_f32_16x16x32_bf16 v[52:55], v[170:173], v[186:189], 0
	v_mfma_f32_16x16x32_bf16 v[52:55], v[174:177], v[190:193], v[52:55]
	v_mfma_f32_16x16x32_bf16 v[44:47], v[178:181], v[186:189], 0
	v_mfma_f32_16x16x32_bf16 v[44:47], v[182:185], v[190:193], v[44:47]
	v_mfma_f32_16x16x32_bf16 v[36:39], v[170:173], v[194:197], 0
	v_mfma_f32_16x16x32_bf16 v[36:39], v[174:177], v[204:207], v[36:39]
	v_mfma_f32_16x16x32_bf16 v[28:31], v[178:181], v[194:197], 0
	v_mfma_f32_16x16x32_bf16 v[28:31], v[182:185], v[204:207], v[28:31]
	v_mfma_f32_16x16x32_bf16 v[20:23], v[170:173], v[208:211], 0
	v_mfma_f32_16x16x32_bf16 v[20:23], v[174:177], v[212:215], v[20:23]
	v_mfma_f32_16x16x32_bf16 v[12:15], v[178:181], v[208:211], 0
	v_mfma_f32_16x16x32_bf16 v[12:15], v[182:185], v[212:215], v[12:15]
	v_mfma_f32_16x16x32_bf16 v[8:11], v[170:173], v[216:219], 0
	v_mfma_f32_16x16x32_bf16 v[8:11], v[174:177], v[220:223], v[8:11]
	s_setprio 3
	s_barrier
	v_mfma_f32_16x16x32_bf16 v[4:7], v[178:181], v[216:219], 0
	v_mfma_f32_16x16x32_bf16 v[4:7], v[182:185], v[220:223], v[4:7]
	s_setprio 0
	s_add_i32 s30, 0, 0x18000
	s_add_i32 s31, 0, 0x1c000
	v_add_u32_e32 v144, s30, v166
	v_add_u32_e32 v160, s31, v166
	ds_read_b128 v[132:135], v144
	ds_read_b128 v[136:139], v144 offset:1024
	ds_read_b128 v[140:143], v144 offset:2048
	ds_read_b128 v[144:147], v144 offset:3072
	ds_read_b128 v[170:173], v160
	ds_read_b128 v[174:177], v160 offset:1024
	ds_read_b128 v[178:181], v160 offset:2048
	ds_read_b128 v[182:185], v160 offset:3072
	s_add_u32 s26, s44, 0x80000
	s_addc_u32 s27, s45, 0
	s_mov_b32 m0, s62
	v_lshl_add_u64 v[228:229], s[26:27], 0, v[150:151]
	ds_read_b128 v[186:189], v168 offset:32768
	ds_read_b128 v[190:193], v168 offset:33792
	ds_read_b128 v[194:197], v168 offset:34816
	ds_read_b128 v[204:207], v168 offset:35840
	ds_read_b128 v[208:211], v168 offset:36864
	ds_read_b128 v[212:215], v168 offset:37888
	ds_read_b128 v[216:219], v168 offset:38912
	ds_read_b128 v[220:223], v168 offset:39936
	global_load_lds_dwordx4 v[228:229], off
	v_lshl_add_u64 v[228:229], s[26:27], 0, v[148:149]
	s_mov_b32 m0, s63
	s_nop 0
	global_load_lds_dwordx4 v[228:229], off
	s_waitcnt vmcnt(8)
	s_waitcnt lgkmcnt(0)
	s_barrier
	s_setprio 1
	s_waitcnt lgkmcnt(0)
	v_mfma_f32_16x16x32_bf16 v[128:131], v[132:135], v[186:189], v[128:131]
	v_mfma_f32_16x16x32_bf16 v[128:131], v[136:139], v[190:193], v[128:131]
	v_mfma_f32_16x16x32_bf16 v[124:127], v[140:143], v[186:189], v[124:127]
	v_mfma_f32_16x16x32_bf16 v[124:127], v[144:147], v[190:193], v[124:127]
	v_mfma_f32_16x16x32_bf16 v[116:119], v[132:135], v[194:197], v[116:119]
	v_mfma_f32_16x16x32_bf16 v[116:119], v[136:139], v[204:207], v[116:119]
	v_mfma_f32_16x16x32_bf16 v[112:115], v[140:143], v[194:197], v[112:115]
	v_mfma_f32_16x16x32_bf16 v[112:115], v[144:147], v[204:207], v[112:115]
	v_mfma_f32_16x16x32_bf16 v[104:107], v[132:135], v[208:211], v[104:107]
	v_mfma_f32_16x16x32_bf16 v[104:107], v[136:139], v[212:215], v[104:107]
	v_mfma_f32_16x16x32_bf16 v[96:99], v[140:143], v[208:211], v[96:99]
	v_mfma_f32_16x16x32_bf16 v[96:99], v[144:147], v[212:215], v[96:99]
	v_mfma_f32_16x16x32_bf16 v[88:91], v[132:135], v[216:219], v[88:91]
	v_mfma_f32_16x16x32_bf16 v[88:91], v[136:139], v[220:223], v[88:91]
	v_mfma_f32_16x16x32_bf16 v[80:83], v[140:143], v[216:219], v[80:83]
	v_mfma_f32_16x16x32_bf16 v[80:83], v[144:147], v[220:223], v[80:83]
	v_mfma_f32_16x16x32_bf16 v[120:123], v[170:173], v[186:189], v[120:123]
	v_mfma_f32_16x16x32_bf16 v[120:123], v[174:177], v[190:193], v[120:123]
	v_mfma_f32_16x16x32_bf16 v[108:111], v[178:181], v[186:189], v[108:111]
	v_mfma_f32_16x16x32_bf16 v[108:111], v[182:185], v[190:193], v[108:111]
	v_mfma_f32_16x16x32_bf16 v[100:103], v[170:173], v[194:197], v[100:103]
	v_mfma_f32_16x16x32_bf16 v[100:103], v[174:177], v[204:207], v[100:103]
	v_mfma_f32_16x16x32_bf16 v[92:95], v[178:181], v[194:197], v[92:95]
	v_mfma_f32_16x16x32_bf16 v[92:95], v[182:185], v[204:207], v[92:95]
	v_mfma_f32_16x16x32_bf16 v[84:87], v[170:173], v[208:211], v[84:87]
	v_mfma_f32_16x16x32_bf16 v[84:87], v[174:177], v[212:215], v[84:87]
	v_mfma_f32_16x16x32_bf16 v[76:79], v[178:181], v[208:211], v[76:79]
	v_mfma_f32_16x16x32_bf16 v[76:79], v[182:185], v[212:215], v[76:79]
	v_mfma_f32_16x16x32_bf16 v[72:75], v[170:173], v[216:219], v[72:75]
	v_mfma_f32_16x16x32_bf16 v[72:75], v[174:177], v[220:223], v[72:75]
	s_setprio 3
	s_barrier
; #define PG8_STAGE(bufoff, gbase, voff) do { _Pragma("unroll") for (int _i = 0; _i < 2; ++_i) \
;         __builtin_amdgcn_global_load_lds((const unsigned*)((const char*)(gbase) + (voff)[_i]), (LAS unsigned*)(lds + (bufoff) + ldsw + _i * 8192), 16, 0, 0); } while (0)
; #define PG8_LDA(dst, b, h) do { _Pragma("unroll") for (int m = 0; m < 4; ++m) _Pragma("unroll") for (int k = 0; k < 2; ++k) dst[m][k] = *(const LAS bf16x8*)(lds + PG8_SA(b, h) + aoff + m * 2048 + k * 1024); } while (0)
; #define PG8_MMA(ai, bj, At, Bt) do { __builtin_amdgcn_s_setprio(1); _Pragma("unroll") for (int m = 0; m < 4; ++m) _Pragma("unroll") for (int n = 0; n < 2; ++n) _Pragma("unroll") for (int k = 0; k < 2; ++k) \
;         acc[ai][bj][m][n] = __builtin_amdgcn_mfma_f32_16x16x32_bf16(Bt[n][k], At[m][k], acc[ai][bj][m][n], 0, 0, 0); __builtin_amdgcn_s_setprio(0); } while (0)
; #define PG8_WAIT_V(n) asm volatile("s_waitcnt vmcnt(" #n ")" ::: "memory")
; #define PG8_WAIT_L(n) asm volatile("s_waitcnt lgkmcnt(" #n ")" ::: "memory")
; #define PG8_BAR __builtin_amdgcn_s_barrier()
; #define PG8_SCHED __builtin_amdgcn_sched_barrier(0)
; template <class Epi, class Sched, bool ALIGN_EPI = true>
; __device__ __forceinline__ void gemm_phase(LAS unsigned char* lds, const Gemm g, const Sched& S, const Epi& E) {
;     ...
;             PG8_WAIT_V(8); PG8_WAIT_L(0); PG8_BAR; PG8_MMA(0, 0, At, B0); PG8_MMA(0, 1, At, B1); PG8_BAR; PG8_SCHED;
;             PG8_LDA(At, 1, 1); PG8_STAGE(PG8_SB(1, 0), b3, voffB); PG8_STAGE(PG8_SB(1, 1), b3 + hB, voffB); PG8_STAGE(PG8_SA(1, 0), a3, voffA);
;             PG8_WAIT_V(8); PG8_WAIT_L(0); PG8_BAR; PG8_MMA(1, 0, At, B0); PG8_MMA(1, 1, At, B1); PG8_BAR; PG8_SCHED;
	v_mfma_f32_16x16x32_bf16 v[68:71], v[178:181], v[216:219], v[68:71]
	v_mfma_f32_16x16x32_bf16 v[68:71], v[182:185], v[220:223], v[68:71]
	s_setprio 0
	s_add_i32 s26, s30, s59
	v_lshl_add_u64 v[156:157], v[156:157], 0, s[86:87]
	s_mov_b32 m0, s26
	ds_read_b128 v[186:189], v168 offset:49152
	ds_read_b128 v[190:193], v168 offset:50176
	ds_read_b128 v[194:197], v168 offset:51200
	ds_read_b128 v[204:207], v168 offset:52224
	ds_read_b128 v[208:211], v168 offset:53248
	ds_read_b128 v[212:215], v168 offset:54272
	ds_read_b128 v[216:219], v168 offset:55296
	ds_read_b128 v[220:223], v168 offset:56320
	global_load_lds_dwordx4 v[156:157], off
	s_add_i32 m0, s26, 0x2000
	s_add_u32 s26, s42, 0x80080
	v_lshl_add_u64 v[156:157], v[164:165], 0, s[86:87]
	s_addc_u32 s27, s43, 0
	s_add_i32 s30, s31, s59
	global_load_lds_dwordx4 v[156:157], off
	v_lshl_add_u64 v[156:157], s[26:27], 0, v[2:3]
	s_mov_b32 m0, s30
	s_nop 0
	global_load_lds_dwordx4 v[156:157], off
	v_lshl_add_u64 v[156:157], s[26:27], 0, v[0:1]
	s_add_i32 m0, s30, 0x2000
	s_nop 0
	global_load_lds_dwordx4 v[156:157], off
	v_lshl_add_u64 v[156:157], v[224:225], 0, s[86:87]
	s_mov_b32 m0, s64
	s_nop 0
	global_load_lds_dwordx4 v[156:157], off
	v_lshl_add_u64 v[156:157], v[226:227], 0, s[86:87]
	s_mov_b32 m0, s65
	s_nop 0
	global_load_lds_dwordx4 v[156:157], off
	s_waitcnt vmcnt(8)
	s_waitcnt lgkmcnt(0)
	s_barrier
	s_setprio 1
	s_waitcnt lgkmcnt(0)
	v_mfma_f32_16x16x32_bf16 v[64:67], v[132:135], v[186:189], v[64:67]
	v_mfma_f32_16x16x32_bf16 v[64:67], v[136:139], v[190:193], v[64:67]
	s_add_i32 s25, s25, 2
	s_add_u32 s6, s6, 0x100
	v_mfma_f32_16x16x32_bf16 v[60:63], v[140:143], v[186:189], v[60:63]
	v_mfma_f32_16x16x32_bf16 v[60:63], v[144:147], v[190:193], v[60:63]
	s_addc_u32 s7, s7, 0
	s_add_u32 s19, s19, 0x100
	v_mfma_f32_16x16x32_bf16 v[56:59], v[132:135], v[194:197], v[56:59]
	v_mfma_f32_16x16x32_bf16 v[56:59], v[136:139], v[204:207], v[56:59]
	s_addc_u32 s24, s24, 0
	s_add_u32 s26, s6, 0xfff80080
	v_mfma_f32_16x16x32_bf16 v[48:51], v[140:143], v[194:197], v[48:51]
	v_mfma_f32_16x16x32_bf16 v[48:51], v[144:147], v[204:207], v[48:51]
	s_addc_u32 s27, s7, -1
	s_add_i32 s30, 0, 0x10000
	v_mfma_f32_16x16x32_bf16 v[40:43], v[132:135], v[208:211], v[40:43]
	v_mfma_f32_16x16x32_bf16 v[40:43], v[136:139], v[212:215], v[40:43]
	s_cmp_eq_u32 s25, 28
	s_cselect_b32 s45, s15, s27
	v_mfma_f32_16x16x32_bf16 v[32:35], v[140:143], v[208:211], v[32:35]
	v_mfma_f32_16x16x32_bf16 v[32:35], v[144:147], v[212:215], v[32:35]
	s_cselect_b32 s44, s17, s26
	s_cselect_b32 s43, s13, s24
	v_mfma_f32_16x16x32_bf16 v[24:27], v[132:135], v[216:219], v[24:27]
	v_mfma_f32_16x16x32_bf16 v[24:27], v[136:139], v[220:223], v[24:27]
	s_cselect_b32 s42, s18, s19
	s_add_i32 s31, 0, 0x14000
	v_mfma_f32_16x16x32_bf16 v[16:19], v[140:143], v[216:219], v[16:19]
	v_mfma_f32_16x16x32_bf16 v[16:19], v[144:147], v[220:223], v[16:19]
	v_mfma_f32_16x16x32_bf16 v[52:55], v[170:173], v[186:189], v[52:55]
	v_mfma_f32_16x16x32_bf16 v[52:55], v[174:177], v[190:193], v[52:55]
	v_mfma_f32_16x16x32_bf16 v[44:47], v[178:181], v[186:189], v[44:47]
	v_mfma_f32_16x16x32_bf16 v[44:47], v[182:185], v[190:193], v[44:47]
	v_mfma_f32_16x16x32_bf16 v[36:39], v[170:173], v[194:197], v[36:39]
	v_mfma_f32_16x16x32_bf16 v[36:39], v[174:177], v[204:207], v[36:39]
	v_mfma_f32_16x16x32_bf16 v[28:31], v[178:181], v[194:197], v[28:31]
	v_mfma_f32_16x16x32_bf16 v[28:31], v[182:185], v[204:207], v[28:31]
	v_mfma_f32_16x16x32_bf16 v[20:23], v[170:173], v[208:211], v[20:23]
	v_mfma_f32_16x16x32_bf16 v[20:23], v[174:177], v[212:215], v[20:23]
	v_mfma_f32_16x16x32_bf16 v[12:15], v[178:181], v[208:211], v[12:15]
	v_mfma_f32_16x16x32_bf16 v[12:15], v[182:185], v[212:215], v[12:15]
	v_mfma_f32_16x16x32_bf16 v[8:11], v[170:173], v[216:219], v[8:11]
	v_mfma_f32_16x16x32_bf16 v[8:11], v[174:177], v[220:223], v[8:11]
	s_setprio 3
	s_barrier
	v_mfma_f32_16x16x32_bf16 v[4:7], v[178:181], v[216:219], v[4:7]
	v_mfma_f32_16x16x32_bf16 v[4:7], v[182:185], v[220:223], v[4:7]
	s_setprio 0
	s_cmp_gt_u32 s25, 29
	s_cbranch_scc1 .Lpeel_exit_77
.LBB0_77:
	v_add_u32_e32 v144, s30, v166
	v_add_u32_e32 v156, s31, v166
	ds_read_b128 v[132:135], v144
	ds_read_b128 v[136:139], v144 offset:1024
	ds_read_b128 v[140:143], v144 offset:2048
	ds_read_b128 v[144:147], v144 offset:3072
	ds_read_b128 v[170:173], v156
	ds_read_b128 v[174:177], v156 offset:1024
	ds_read_b128 v[178:181], v156 offset:2048
	ds_read_b128 v[182:185], v156 offset:3072
	v_lshl_add_u64 v[156:157], s[6:7], 0, v[152:153]
	s_add_i32 m0, s60, 0xc000
	ds_read_b128 v[186:189], v168
	ds_read_b128 v[190:193], v168 offset:1024
	ds_read_b128 v[194:197], v168 offset:2048
	ds_read_b128 v[204:207], v168 offset:3072
	ds_read_b128 v[208:211], v168 offset:4096
	ds_read_b128 v[212:215], v168 offset:5120
	ds_read_b128 v[216:219], v168 offset:6144
	ds_read_b128 v[220:223], v168 offset:7168
	global_load_lds_dwordx4 v[156:157], off
	v_lshl_add_u64 v[156:157], s[6:7], 0, v[154:155]
	s_add_i32 m0, s60, 0xe000
	s_nop 0
	global_load_lds_dwordx4 v[156:157], off
	s_waitcnt vmcnt(8)
	s_waitcnt lgkmcnt(0)
	s_barrier
; #define PG8_STAGE(bufoff, gbase, voff) do { _Pragma("unroll") for (int _i = 0; _i < 2; ++_i) \
;         __builtin_amdgcn_global_load_lds((const unsigned*)((const char*)(gbase) + (voff)[_i]), (LAS unsigned*)(lds + (bufoff) + ldsw + _i * 8192), 16, 0, 0); } while (0)
; #define PG8_LDA(dst, b, h) do { _Pragma("unroll") for (int m = 0; m < 4; ++m) _Pragma("unroll") for (int k = 0; k < 2; ++k) dst[m][k] = *(const LAS bf16x8*)(lds + PG8_SA(b, h) + aoff + m * 2048 + k * 1024); } while (0)
; #define PG8_MMA(ai, bj, At, Bt) do { __builtin_amdgcn_s_setprio(1); _Pragma("unroll") for (int m = 0; m < 4; ++m) _Pragma("unroll") for (int n = 0; n < 2; ++n) _Pragma("unroll") for (int k = 0; k < 2; ++k) \
;         acc[ai][bj][m][n] = __builtin_amdgcn_mfma_f32_16x16x32_bf16(Bt[n][k], At[m][k], acc[ai][bj][m][n], 0, 0, 0); __builtin_amdgcn_s_setprio(0); } while (0)
; #define PG8_WAIT_V(n) asm volatile("s_waitcnt vmcnt(" #n ")" ::: "memory")
; #define PG8_WAIT_L(n) asm volatile("s_waitcnt lgkmcnt(" #n ")" ::: "memory")
; #define PG8_BAR __builtin_amdgcn_s_barrier()
; #define PG8_SCHED __builtin_amdgcn_sched_barrier(0)
; template <class Epi, class Sched, bool ALIGN_EPI = true>
; __device__ __forceinline__ void gemm_phase(LAS unsigned char* lds, const Gemm g, const Sched& S, const Epi& E) {
;     ...
;             PG8_WAIT_V(8); PG8_WAIT_L(0); PG8_BAR; PG8_MMA(0, 0, At, B0); PG8_MMA(0, 1, At, B1); PG8_BAR; PG8_SCHED;
;             PG8_LDA(At, 0, 1); PG8_STAGE(PG8_SB(0, 0), b2, voffB); PG8_STAGE(PG8_SB(0, 1), b2 + hB, voffB); PG8_STAGE(PG8_SA(0, 0), a2, voffA);
;             PG8_WAIT_V(8); PG8_WAIT_L(0); PG8_BAR; PG8_MMA(1, 0, At, B0); PG8_MMA(1, 1, At, B1); PG8_BAR; PG8_SCHED;
	s_setprio 1
	s_waitcnt lgkmcnt(0)
	v_mfma_f32_16x16x32_bf16 v[128:131], v[132:135], v[186:189], v[128:131]
	v_mfma_f32_16x16x32_bf16 v[128:131], v[136:139], v[190:193], v[128:131]
	v_mfma_f32_16x16x32_bf16 v[124:127], v[140:143], v[186:189], v[124:127]
	v_mfma_f32_16x16x32_bf16 v[124:127], v[144:147], v[190:193], v[124:127]
	v_mfma_f32_16x16x32_bf16 v[116:119], v[132:135], v[194:197], v[116:119]
	v_mfma_f32_16x16x32_bf16 v[116:119], v[136:139], v[204:207], v[116:119]
	v_mfma_f32_16x16x32_bf16 v[112:115], v[140:143], v[194:197], v[112:115]
	v_mfma_f32_16x16x32_bf16 v[112:115], v[144:147], v[204:207], v[112:115]
	v_mfma_f32_16x16x32_bf16 v[104:107], v[132:135], v[208:211], v[104:107]
	v_mfma_f32_16x16x32_bf16 v[104:107], v[136:139], v[212:215], v[104:107]
	v_mfma_f32_16x16x32_bf16 v[96:99], v[140:143], v[208:211], v[96:99]
	v_mfma_f32_16x16x32_bf16 v[96:99], v[144:147], v[212:215], v[96:99]
	v_mfma_f32_16x16x32_bf16 v[88:91], v[132:135], v[216:219], v[88:91]
	v_mfma_f32_16x16x32_bf16 v[88:91], v[136:139], v[220:223], v[88:91]
	v_mfma_f32_16x16x32_bf16 v[80:83], v[140:143], v[216:219], v[80:83]
	v_mfma_f32_16x16x32_bf16 v[80:83], v[144:147], v[220:223], v[80:83]
	v_mfma_f32_16x16x32_bf16 v[120:123], v[170:173], v[186:189], v[120:123]
	v_mfma_f32_16x16x32_bf16 v[120:123], v[174:177], v[190:193], v[120:123]
	v_mfma_f32_16x16x32_bf16 v[108:111], v[178:181], v[186:189], v[108:111]
	v_mfma_f32_16x16x32_bf16 v[108:111], v[182:185], v[190:193], v[108:111]
	v_mfma_f32_16x16x32_bf16 v[100:103], v[170:173], v[194:197], v[100:103]
	v_mfma_f32_16x16x32_bf16 v[100:103], v[174:177], v[204:207], v[100:103]
	v_mfma_f32_16x16x32_bf16 v[92:95], v[178:181], v[194:197], v[92:95]
	v_mfma_f32_16x16x32_bf16 v[92:95], v[182:185], v[204:207], v[92:95]
	v_mfma_f32_16x16x32_bf16 v[84:87], v[170:173], v[208:211], v[84:87]
	v_mfma_f32_16x16x32_bf16 v[84:87], v[174:177], v[212:215], v[84:87]
	v_mfma_f32_16x16x32_bf16 v[76:79], v[178:181], v[208:211], v[76:79]
	v_mfma_f32_16x16x32_bf16 v[76:79], v[182:185], v[212:215], v[76:79]
	v_mfma_f32_16x16x32_bf16 v[72:75], v[170:173], v[216:219], v[72:75]
	v_mfma_f32_16x16x32_bf16 v[72:75], v[174:177], v[220:223], v[72:75]
	s_setprio 3
	s_barrier
	v_mfma_f32_16x16x32_bf16 v[68:71], v[178:181], v[216:219], v[68:71]
	v_mfma_f32_16x16x32_bf16 v[68:71], v[182:185], v[220:223], v[68:71]
	s_setprio 0
	s_add_i32 s26, s30, s59
	v_lshl_add_u64 v[156:157], s[42:43], 0, v[2:3]
	s_mov_b32 m0, s26
	ds_read_b128 v[186:189], v168 offset:16384
	ds_read_b128 v[190:193], v168 offset:17408
	ds_read_b128 v[194:197], v168 offset:18432
	ds_read_b128 v[204:207], v168 offset:19456
	ds_read_b128 v[208:211], v168 offset:20480
	ds_read_b128 v[212:215], v168 offset:21504
	ds_read_b128 v[216:219], v168 offset:22528
	ds_read_b128 v[220:223], v168 offset:23552
	global_load_lds_dwordx4 v[156:157], off
	s_add_i32 m0, s26, 0x2000
	s_add_u32 s26, s42, 0x80000
	v_lshl_add_u64 v[164:165], s[42:43], 0, v[0:1]
	s_addc_u32 s27, s43, 0
	s_add_i32 s30, s31, s59
	global_load_lds_dwordx4 v[164:165], off
	v_lshl_add_u64 v[224:225], s[26:27], 0, v[2:3]
	s_mov_b32 m0, s30
	v_lshl_add_u64 v[226:227], s[44:45], 0, v[148:149]
	global_load_lds_dwordx4 v[224:225], off
	v_lshl_add_u64 v[224:225], s[26:27], 0, v[0:1]
	s_add_i32 m0, s30, 0x2000
	s_nop 0
	global_load_lds_dwordx4 v[224:225], off
	v_lshl_add_u64 v[224:225], s[44:45], 0, v[150:151]
	s_mov_b32 m0, s60
	s_nop 0
	global_load_lds_dwordx4 v[224:225], off
	s_mov_b32 m0, s61
	s_nop 0
	global_load_lds_dwordx4 v[226:227], off
	s_waitcnt vmcnt(8)
	s_waitcnt lgkmcnt(0)
	s_barrier
	s_setprio 1
	s_waitcnt lgkmcnt(0)
	v_mfma_f32_16x16x32_bf16 v[64:67], v[132:135], v[186:189], v[64:67]
	v_mfma_f32_16x16x32_bf16 v[64:67], v[136:139], v[190:193], v[64:67]
	v_mfma_f32_16x16x32_bf16 v[60:63], v[140:143], v[186:189], v[60:63]
	v_mfma_f32_16x16x32_bf16 v[60:63], v[144:147], v[190:193], v[60:63]
	v_mfma_f32_16x16x32_bf16 v[56:59], v[132:135], v[194:197], v[56:59]
	v_mfma_f32_16x16x32_bf16 v[56:59], v[136:139], v[204:207], v[56:59]
	v_mfma_f32_16x16x32_bf16 v[48:51], v[140:143], v[194:197], v[48:51]
	v_mfma_f32_16x16x32_bf16 v[48:51], v[144:147], v[204:207], v[48:51]
	v_mfma_f32_16x16x32_bf16 v[40:43], v[132:135], v[208:211], v[40:43]
	v_mfma_f32_16x16x32_bf16 v[40:43], v[136:139], v[212:215], v[40:43]
	v_mfma_f32_16x16x32_bf16 v[32:35], v[140:143], v[208:211], v[32:35]
	v_mfma_f32_16x16x32_bf16 v[32:35], v[144:147], v[212:215], v[32:35]
	v_mfma_f32_16x16x32_bf16 v[24:27], v[132:135], v[216:219], v[24:27]
	v_mfma_f32_16x16x32_bf16 v[24:27], v[136:139], v[220:223], v[24:27]
	v_mfma_f32_16x16x32_bf16 v[16:19], v[140:143], v[216:219], v[16:19]
	v_mfma_f32_16x16x32_bf16 v[16:19], v[144:147], v[220:223], v[16:19]
	v_mfma_f32_16x16x32_bf16 v[52:55], v[170:173], v[186:189], v[52:55]
	v_mfma_f32_16x16x32_bf16 v[52:55], v[174:177], v[190:193], v[52:55]
	v_mfma_f32_16x16x32_bf16 v[44:47], v[178:181], v[186:189], v[44:47]
	v_mfma_f32_16x16x32_bf16 v[44:47], v[182:185], v[190:193], v[44:47]
	v_mfma_f32_16x16x32_bf16 v[36:39], v[170:173], v[194:197], v[36:39]
	v_mfma_f32_16x16x32_bf16 v[36:39], v[174:177], v[204:207], v[36:39]
	v_mfma_f32_16x16x32_bf16 v[28:31], v[178:181], v[194:197], v[28:31]
	v_mfma_f32_16x16x32_bf16 v[28:31], v[182:185], v[204:207], v[28:31]
	v_mfma_f32_16x16x32_bf16 v[20:23], v[170:173], v[208:211], v[20:23]
	v_mfma_f32_16x16x32_bf16 v[20:23], v[174:177], v[212:215], v[20:23]
	v_mfma_f32_16x16x32_bf16 v[12:15], v[178:181], v[208:211], v[12:15]
	v_mfma_f32_16x16x32_bf16 v[12:15], v[182:185], v[212:215], v[12:15]
	v_mfma_f32_16x16x32_bf16 v[8:11], v[170:173], v[216:219], v[8:11]
	v_mfma_f32_16x16x32_bf16 v[8:11], v[174:177], v[220:223], v[8:11]
	s_setprio 3
	s_barrier
; #define PG8_STAGE(bufoff, gbase, voff) do { _Pragma("unroll") for (int _i = 0; _i < 2; ++_i) \
;         __builtin_amdgcn_global_load_lds((const unsigned*)((const char*)(gbase) + (voff)[_i]), (LAS unsigned*)(lds + (bufoff) + ldsw + _i * 8192), 16, 0, 0); } while (0)
; #define PG8_LDA(dst, b, h) do { _Pragma("unroll") for (int m = 0; m < 4; ++m) _Pragma("unroll") for (int k = 0; k < 2; ++k) dst[m][k] = *(const LAS bf16x8*)(lds + PG8_SA(b, h) + aoff + m * 2048 + k * 1024); } while (0)
; #define PG8_LDB(dst, b, h) do { _Pragma("unroll") for (int n = 0; n < 2; ++n) _Pragma("unroll") for (int k = 0; k < 2; ++k) dst[n][k] = *(const LAS bf16x8*)(lds + PG8_SB(b, h) + boff + n * 2048 + k * 1024); } while (0)
; #define PG8_MMA(ai, bj, At, Bt) do { __builtin_amdgcn_s_setprio(1); _Pragma("unroll") for (int m = 0; m < 4; ++m) _Pragma("unroll") for (int n = 0; n < 2; ++n) _Pragma("unroll") for (int k = 0; k < 2; ++k) \
;         acc[ai][bj][m][n] = __builtin_amdgcn_mfma_f32_16x16x32_bf16(Bt[n][k], At[m][k], acc[ai][bj][m][n], 0, 0, 0); __builtin_amdgcn_s_setprio(0); } while (0)
; #define PG8_WAIT_V(n) asm volatile("s_waitcnt vmcnt(" #n ")" ::: "memory")
; #define PG8_WAIT_L(n) asm volatile("s_waitcnt lgkmcnt(" #n ")" ::: "memory")
; #define PG8_BAR __builtin_amdgcn_s_barrier()
; #define PG8_SCHED __builtin_amdgcn_sched_barrier(0)
; template <class Epi, class Sched, bool ALIGN_EPI = true>
; __device__ __forceinline__ void gemm_phase(LAS unsigned char* lds, const Gemm g, const Sched& S, const Epi& E) {
;     ...
;             PG8_WAIT_V(8); PG8_WAIT_L(0); PG8_BAR; PG8_MMA(1, 0, At, B0); PG8_MMA(1, 1, At, B1); PG8_BAR; PG8_SCHED;
;             PG8_LDB(B0, 1, 0); PG8_LDB(B1, 1, 1); PG8_SCHED; PG8_LDA(At, 1, 0); PG8_STAGE(PG8_SA(0, 1), a2 + hA, voffA);
;             PG8_WAIT_V(8); PG8_WAIT_L(0); PG8_BAR; PG8_MMA(0, 0, At, B0); PG8_MMA(0, 1, At, B1); PG8_BAR; PG8_SCHED;
	v_mfma_f32_16x16x32_bf16 v[4:7], v[178:181], v[216:219], v[4:7]
	v_mfma_f32_16x16x32_bf16 v[4:7], v[182:185], v[220:223], v[4:7]
	s_setprio 0
	s_add_i32 s30, 0, 0x18000
	s_add_i32 s31, 0, 0x1c000
	v_add_u32_e32 v144, s30, v166
	v_add_u32_e32 v160, s31, v166
	ds_read_b128 v[132:135], v144
	ds_read_b128 v[136:139], v144 offset:1024
	ds_read_b128 v[140:143], v144 offset:2048
	ds_read_b128 v[144:147], v144 offset:3072
	ds_read_b128 v[170:173], v160
	ds_read_b128 v[174:177], v160 offset:1024
	ds_read_b128 v[178:181], v160 offset:2048
	ds_read_b128 v[182:185], v160 offset:3072
	s_add_u32 s26, s44, 0x80000
	s_addc_u32 s27, s45, 0
	s_mov_b32 m0, s62
	v_lshl_add_u64 v[228:229], s[26:27], 0, v[150:151]
	ds_read_b128 v[186:189], v168 offset:32768
	ds_read_b128 v[190:193], v168 offset:33792
	ds_read_b128 v[194:197], v168 offset:34816
	ds_read_b128 v[204:207], v168 offset:35840
	ds_read_b128 v[208:211], v168 offset:36864
	ds_read_b128 v[212:215], v168 offset:37888
	ds_read_b128 v[216:219], v168 offset:38912
	ds_read_b128 v[220:223], v168 offset:39936
	global_load_lds_dwordx4 v[228:229], off
	v_lshl_add_u64 v[228:229], s[26:27], 0, v[148:149]
	s_mov_b32 m0, s63
	s_nop 0
	global_load_lds_dwordx4 v[228:229], off
	s_waitcnt vmcnt(8)
	s_waitcnt lgkmcnt(0)
	s_barrier
	s_setprio 1
	s_waitcnt lgkmcnt(0)
	v_mfma_f32_16x16x32_bf16 v[128:131], v[132:135], v[186:189], v[128:131]
	v_mfma_f32_16x16x32_bf16 v[128:131], v[136:139], v[190:193], v[128:131]
	v_mfma_f32_16x16x32_bf16 v[124:127], v[140:143], v[186:189], v[124:127]
	v_mfma_f32_16x16x32_bf16 v[124:127], v[144:147], v[190:193], v[124:127]
	v_mfma_f32_16x16x32_bf16 v[116:119], v[132:135], v[194:197], v[116:119]
	v_mfma_f32_16x16x32_bf16 v[116:119], v[136:139], v[204:207], v[116:119]
	v_mfma_f32_16x16x32_bf16 v[112:115], v[140:143], v[194:197], v[112:115]
	v_mfma_f32_16x16x32_bf16 v[112:115], v[144:147], v[204:207], v[112:115]
	v_mfma_f32_16x16x32_bf16 v[104:107], v[132:135], v[208:211], v[104:107]
	v_mfma_f32_16x16x32_bf16 v[104:107], v[136:139], v[212:215], v[104:107]
	v_mfma_f32_16x16x32_bf16 v[96:99], v[140:143], v[208:211], v[96:99]
	v_mfma_f32_16x16x32_bf16 v[96:99], v[144:147], v[212:215], v[96:99]
	v_mfma_f32_16x16x32_bf16 v[88:91], v[132:135], v[216:219], v[88:91]
	v_mfma_f32_16x16x32_bf16 v[88:91], v[136:139], v[220:223], v[88:91]
	v_mfma_f32_16x16x32_bf16 v[80:83], v[140:143], v[216:219], v[80:83]
	v_mfma_f32_16x16x32_bf16 v[80:83], v[144:147], v[220:223], v[80:83]
	v_mfma_f32_16x16x32_bf16 v[120:123], v[170:173], v[186:189], v[120:123]
	v_mfma_f32_16x16x32_bf16 v[120:123], v[174:177], v[190:193], v[120:123]
	v_mfma_f32_16x16x32_bf16 v[108:111], v[178:181], v[186:189], v[108:111]
	v_mfma_f32_16x16x32_bf16 v[108:111], v[182:185], v[190:193], v[108:111]
	v_mfma_f32_16x16x32_bf16 v[100:103], v[170:173], v[194:197], v[100:103]
	v_mfma_f32_16x16x32_bf16 v[100:103], v[174:177], v[204:207], v[100:103]
	v_mfma_f32_16x16x32_bf16 v[92:95], v[178:181], v[194:197], v[92:95]
	v_mfma_f32_16x16x32_bf16 v[92:95], v[182:185], v[204:207], v[92:95]
	v_mfma_f32_16x16x32_bf16 v[84:87], v[170:173], v[208:211], v[84:87]
	v_mfma_f32_16x16x32_bf16 v[84:87], v[174:177], v[212:215], v[84:87]
	v_mfma_f32_16x16x32_bf16 v[76:79], v[178:181], v[208:211], v[76:79]
	v_mfma_f32_16x16x32_bf16 v[76:79], v[182:185], v[212:215], v[76:79]
	v_mfma_f32_16x16x32_bf16 v[72:75], v[170:173], v[216:219], v[72:75]
	v_mfma_f32_16x16x32_bf16 v[72:75], v[174:177], v[220:223], v[72:75]
	s_setprio 3
	s_barrier
; #define PG8_STAGE(bufoff, gbase, voff) do { _Pragma("unroll") for (int _i = 0; _i < 2; ++_i) \
;         __builtin_amdgcn_global_load_lds((const unsigned*)((const char*)(gbase) + (voff)[_i]), (LAS unsigned*)(lds + (bufoff) + ldsw + _i * 8192), 16, 0, 0); } while (0)
; #define PG8_LDA(dst, b, h) do { _Pragma("unroll") for (int m = 0; m < 4; ++m) _Pragma("unroll") for (int k = 0; k < 2; ++k) dst[m][k] = *(const LAS bf16x8*)(lds + PG8_SA(b, h) + aoff + m * 2048 + k * 1024); } while (0)
; #define PG8_LDB(dst, b, h) do { _Pragma("unroll") for (int n = 0; n < 2; ++n) _Pragma("unroll") for (int k = 0; k < 2; ++k) dst[n][k] = *(const LAS bf16x8*)(lds + PG8_SB(b, h) + boff + n * 2048 + k * 1024); } while (0)
; #define PG8_WAIT_V(n) asm volatile("s_waitcnt vmcnt(" #n ")" ::: "memory")
; #define PG8_WAIT_L(n) asm volatile("s_waitcnt lgkmcnt(" #n ")" ::: "memory")
; template <class Epi, class Sched, bool ALIGN_EPI = true>
; __device__ __forceinline__ void gemm_phase(LAS unsigned char* lds, const Gemm g, const Sched& S, const Epi& E) {
;     ...
;             const bool last = (t == nt - 2);
;             const char* a1 = cA + (size_t)(t + 1) * kstep;
;             const char* a2 = last ? nA : cA + (size_t)(t + 2) * kstep; const char* b2 = last ? nB : cB + (size_t)(t + 2) * kstep;
;             const char* a3 = a2 + kstep; const char* b3 = b2 + kstep;
;             PG8_LDB(B0, 0, 0); PG8_LDB(B1, 0, 1); PG8_SCHED; PG8_LDA(At, 0, 0); PG8_STAGE(PG8_SA(1, 1), a1 + hA, voffA);
;             PG8_WAIT_V(8); PG8_WAIT_L(0); PG8_BAR; PG8_MMA(0, 0, At, B0); PG8_MMA(0, 1, At, B1); PG8_BAR; PG8_SCHED;
;             PG8_LDA(At, 0, 1); PG8_STAGE(PG8_SB(0, 0), b2, voffB); PG8_STAGE(PG8_SB(0, 1), b2 + hB, voffB); PG8_STAGE(PG8_SA(0, 0), a2, voffA);
;             PG8_WAIT_V(8); PG8_WAIT_L(0); PG8_BAR; PG8_MMA(1, 0, At, B0); PG8_MMA(1, 1, At, B1); PG8_BAR; PG8_SCHED;
;             PG8_LDB(B0, 1, 0); PG8_LDB(B1, 1, 1); PG8_SCHED; PG8_LDA(At, 1, 0); PG8_STAGE(PG8_SA(0, 1), a2 + hA, voffA);
;             PG8_WAIT_V(8); PG8_WAIT_L(0); PG8_BAR; PG8_MMA(0, 0, At, B0); PG8_MMA(0, 1, At, B1); PG8_BAR; PG8_SCHED;
;             PG8_LDA(At, 1, 1); PG8_STAGE(PG8_SB(1, 0), b3, voffB); PG8_STAGE(PG8_SB(1, 1), b3 + hB, voffB); PG8_STAGE(PG8_SA(1, 0), a3, voffA);
;             PG8_WAIT_V(8); PG8_WAIT_L(0); PG8_BAR; PG8_MMA(1, 0, At, B0); PG8_MMA(1, 1, At, B1); PG8_BAR; PG8_SCHED;
	v_mfma_f32_16x16x32_bf16 v[68:71], v[178:181], v[216:219], v[68:71]
	v_mfma_f32_16x16x32_bf16 v[68:71], v[182:185], v[220:223], v[68:71]
	s_setprio 0
	s_add_i32 s26, s30, s59
	v_lshl_add_u64 v[156:157], v[156:157], 0, s[86:87]
	s_mov_b32 m0, s26
	ds_read_b128 v[186:189], v168 offset:49152
	ds_read_b128 v[190:193], v168 offset:50176
	ds_read_b128 v[194:197], v168 offset:51200
	ds_read_b128 v[204:207], v168 offset:52224
	ds_read_b128 v[208:211], v168 offset:53248
	ds_read_b128 v[212:215], v168 offset:54272
	ds_read_b128 v[216:219], v168 offset:55296
	ds_read_b128 v[220:223], v168 offset:56320
	global_load_lds_dwordx4 v[156:157], off
	s_add_i32 m0, s26, 0x2000
	s_add_u32 s26, s42, 0x80080
	v_lshl_add_u64 v[156:157], v[164:165], 0, s[86:87]
	s_addc_u32 s27, s43, 0
	s_add_i32 s30, s31, s59
	global_load_lds_dwordx4 v[156:157], off
	v_lshl_add_u64 v[156:157], s[26:27], 0, v[2:3]
	s_mov_b32 m0, s30
	s_nop 0
	global_load_lds_dwordx4 v[156:157], off
	v_lshl_add_u64 v[156:157], s[26:27], 0, v[0:1]
	s_add_i32 m0, s30, 0x2000
	s_nop 0
	global_load_lds_dwordx4 v[156:157], off
	v_lshl_add_u64 v[156:157], v[224:225], 0, s[86:87]
	s_mov_b32 m0, s64
	s_nop 0
	global_load_lds_dwordx4 v[156:157], off
	v_lshl_add_u64 v[156:157], v[226:227], 0, s[86:87]
	s_mov_b32 m0, s65
	s_nop 0
	global_load_lds_dwordx4 v[156:157], off
	s_waitcnt vmcnt(8)
	s_waitcnt lgkmcnt(0)
	s_barrier
	s_setprio 1
	s_waitcnt lgkmcnt(0)
	v_mfma_f32_16x16x32_bf16 v[64:67], v[132:135], v[186:189], v[64:67]
	v_mfma_f32_16x16x32_bf16 v[64:67], v[136:139], v[190:193], v[64:67]
	s_add_i32 s25, s25, 2
	s_add_u32 s6, s6, 0x100
	v_mfma_f32_16x16x32_bf16 v[60:63], v[140:143], v[186:189], v[60:63]
	v_mfma_f32_16x16x32_bf16 v[60:63], v[144:147], v[190:193], v[60:63]
	s_addc_u32 s7, s7, 0
	s_add_u32 s19, s19, 0x100
	v_mfma_f32_16x16x32_bf16 v[56:59], v[132:135], v[194:197], v[56:59]
	v_mfma_f32_16x16x32_bf16 v[56:59], v[136:139], v[204:207], v[56:59]
	s_addc_u32 s24, s24, 0
	s_add_u32 s26, s6, 0xfff80080
	v_mfma_f32_16x16x32_bf16 v[48:51], v[140:143], v[194:197], v[48:51]
	v_mfma_f32_16x16x32_bf16 v[48:51], v[144:147], v[204:207], v[48:51]
	s_addc_u32 s27, s7, -1
	s_add_i32 s30, 0, 0x10000
	v_mfma_f32_16x16x32_bf16 v[40:43], v[132:135], v[208:211], v[40:43]
	v_mfma_f32_16x16x32_bf16 v[40:43], v[136:139], v[212:215], v[40:43]
	s_cmp_eq_u32 s25, 28
	s_cselect_b32 s45, s15, s27
	v_mfma_f32_16x16x32_bf16 v[32:35], v[140:143], v[208:211], v[32:35]
	v_mfma_f32_16x16x32_bf16 v[32:35], v[144:147], v[212:215], v[32:35]
	s_cselect_b32 s44, s17, s26
	s_cselect_b32 s43, s13, s24
	v_mfma_f32_16x16x32_bf16 v[24:27], v[132:135], v[216:219], v[24:27]
	v_mfma_f32_16x16x32_bf16 v[24:27], v[136:139], v[220:223], v[24:27]
	s_cselect_b32 s42, s18, s19
	s_add_i32 s31, 0, 0x14000
	v_mfma_f32_16x16x32_bf16 v[16:19], v[140:143], v[216:219], v[16:19]
	v_mfma_f32_16x16x32_bf16 v[16:19], v[144:147], v[220:223], v[16:19]
	v_mfma_f32_16x16x32_bf16 v[52:55], v[170:173], v[186:189], v[52:55]
	v_mfma_f32_16x16x32_bf16 v[52:55], v[174:177], v[190:193], v[52:55]
	v_mfma_f32_16x16x32_bf16 v[44:47], v[178:181], v[186:189], v[44:47]
	v_mfma_f32_16x16x32_bf16 v[44:47], v[182:185], v[190:193], v[44:47]
	v_mfma_f32_16x16x32_bf16 v[36:39], v[170:173], v[194:197], v[36:39]
	v_mfma_f32_16x16x32_bf16 v[36:39], v[174:177], v[204:207], v[36:39]
	v_mfma_f32_16x16x32_bf16 v[28:31], v[178:181], v[194:197], v[28:31]
	v_mfma_f32_16x16x32_bf16 v[28:31], v[182:185], v[204:207], v[28:31]
	v_mfma_f32_16x16x32_bf16 v[20:23], v[170:173], v[208:211], v[20:23]
	v_mfma_f32_16x16x32_bf16 v[20:23], v[174:177], v[212:215], v[20:23]
	v_mfma_f32_16x16x32_bf16 v[12:15], v[178:181], v[208:211], v[12:15]
	v_mfma_f32_16x16x32_bf16 v[12:15], v[182:185], v[212:215], v[12:15]
	v_mfma_f32_16x16x32_bf16 v[8:11], v[170:173], v[216:219], v[8:11]
	v_mfma_f32_16x16x32_bf16 v[8:11], v[174:177], v[220:223], v[8:11]
	s_setprio 3
	s_barrier
	v_mfma_f32_16x16x32_bf16 v[4:7], v[178:181], v[216:219], v[4:7]
	v_mfma_f32_16x16x32_bf16 v[4:7], v[182:185], v[220:223], v[4:7]
	s_setprio 0
	s_cmp_gt_u32 s25, 29
	s_cbranch_scc0 .LBB0_77

;     __device__ bool next(int i, Unit& u) const { if (i >= 2) return false; const int x = c & 7, j = c >> 3; u.pm = 32 * i + 4 * x + (j & 3); u.pn = j >> 2; return true; }
; #define PG8_STAGE(bufoff, gbase, voff) do { _Pragma("unroll") for (int _i = 0; _i < 2; ++_i) \
;         __builtin_amdgcn_global_load_lds((const unsigned*)((const char*)(gbase) + (voff)[_i]), (LAS unsigned*)(lds + (bufoff) + ldsw + _i * 8192), 16, 0, 0); } while (0)
; #define PG8_LDA(dst, b, h) do { _Pragma("unroll") for (int m = 0; m < 4; ++m) _Pragma("unroll") for (int k = 0; k < 2; ++k) dst[m][k] = *(const LAS bf16x8*)(lds + PG8_SA(b, h) + aoff + m * 2048 + k * 1024); } while (0)
; #define PG8_LDB(dst, b, h) do { _Pragma("unroll") for (int n = 0; n < 2; ++n) _Pragma("unroll") for (int k = 0; k < 2; ++k) dst[n][k] = *(const LAS bf16x8*)(lds + PG8_SB(b, h) + boff + n * 2048 + k * 1024); } while (0)
; #define PG8_WAIT_V(n) asm volatile("s_waitcnt vmcnt(" #n ")" ::: "memory")
; #define PG8_WAIT_L(n) asm volatile("s_waitcnt lgkmcnt(" #n ")" ::: "memory")
; #define PG8_BAR __builtin_amdgcn_s_barrier()
; #define PG8_SCHED __builtin_amdgcn_sched_barrier(0)
; template <class Epi, class Sched, bool ALIGN_EPI = true>
; __device__ __forceinline__ void gemm_phase(LAS unsigned char* lds, const Gemm g, const Sched& S, const Epi& E) {
;     ...
;         const bool has_next = S.next(ui + 1, nxt);
;         const char* nA = has_next ? (const char*)g.A + ((size_t)nxt.pm * BM * g.lda + (size_t)nxt.pn * g.a_pn_off) * 2 : cA; const char* nB = has_next ? (const char*)g.Bt + (size_t)nxt.pn * BM * g.ldb * 2 : cB;
;         for (int t = 0; t < nt; t += 2) {
;             const bool last = (t == nt - 2);
;             const char* a1 = cA + (size_t)(t + 1) * kstep;
;             const char* a2 = last ? nA : cA + (size_t)(t + 2) * kstep; const char* b2 = last ? nB : cB + (size_t)(t + 2) * kstep;
;             const char* a3 = a2 + kstep; const char* b3 = b2 + kstep;
;             PG8_LDB(B0, 0, 0); PG8_LDB(B1, 0, 1); PG8_SCHED; PG8_LDA(At, 0, 0); PG8_STAGE(PG8_SA(1, 1), a1 + hA, voffA);
;             PG8_WAIT_V(8); PG8_WAIT_L(0); PG8_BAR; PG8_MMA(0, 0, At, B0); PG8_MMA(0, 1, At, B1); PG8_BAR; PG8_SCHED;
;             PG8_LDA(At, 0, 1); PG8_STAGE(PG8_SB(0, 0), b2, voffB); PG8_STAGE(PG8_SB(0, 1), b2 + hB, voffB); PG8_STAGE(PG8_SA(0, 0), a2, voffA);
.LBB0_217:
	s_ashr_i32 s11, s10, 31
	s_lshl_b64 s[12:13], s[10:11], 20
	s_add_u32 s12, s46, s12
	s_addc_u32 s13, s47, s13
	s_and_b64 s[14:15], s[4:5], exec
	s_cselect_b32 s11, s13, s39
	s_cselect_b32 s18, s12, s38
	s_ashr_i32 s9, s8, 31
	s_lshl_b64 s[14:15], s[8:9], 20
	s_add_u32 s14, s44, s14
	s_addc_u32 s15, s45, s15
	s_and_b64 s[24:25], s[4:5], exec
	s_cselect_b32 s9, s15, s41
	s_cselect_b32 s19, s14, s40
	s_add_u32 s38, s38, 0x80080
	s_addc_u32 s39, s39, 0
	s_add_u32 s24, s40, 0x100
	s_addc_u32 s25, s41, 0
	s_mov_b32 s26, -2
	s_add_u32 s27, s38, 0xfff80080
	s_addc_u32 s30, s39, -1
	s_add_i32 s31, 0, 0x10000
	s_cmp_eq_u32 s26, 28
	s_cselect_b32 s43, s11, s30
	s_cselect_b32 s42, s18, s27
	v_add_u32_e32 v156, s31, v145
	s_cselect_b32 s41, s9, s25
	s_cselect_b32 s40, s19, s24
	s_add_i32 s27, 0, 0x14000
	ds_read_b128 v[140:143], v156
	ds_read_b128 v[148:151], v156 offset:1024
	ds_read_b128 v[152:155], v156 offset:2048
	ds_read_b128 v[164:167], v156 offset:3072
	v_add_u32_e32 v156, s27, v145
	ds_read_b128 v[168:171], v156
	ds_read_b128 v[172:175], v156 offset:1024
	ds_read_b128 v[176:179], v156 offset:2048
	ds_read_b128 v[180:183], v156 offset:3072
	v_lshl_add_u64 v[156:157], s[38:39], 0, v[136:137]
	s_add_i32 m0, s58, 0xc000
	ds_read_b128 v[184:187], v147
	ds_read_b128 v[188:191], v147 offset:1024
	ds_read_b128 v[192:195], v147 offset:2048
	ds_read_b128 v[204:207], v147 offset:3072
	ds_read_b128 v[208:211], v147 offset:4096
	ds_read_b128 v[212:215], v147 offset:5120
	ds_read_b128 v[216:219], v147 offset:6144
	ds_read_b128 v[220:223], v147 offset:7168
	global_load_lds_dwordx4 v[156:157], off
	v_lshl_add_u64 v[156:157], s[38:39], 0, v[138:139]
	s_add_i32 m0, s58, 0xe000
	s_nop 0
	global_load_lds_dwordx4 v[156:157], off
	s_waitcnt vmcnt(8)
	s_waitcnt lgkmcnt(0)
	s_barrier
	s_setprio 1
	s_waitcnt lgkmcnt(0)
	v_mfma_f32_16x16x32_bf16 v[128:131], v[140:143], v[184:187], 0
	v_mfma_f32_16x16x32_bf16 v[128:131], v[148:151], v[188:191], v[128:131]
	v_mfma_f32_16x16x32_bf16 v[124:127], v[152:155], v[184:187], 0
	v_mfma_f32_16x16x32_bf16 v[124:127], v[164:167], v[188:191], v[124:127]
	v_mfma_f32_16x16x32_bf16 v[120:123], v[140:143], v[192:195], 0
	v_mfma_f32_16x16x32_bf16 v[120:123], v[148:151], v[204:207], v[120:123]
	v_mfma_f32_16x16x32_bf16 v[112:115], v[152:155], v[192:195], 0
	v_mfma_f32_16x16x32_bf16 v[112:115], v[164:167], v[204:207], v[112:115]
	v_mfma_f32_16x16x32_bf16 v[104:107], v[140:143], v[208:211], 0
	v_mfma_f32_16x16x32_bf16 v[104:107], v[148:151], v[212:215], v[104:107]
	v_mfma_f32_16x16x32_bf16 v[96:99], v[152:155], v[208:211], 0
	v_mfma_f32_16x16x32_bf16 v[96:99], v[164:167], v[212:215], v[96:99]
	v_mfma_f32_16x16x32_bf16 v[88:91], v[140:143], v[216:219], 0
	v_mfma_f32_16x16x32_bf16 v[88:91], v[148:151], v[220:223], v[88:91]
	v_mfma_f32_16x16x32_bf16 v[80:83], v[152:155], v[216:219], 0
	v_mfma_f32_16x16x32_bf16 v[80:83], v[164:167], v[220:223], v[80:83]
	v_mfma_f32_16x16x32_bf16 v[116:119], v[168:171], v[184:187], 0
	v_mfma_f32_16x16x32_bf16 v[116:119], v[172:175], v[188:191], v[116:119]
	v_mfma_f32_16x16x32_bf16 v[108:111], v[176:179], v[184:187], 0
	v_mfma_f32_16x16x32_bf16 v[108:111], v[180:183], v[188:191], v[108:111]
	v_mfma_f32_16x16x32_bf16 v[100:103], v[168:171], v[192:195], 0
	v_mfma_f32_16x16x32_bf16 v[100:103], v[172:175], v[204:207], v[100:103]
	v_mfma_f32_16x16x32_bf16 v[92:95], v[176:179], v[192:195], 0
	v_mfma_f32_16x16x32_bf16 v[92:95], v[180:183], v[204:207], v[92:95]
	v_mfma_f32_16x16x32_bf16 v[84:87], v[168:171], v[208:211], 0
	v_mfma_f32_16x16x32_bf16 v[84:87], v[172:175], v[212:215], v[84:87]
	v_mfma_f32_16x16x32_bf16 v[76:79], v[176:179], v[208:211], 0
	v_mfma_f32_16x16x32_bf16 v[76:79], v[180:183], v[212:215], v[76:79]
	v_mfma_f32_16x16x32_bf16 v[72:75], v[168:171], v[216:219], 0
	v_mfma_f32_16x16x32_bf16 v[72:75], v[172:175], v[220:223], v[72:75]
	s_setprio 3
	s_barrier
	v_mfma_f32_16x16x32_bf16 v[68:71], v[176:179], v[216:219], 0
	v_mfma_f32_16x16x32_bf16 v[68:71], v[180:183], v[220:223], v[68:71]
	s_setprio 0
	s_add_i32 s30, s31, s53
	v_lshl_add_u64 v[156:157], s[40:41], 0, v[2:3]
	s_mov_b32 m0, s30
	ds_read_b128 v[184:187], v147 offset:16384
	ds_read_b128 v[188:191], v147 offset:17408
	ds_read_b128 v[192:195], v147 offset:18432
	ds_read_b128 v[204:207], v147 offset:19456
	ds_read_b128 v[208:211], v147 offset:20480
	ds_read_b128 v[212:215], v147 offset:21504
	ds_read_b128 v[216:219], v147 offset:22528
	ds_read_b128 v[220:223], v147 offset:23552
	global_load_lds_dwordx4 v[156:157], off
	s_add_i32 m0, s30, 0x2000
	s_add_u32 s30, s40, 0x80000
	v_lshl_add_u64 v[196:197], s[40:41], 0, v[0:1]
	s_addc_u32 s31, s41, 0
	s_add_i32 s27, s27, s53
	global_load_lds_dwordx4 v[196:197], off
	v_lshl_add_u64 v[224:225], s[30:31], 0, v[2:3]
	s_mov_b32 m0, s27
	v_lshl_add_u64 v[226:227], s[42:43], 0, v[132:133]
	global_load_lds_dwordx4 v[224:225], off
	v_lshl_add_u64 v[224:225], s[30:31], 0, v[0:1]
	s_add_i32 m0, s27, 0x2000
	s_nop 0
	global_load_lds_dwordx4 v[224:225], off
	v_lshl_add_u64 v[224:225], s[42:43], 0, v[134:135]
	s_mov_b32 m0, s58
	s_nop 0
	global_load_lds_dwordx4 v[224:225], off
	s_mov_b32 m0, s59
	s_nop 0
	global_load_lds_dwordx4 v[226:227], off
	s_waitcnt vmcnt(8)
	s_waitcnt lgkmcnt(0)
	s_barrier
; #define PG8_STAGE(bufoff, gbase, voff) do { _Pragma("unroll") for (int _i = 0; _i < 2; ++_i) \
;         __builtin_amdgcn_global_load_lds((const unsigned*)((const char*)(gbase) + (voff)[_i]), (LAS unsigned*)(lds + (bufoff) + ldsw + _i * 8192), 16, 0, 0); } while (0)
; #define PG8_LDA(dst, b, h) do { _Pragma("unroll") for (int m = 0; m < 4; ++m) _Pragma("unroll") for (int k = 0; k < 2; ++k) dst[m][k] = *(const LAS bf16x8*)(lds + PG8_SA(b, h) + aoff + m * 2048 + k * 1024); } while (0)
; #define PG8_LDB(dst, b, h) do { _Pragma("unroll") for (int n = 0; n < 2; ++n) _Pragma("unroll") for (int k = 0; k < 2; ++k) dst[n][k] = *(const LAS bf16x8*)(lds + PG8_SB(b, h) + boff + n * 2048 + k * 1024); } while (0)
; #define PG8_MMA(ai, bj, At, Bt) do { __builtin_amdgcn_s_setprio(1); _Pragma("unroll") for (int m = 0; m < 4; ++m) _Pragma("unroll") for (int n = 0; n < 2; ++n) _Pragma("unroll") for (int k = 0; k < 2; ++k) \
;         acc[ai][bj][m][n] = __builtin_amdgcn_mfma_f32_16x16x32_bf16(Bt[n][k], At[m][k], acc[ai][bj][m][n], 0, 0, 0); __builtin_amdgcn_s_setprio(0); } while (0)
; #define PG8_WAIT_V(n) asm volatile("s_waitcnt vmcnt(" #n ")" ::: "memory")
; #define PG8_WAIT_L(n) asm volatile("s_waitcnt lgkmcnt(" #n ")" ::: "memory")
; #define PG8_BAR __builtin_amdgcn_s_barrier()
; #define PG8_SCHED __builtin_amdgcn_sched_barrier(0)
; template <class Epi, class Sched, bool ALIGN_EPI = true>
; __device__ __forceinline__ void gemm_phase(LAS unsigned char* lds, const Gemm g, const Sched& S, const Epi& E) {
;     ...
;             PG8_WAIT_V(8); PG8_WAIT_L(0); PG8_BAR; PG8_MMA(1, 0, At, B0); PG8_MMA(1, 1, At, B1); PG8_BAR; PG8_SCHED;
;             PG8_LDB(B0, 1, 0); PG8_LDB(B1, 1, 1); PG8_SCHED; PG8_LDA(At, 1, 0); PG8_STAGE(PG8_SA(0, 1), a2 + hA, voffA);
;             PG8_WAIT_V(8); PG8_WAIT_L(0); PG8_BAR; PG8_MMA(0, 0, At, B0); PG8_MMA(0, 1, At, B1); PG8_BAR; PG8_SCHED;
	s_setprio 1
	s_waitcnt lgkmcnt(0)
	v_mfma_f32_16x16x32_bf16 v[64:67], v[140:143], v[184:187], 0
	v_mfma_f32_16x16x32_bf16 v[64:67], v[148:151], v[188:191], v[64:67]
	v_mfma_f32_16x16x32_bf16 v[60:63], v[152:155], v[184:187], 0
	v_mfma_f32_16x16x32_bf16 v[60:63], v[164:167], v[188:191], v[60:63]
	v_mfma_f32_16x16x32_bf16 v[56:59], v[140:143], v[192:195], 0
	v_mfma_f32_16x16x32_bf16 v[56:59], v[148:151], v[204:207], v[56:59]
	v_mfma_f32_16x16x32_bf16 v[48:51], v[152:155], v[192:195], 0
	v_mfma_f32_16x16x32_bf16 v[48:51], v[164:167], v[204:207], v[48:51]
	v_mfma_f32_16x16x32_bf16 v[40:43], v[140:143], v[208:211], 0
	v_mfma_f32_16x16x32_bf16 v[40:43], v[148:151], v[212:215], v[40:43]
	v_mfma_f32_16x16x32_bf16 v[32:35], v[152:155], v[208:211], 0
	v_mfma_f32_16x16x32_bf16 v[32:35], v[164:167], v[212:215], v[32:35]
	v_mfma_f32_16x16x32_bf16 v[24:27], v[140:143], v[216:219], 0
	v_mfma_f32_16x16x32_bf16 v[24:27], v[148:151], v[220:223], v[24:27]
	v_mfma_f32_16x16x32_bf16 v[16:19], v[152:155], v[216:219], 0
	v_mfma_f32_16x16x32_bf16 v[16:19], v[164:167], v[220:223], v[16:19]
	v_mfma_f32_16x16x32_bf16 v[52:55], v[168:171], v[184:187], 0
	v_mfma_f32_16x16x32_bf16 v[52:55], v[172:175], v[188:191], v[52:55]
	v_mfma_f32_16x16x32_bf16 v[44:47], v[176:179], v[184:187], 0
	v_mfma_f32_16x16x32_bf16 v[44:47], v[180:183], v[188:191], v[44:47]
	v_mfma_f32_16x16x32_bf16 v[36:39], v[168:171], v[192:195], 0
	v_mfma_f32_16x16x32_bf16 v[36:39], v[172:175], v[204:207], v[36:39]
	v_mfma_f32_16x16x32_bf16 v[28:31], v[176:179], v[192:195], 0
	v_mfma_f32_16x16x32_bf16 v[28:31], v[180:183], v[204:207], v[28:31]
	v_mfma_f32_16x16x32_bf16 v[20:23], v[168:171], v[208:211], 0
	v_mfma_f32_16x16x32_bf16 v[20:23], v[172:175], v[212:215], v[20:23]
	v_mfma_f32_16x16x32_bf16 v[12:15], v[176:179], v[208:211], 0
	v_mfma_f32_16x16x32_bf16 v[12:15], v[180:183], v[212:215], v[12:15]
	v_mfma_f32_16x16x32_bf16 v[8:11], v[168:171], v[216:219], 0
	v_mfma_f32_16x16x32_bf16 v[8:11], v[172:175], v[220:223], v[8:11]
	s_setprio 3
	s_barrier
	v_mfma_f32_16x16x32_bf16 v[4:7], v[176:179], v[216:219], 0
	v_mfma_f32_16x16x32_bf16 v[4:7], v[180:183], v[220:223], v[4:7]
	s_setprio 0
	s_add_i32 s27, 0, 0x18000
	v_add_u32_e32 v158, s27, v145
	s_add_i32 s65, 0, 0x1c000
	ds_read_b128 v[140:143], v158
	ds_read_b128 v[148:151], v158 offset:1024
	ds_read_b128 v[152:155], v158 offset:2048
	ds_read_b128 v[164:167], v158 offset:3072
	v_add_u32_e32 v158, s65, v145
	ds_read_b128 v[168:171], v158
	ds_read_b128 v[172:175], v158 offset:1024
	ds_read_b128 v[176:179], v158 offset:2048
	ds_read_b128 v[180:183], v158 offset:3072
	s_add_u32 s30, s42, 0x80000
	s_addc_u32 s31, s43, 0
	s_mov_b32 m0, s60
	v_lshl_add_u64 v[228:229], s[30:31], 0, v[134:135]
	ds_read_b128 v[184:187], v147 offset:32768
	ds_read_b128 v[188:191], v147 offset:33792
	ds_read_b128 v[192:195], v147 offset:34816
	ds_read_b128 v[204:207], v147 offset:35840
	ds_read_b128 v[208:211], v147 offset:36864
	ds_read_b128 v[212:215], v147 offset:37888
	ds_read_b128 v[216:219], v147 offset:38912
	ds_read_b128 v[220:223], v147 offset:39936
	global_load_lds_dwordx4 v[228:229], off
	v_lshl_add_u64 v[228:229], s[30:31], 0, v[132:133]
	s_mov_b32 m0, s61
	s_nop 0
	global_load_lds_dwordx4 v[228:229], off
	s_waitcnt vmcnt(8)
	s_waitcnt lgkmcnt(0)
	s_barrier
	s_setprio 1
	s_waitcnt lgkmcnt(0)
	v_mfma_f32_16x16x32_bf16 v[128:131], v[140:143], v[184:187], v[128:131]
	v_mfma_f32_16x16x32_bf16 v[128:131], v[148:151], v[188:191], v[128:131]
	v_mfma_f32_16x16x32_bf16 v[124:127], v[152:155], v[184:187], v[124:127]
	v_mfma_f32_16x16x32_bf16 v[124:127], v[164:167], v[188:191], v[124:127]
	v_mfma_f32_16x16x32_bf16 v[120:123], v[140:143], v[192:195], v[120:123]
	v_mfma_f32_16x16x32_bf16 v[120:123], v[148:151], v[204:207], v[120:123]
	v_mfma_f32_16x16x32_bf16 v[112:115], v[152:155], v[192:195], v[112:115]
	v_mfma_f32_16x16x32_bf16 v[112:115], v[164:167], v[204:207], v[112:115]
	v_mfma_f32_16x16x32_bf16 v[104:107], v[140:143], v[208:211], v[104:107]
	v_mfma_f32_16x16x32_bf16 v[104:107], v[148:151], v[212:215], v[104:107]
	v_mfma_f32_16x16x32_bf16 v[96:99], v[152:155], v[208:211], v[96:99]
	v_mfma_f32_16x16x32_bf16 v[96:99], v[164:167], v[212:215], v[96:99]
	v_mfma_f32_16x16x32_bf16 v[88:91], v[140:143], v[216:219], v[88:91]
	v_mfma_f32_16x16x32_bf16 v[88:91], v[148:151], v[220:223], v[88:91]
	v_mfma_f32_16x16x32_bf16 v[80:83], v[152:155], v[216:219], v[80:83]
	v_mfma_f32_16x16x32_bf16 v[80:83], v[164:167], v[220:223], v[80:83]
	v_mfma_f32_16x16x32_bf16 v[116:119], v[168:171], v[184:187], v[116:119]
	v_mfma_f32_16x16x32_bf16 v[116:119], v[172:175], v[188:191], v[116:119]
	v_mfma_f32_16x16x32_bf16 v[108:111], v[176:179], v[184:187], v[108:111]
	v_mfma_f32_16x16x32_bf16 v[108:111], v[180:183], v[188:191], v[108:111]
	v_mfma_f32_16x16x32_bf16 v[100:103], v[168:171], v[192:195], v[100:103]
	v_mfma_f32_16x16x32_bf16 v[100:103], v[172:175], v[204:207], v[100:103]
	v_mfma_f32_16x16x32_bf16 v[92:95], v[176:179], v[192:195], v[92:95]
	v_mfma_f32_16x16x32_bf16 v[92:95], v[180:183], v[204:207], v[92:95]
	v_mfma_f32_16x16x32_bf16 v[84:87], v[168:171], v[208:211], v[84:87]
	v_mfma_f32_16x16x32_bf16 v[84:87], v[172:175], v[212:215], v[84:87]
	v_mfma_f32_16x16x32_bf16 v[76:79], v[176:179], v[208:211], v[76:79]
	v_mfma_f32_16x16x32_bf16 v[76:79], v[180:183], v[212:215], v[76:79]
	v_mfma_f32_16x16x32_bf16 v[72:75], v[168:171], v[216:219], v[72:75]
	v_mfma_f32_16x16x32_bf16 v[72:75], v[172:175], v[220:223], v[72:75]
	s_setprio 3
	s_barrier
; #define PG8_STAGE(bufoff, gbase, voff) do { _Pragma("unroll") for (int _i = 0; _i < 2; ++_i) \
;         __builtin_amdgcn_global_load_lds((const unsigned*)((const char*)(gbase) + (voff)[_i]), (LAS unsigned*)(lds + (bufoff) + ldsw + _i * 8192), 16, 0, 0); } while (0)
; #define PG8_LDA(dst, b, h) do { _Pragma("unroll") for (int m = 0; m < 4; ++m) _Pragma("unroll") for (int k = 0; k < 2; ++k) dst[m][k] = *(const LAS bf16x8*)(lds + PG8_SA(b, h) + aoff + m * 2048 + k * 1024); } while (0)
; #define PG8_LDB(dst, b, h) do { _Pragma("unroll") for (int n = 0; n < 2; ++n) _Pragma("unroll") for (int k = 0; k < 2; ++k) dst[n][k] = *(const LAS bf16x8*)(lds + PG8_SB(b, h) + boff + n * 2048 + k * 1024); } while (0)
; #define PG8_WAIT_V(n) asm volatile("s_waitcnt vmcnt(" #n ")" ::: "memory")
; #define PG8_WAIT_L(n) asm volatile("s_waitcnt lgkmcnt(" #n ")" ::: "memory")
; template <class Epi, class Sched, bool ALIGN_EPI = true>
; __device__ __forceinline__ void gemm_phase(LAS unsigned char* lds, const Gemm g, const Sched& S, const Epi& E) {
;     ...
;             const bool last = (t == nt - 2);
;             const char* a1 = cA + (size_t)(t + 1) * kstep;
;             const char* a2 = last ? nA : cA + (size_t)(t + 2) * kstep; const char* b2 = last ? nB : cB + (size_t)(t + 2) * kstep;
;             const char* a3 = a2 + kstep; const char* b3 = b2 + kstep;
;             PG8_LDB(B0, 0, 0); PG8_LDB(B1, 0, 1); PG8_SCHED; PG8_LDA(At, 0, 0); PG8_STAGE(PG8_SA(1, 1), a1 + hA, voffA);
;             PG8_WAIT_V(8); PG8_WAIT_L(0); PG8_BAR; PG8_MMA(0, 0, At, B0); PG8_MMA(0, 1, At, B1); PG8_BAR; PG8_SCHED;
;             PG8_LDA(At, 0, 1); PG8_STAGE(PG8_SB(0, 0), b2, voffB); PG8_STAGE(PG8_SB(0, 1), b2 + hB, voffB); PG8_STAGE(PG8_SA(0, 0), a2, voffA);
;             PG8_WAIT_V(8); PG8_WAIT_L(0); PG8_BAR; PG8_MMA(1, 0, At, B0); PG8_MMA(1, 1, At, B1); PG8_BAR; PG8_SCHED;
;             PG8_LDB(B0, 1, 0); PG8_LDB(B1, 1, 1); PG8_SCHED; PG8_LDA(At, 1, 0); PG8_STAGE(PG8_SA(0, 1), a2 + hA, voffA);
;             PG8_WAIT_V(8); PG8_WAIT_L(0); PG8_BAR; PG8_MMA(0, 0, At, B0); PG8_MMA(0, 1, At, B1); PG8_BAR; PG8_SCHED;
;             PG8_LDA(At, 1, 1); PG8_STAGE(PG8_SB(1, 0), b3, voffB); PG8_STAGE(PG8_SB(1, 1), b3 + hB, voffB); PG8_STAGE(PG8_SA(1, 0), a3, voffA);
;             PG8_WAIT_V(8); PG8_WAIT_L(0); PG8_BAR; PG8_MMA(1, 0, At, B0); PG8_MMA(1, 1, At, B1); PG8_BAR; PG8_SCHED;
	v_mfma_f32_16x16x32_bf16 v[68:71], v[176:179], v[216:219], v[68:71]
	v_mfma_f32_16x16x32_bf16 v[68:71], v[180:183], v[220:223], v[68:71]
	s_setprio 0
	s_add_i32 s27, s27, s53
	v_lshl_add_u64 v[156:157], v[156:157], 0, s[86:87]
	s_mov_b32 m0, s27
	ds_read_b128 v[184:187], v147 offset:49152
	ds_read_b128 v[188:191], v147 offset:50176
	ds_read_b128 v[192:195], v147 offset:51200
	ds_read_b128 v[204:207], v147 offset:52224
	ds_read_b128 v[208:211], v147 offset:53248
	ds_read_b128 v[212:215], v147 offset:54272
	ds_read_b128 v[216:219], v147 offset:55296
	ds_read_b128 v[220:223], v147 offset:56320
	global_load_lds_dwordx4 v[156:157], off
	s_add_i32 m0, s27, 0x2000
	s_add_u32 s30, s40, 0x80080
	v_lshl_add_u64 v[156:157], v[196:197], 0, s[86:87]
	s_addc_u32 s31, s41, 0
	s_add_i32 s27, s65, s53
	global_load_lds_dwordx4 v[156:157], off
	v_lshl_add_u64 v[156:157], s[30:31], 0, v[2:3]
	s_mov_b32 m0, s27
	s_nop 0
	global_load_lds_dwordx4 v[156:157], off
	v_lshl_add_u64 v[156:157], s[30:31], 0, v[0:1]
	s_add_i32 m0, s27, 0x2000
	s_nop 0
	global_load_lds_dwordx4 v[156:157], off
	v_lshl_add_u64 v[156:157], v[224:225], 0, s[86:87]
	s_mov_b32 m0, s62
	s_nop 0
	global_load_lds_dwordx4 v[156:157], off
	v_lshl_add_u64 v[156:157], v[226:227], 0, s[86:87]
	s_mov_b32 m0, s63
	s_nop 0
	global_load_lds_dwordx4 v[156:157], off
	s_waitcnt vmcnt(8)
	s_waitcnt lgkmcnt(0)
	s_barrier
	s_setprio 1
	s_waitcnt lgkmcnt(0)
	v_mfma_f32_16x16x32_bf16 v[64:67], v[140:143], v[184:187], v[64:67]
	v_mfma_f32_16x16x32_bf16 v[64:67], v[148:151], v[188:191], v[64:67]
	s_add_i32 s26, s26, 2
	s_add_u32 s38, s38, 0x100
	v_mfma_f32_16x16x32_bf16 v[60:63], v[152:155], v[184:187], v[60:63]
	v_mfma_f32_16x16x32_bf16 v[60:63], v[164:167], v[188:191], v[60:63]
	s_addc_u32 s39, s39, 0
	s_add_u32 s24, s24, 0x100
	v_mfma_f32_16x16x32_bf16 v[56:59], v[140:143], v[192:195], v[56:59]
	v_mfma_f32_16x16x32_bf16 v[56:59], v[148:151], v[204:207], v[56:59]
	s_addc_u32 s25, s25, 0
	s_add_u32 s27, s38, 0xfff80080
	v_mfma_f32_16x16x32_bf16 v[48:51], v[152:155], v[192:195], v[48:51]
	v_mfma_f32_16x16x32_bf16 v[48:51], v[164:167], v[204:207], v[48:51]
	s_addc_u32 s30, s39, -1
	s_add_i32 s31, 0, 0x10000
	v_mfma_f32_16x16x32_bf16 v[40:43], v[140:143], v[208:211], v[40:43]
	v_mfma_f32_16x16x32_bf16 v[40:43], v[148:151], v[212:215], v[40:43]
	s_cmp_eq_u32 s26, 28
	s_cselect_b32 s43, s11, s30
	v_mfma_f32_16x16x32_bf16 v[32:35], v[152:155], v[208:211], v[32:35]
	v_mfma_f32_16x16x32_bf16 v[32:35], v[164:167], v[212:215], v[32:35]
	s_cselect_b32 s42, s18, s27
	s_cselect_b32 s41, s9, s25
	v_mfma_f32_16x16x32_bf16 v[24:27], v[140:143], v[216:219], v[24:27]
	v_mfma_f32_16x16x32_bf16 v[24:27], v[148:151], v[220:223], v[24:27]
	s_cselect_b32 s40, s19, s24
	s_add_i32 s27, 0, 0x14000
	v_mfma_f32_16x16x32_bf16 v[16:19], v[152:155], v[216:219], v[16:19]
	v_mfma_f32_16x16x32_bf16 v[16:19], v[164:167], v[220:223], v[16:19]
	v_mfma_f32_16x16x32_bf16 v[52:55], v[168:171], v[184:187], v[52:55]
	v_mfma_f32_16x16x32_bf16 v[52:55], v[172:175], v[188:191], v[52:55]
	v_mfma_f32_16x16x32_bf16 v[44:47], v[176:179], v[184:187], v[44:47]
	v_mfma_f32_16x16x32_bf16 v[44:47], v[180:183], v[188:191], v[44:47]
	v_mfma_f32_16x16x32_bf16 v[36:39], v[168:171], v[192:195], v[36:39]
	v_mfma_f32_16x16x32_bf16 v[36:39], v[172:175], v[204:207], v[36:39]
	v_mfma_f32_16x16x32_bf16 v[28:31], v[176:179], v[192:195], v[28:31]
	v_mfma_f32_16x16x32_bf16 v[28:31], v[180:183], v[204:207], v[28:31]
	v_mfma_f32_16x16x32_bf16 v[20:23], v[168:171], v[208:211], v[20:23]
	v_mfma_f32_16x16x32_bf16 v[20:23], v[172:175], v[212:215], v[20:23]
	v_mfma_f32_16x16x32_bf16 v[12:15], v[176:179], v[208:211], v[12:15]
	v_mfma_f32_16x16x32_bf16 v[12:15], v[180:183], v[212:215], v[12:15]
	v_mfma_f32_16x16x32_bf16 v[8:11], v[168:171], v[216:219], v[8:11]
	v_mfma_f32_16x16x32_bf16 v[8:11], v[172:175], v[220:223], v[8:11]
	s_setprio 3
	s_barrier
	v_mfma_f32_16x16x32_bf16 v[4:7], v[176:179], v[216:219], v[4:7]
	v_mfma_f32_16x16x32_bf16 v[4:7], v[180:183], v[220:223], v[4:7]
	s_setprio 0
	s_cmp_gt_u32 s26, 29
	s_cbranch_scc1 .Lpeel_exit_218
.LBB0_218:
	v_add_u32_e32 v156, s31, v145
	ds_read_b128 v[140:143], v156
	ds_read_b128 v[148:151], v156 offset:1024
	ds_read_b128 v[152:155], v156 offset:2048
	ds_read_b128 v[164:167], v156 offset:3072
	v_add_u32_e32 v156, s27, v145
	ds_read_b128 v[168:171], v156
	ds_read_b128 v[172:175], v156 offset:1024
	ds_read_b128 v[176:179], v156 offset:2048
	ds_read_b128 v[180:183], v156 offset:3072
	v_lshl_add_u64 v[156:157], s[38:39], 0, v[136:137]
	s_add_i32 m0, s58, 0xc000
	ds_read_b128 v[184:187], v147
	ds_read_b128 v[188:191], v147 offset:1024
	ds_read_b128 v[192:195], v147 offset:2048
	ds_read_b128 v[204:207], v147 offset:3072
	ds_read_b128 v[208:211], v147 offset:4096
	ds_read_b128 v[212:215], v147 offset:5120
	ds_read_b128 v[216:219], v147 offset:6144
	ds_read_b128 v[220:223], v147 offset:7168
	global_load_lds_dwordx4 v[156:157], off
	v_lshl_add_u64 v[156:157], s[38:39], 0, v[138:139]
	s_add_i32 m0, s58, 0xe000
	s_nop 0
	global_load_lds_dwordx4 v[156:157], off
	s_waitcnt vmcnt(8)
	s_waitcnt lgkmcnt(0)
	s_barrier
; #define PG8_STAGE(bufoff, gbase, voff) do { _Pragma("unroll") for (int _i = 0; _i < 2; ++_i) \
;         __builtin_amdgcn_global_load_lds((const unsigned*)((const char*)(gbase) + (voff)[_i]), (LAS unsigned*)(lds + (bufoff) + ldsw + _i * 8192), 16, 0, 0); } while (0)
; #define PG8_LDA(dst, b, h) do { _Pragma("unroll") for (int m = 0; m < 4; ++m) _Pragma("unroll") for (int k = 0; k < 2; ++k) dst[m][k] = *(const LAS bf16x8*)(lds + PG8_SA(b, h) + aoff + m * 2048 + k * 1024); } while (0)
; #define PG8_MMA(ai, bj, At, Bt) do { __builtin_amdgcn_s_setprio(1); _Pragma("unroll") for (int m = 0; m < 4; ++m) _Pragma("unroll") for (int n = 0; n < 2; ++n) _Pragma("unroll") for (int k = 0; k < 2; ++k) \
;         acc[ai][bj][m][n] = __builtin_amdgcn_mfma_f32_16x16x32_bf16(Bt[n][k], At[m][k], acc[ai][bj][m][n], 0, 0, 0); __builtin_amdgcn_s_setprio(0); } while (0)
; #define PG8_WAIT_V(n) asm volatile("s_waitcnt vmcnt(" #n ")" ::: "memory")
; #define PG8_WAIT_L(n) asm volatile("s_waitcnt lgkmcnt(" #n ")" ::: "memory")
; #define PG8_BAR __builtin_amdgcn_s_barrier()
; #define PG8_SCHED __builtin_amdgcn_sched_barrier(0)
; template <class Epi, class Sched, bool ALIGN_EPI = true>
; __device__ __forceinline__ void gemm_phase(LAS unsigned char* lds, const Gemm g, const Sched& S, const Epi& E) {
;     ...
;             PG8_WAIT_V(8); PG8_WAIT_L(0); PG8_BAR; PG8_MMA(0, 0, At, B0); PG8_MMA(0, 1, At, B1); PG8_BAR; PG8_SCHED;
;             PG8_LDA(At, 0, 1); PG8_STAGE(PG8_SB(0, 0), b2, voffB); PG8_STAGE(PG8_SB(0, 1), b2 + hB, voffB); PG8_STAGE(PG8_SA(0, 0), a2, voffA);
;             PG8_WAIT_V(8); PG8_WAIT_L(0); PG8_BAR; PG8_MMA(1, 0, At, B0); PG8_MMA(1, 1, At, B1); PG8_BAR; PG8_SCHED;
	s_setprio 1
	s_waitcnt lgkmcnt(0)
	v_mfma_f32_16x16x32_bf16 v[128:131], v[140:143], v[184:187], v[128:131]
	v_mfma_f32_16x16x32_bf16 v[128:131], v[148:151], v[188:191], v[128:131]
	v_mfma_f32_16x16x32_bf16 v[124:127], v[152:155], v[184:187], v[124:127]
	v_mfma_f32_16x16x32_bf16 v[124:127], v[164:167], v[188:191], v[124:127]
	v_mfma_f32_16x16x32_bf16 v[120:123], v[140:143], v[192:195], v[120:123]
	v_mfma_f32_16x16x32_bf16 v[120:123], v[148:151], v[204:207], v[120:123]
	v_mfma_f32_16x16x32_bf16 v[112:115], v[152:155], v[192:195], v[112:115]
	v_mfma_f32_16x16x32_bf16 v[112:115], v[164:167], v[204:207], v[112:115]
	v_mfma_f32_16x16x32_bf16 v[104:107], v[140:143], v[208:211], v[104:107]
	v_mfma_f32_16x16x32_bf16 v[104:107], v[148:151], v[212:215], v[104:107]
	v_mfma_f32_16x16x32_bf16 v[96:99], v[152:155], v[208:211], v[96:99]
	v_mfma_f32_16x16x32_bf16 v[96:99], v[164:167], v[212:215], v[96:99]
	v_mfma_f32_16x16x32_bf16 v[88:91], v[140:143], v[216:219], v[88:91]
	v_mfma_f32_16x16x32_bf16 v[88:91], v[148:151], v[220:223], v[88:91]
	v_mfma_f32_16x16x32_bf16 v[80:83], v[152:155], v[216:219], v[80:83]
	v_mfma_f32_16x16x32_bf16 v[80:83], v[164:167], v[220:223], v[80:83]
	v_mfma_f32_16x16x32_bf16 v[116:119], v[168:171], v[184:187], v[116:119]
	v_mfma_f32_16x16x32_bf16 v[116:119], v[172:175], v[188:191], v[116:119]
	v_mfma_f32_16x16x32_bf16 v[108:111], v[176:179], v[184:187], v[108:111]
	v_mfma_f32_16x16x32_bf16 v[108:111], v[180:183], v[188:191], v[108:111]
	v_mfma_f32_16x16x32_bf16 v[100:103], v[168:171], v[192:195], v[100:103]
	v_mfma_f32_16x16x32_bf16 v[100:103], v[172:175], v[204:207], v[100:103]
	v_mfma_f32_16x16x32_bf16 v[92:95], v[176:179], v[192:195], v[92:95]
	v_mfma_f32_16x16x32_bf16 v[92:95], v[180:183], v[204:207], v[92:95]
	v_mfma_f32_16x16x32_bf16 v[84:87], v[168:171], v[208:211], v[84:87]
	v_mfma_f32_16x16x32_bf16 v[84:87], v[172:175], v[212:215], v[84:87]
	v_mfma_f32_16x16x32_bf16 v[76:79], v[176:179], v[208:211], v[76:79]
	v_mfma_f32_16x16x32_bf16 v[76:79], v[180:183], v[212:215], v[76:79]
	v_mfma_f32_16x16x32_bf16 v[72:75], v[168:171], v[216:219], v[72:75]
	v_mfma_f32_16x16x32_bf16 v[72:75], v[172:175], v[220:223], v[72:75]
	s_setprio 3
	s_barrier
	v_mfma_f32_16x16x32_bf16 v[68:71], v[176:179], v[216:219], v[68:71]
	v_mfma_f32_16x16x32_bf16 v[68:71], v[180:183], v[220:223], v[68:71]
	s_setprio 0
	s_add_i32 s30, s31, s53
	v_lshl_add_u64 v[156:157], s[40:41], 0, v[2:3]
	s_mov_b32 m0, s30
	ds_read_b128 v[184:187], v147 offset:16384
	ds_read_b128 v[188:191], v147 offset:17408
	ds_read_b128 v[192:195], v147 offset:18432
	ds_read_b128 v[204:207], v147 offset:19456
	ds_read_b128 v[208:211], v147 offset:20480
	ds_read_b128 v[212:215], v147 offset:21504
	ds_read_b128 v[216:219], v147 offset:22528
	ds_read_b128 v[220:223], v147 offset:23552
	global_load_lds_dwordx4 v[156:157], off
	s_add_i32 m0, s30, 0x2000
	s_add_u32 s30, s40, 0x80000
	v_lshl_add_u64 v[196:197], s[40:41], 0, v[0:1]
	s_addc_u32 s31, s41, 0
	s_add_i32 s27, s27, s53
	global_load_lds_dwordx4 v[196:197], off
	v_lshl_add_u64 v[224:225], s[30:31], 0, v[2:3]
	s_mov_b32 m0, s27
	v_lshl_add_u64 v[226:227], s[42:43], 0, v[132:133]
	global_load_lds_dwordx4 v[224:225], off
	v_lshl_add_u64 v[224:225], s[30:31], 0, v[0:1]
	s_add_i32 m0, s27, 0x2000
	s_nop 0
	global_load_lds_dwordx4 v[224:225], off
	v_lshl_add_u64 v[224:225], s[42:43], 0, v[134:135]
	s_mov_b32 m0, s58
	s_nop 0
	global_load_lds_dwordx4 v[224:225], off
	s_mov_b32 m0, s59
	s_nop 0
	global_load_lds_dwordx4 v[226:227], off
	s_waitcnt vmcnt(8)
	s_waitcnt lgkmcnt(0)
	s_barrier
	s_setprio 1
	s_waitcnt lgkmcnt(0)
	v_mfma_f32_16x16x32_bf16 v[64:67], v[140:143], v[184:187], v[64:67]
	v_mfma_f32_16x16x32_bf16 v[64:67], v[148:151], v[188:191], v[64:67]
	v_mfma_f32_16x16x32_bf16 v[60:63], v[152:155], v[184:187], v[60:63]
	v_mfma_f32_16x16x32_bf16 v[60:63], v[164:167], v[188:191], v[60:63]
	v_mfma_f32_16x16x32_bf16 v[56:59], v[140:143], v[192:195], v[56:59]
	v_mfma_f32_16x16x32_bf16 v[56:59], v[148:151], v[204:207], v[56:59]
	v_mfma_f32_16x16x32_bf16 v[48:51], v[152:155], v[192:195], v[48:51]
	v_mfma_f32_16x16x32_bf16 v[48:51], v[164:167], v[204:207], v[48:51]
	v_mfma_f32_16x16x32_bf16 v[40:43], v[140:143], v[208:211], v[40:43]
	v_mfma_f32_16x16x32_bf16 v[40:43], v[148:151], v[212:215], v[40:43]
	v_mfma_f32_16x16x32_bf16 v[32:35], v[152:155], v[208:211], v[32:35]
	v_mfma_f32_16x16x32_bf16 v[32:35], v[164:167], v[212:215], v[32:35]
	v_mfma_f32_16x16x32_bf16 v[24:27], v[140:143], v[216:219], v[24:27]
	v_mfma_f32_16x16x32_bf16 v[24:27], v[148:151], v[220:223], v[24:27]
	v_mfma_f32_16x16x32_bf16 v[16:19], v[152:155], v[216:219], v[16:19]
	v_mfma_f32_16x16x32_bf16 v[16:19], v[164:167], v[220:223], v[16:19]
	v_mfma_f32_16x16x32_bf16 v[52:55], v[168:171], v[184:187], v[52:55]
	v_mfma_f32_16x16x32_bf16 v[52:55], v[172:175], v[188:191], v[52:55]
	v_mfma_f32_16x16x32_bf16 v[44:47], v[176:179], v[184:187], v[44:47]
	v_mfma_f32_16x16x32_bf16 v[44:47], v[180:183], v[188:191], v[44:47]
	v_mfma_f32_16x16x32_bf16 v[36:39], v[168:171], v[192:195], v[36:39]
	v_mfma_f32_16x16x32_bf16 v[36:39], v[172:175], v[204:207], v[36:39]
	v_mfma_f32_16x16x32_bf16 v[28:31], v[176:179], v[192:195], v[28:31]
	v_mfma_f32_16x16x32_bf16 v[28:31], v[180:183], v[204:207], v[28:31]
	v_mfma_f32_16x16x32_bf16 v[20:23], v[168:171], v[208:211], v[20:23]
	v_mfma_f32_16x16x32_bf16 v[20:23], v[172:175], v[212:215], v[20:23]
	v_mfma_f32_16x16x32_bf16 v[12:15], v[176:179], v[208:211], v[12:15]
	v_mfma_f32_16x16x32_bf16 v[12:15], v[180:183], v[212:215], v[12:15]
	v_mfma_f32_16x16x32_bf16 v[8:11], v[168:171], v[216:219], v[8:11]
	v_mfma_f32_16x16x32_bf16 v[8:11], v[172:175], v[220:223], v[8:11]
	s_setprio 3
	s_barrier
; #define PG8_STAGE(bufoff, gbase, voff) do { _Pragma("unroll") for (int _i = 0; _i < 2; ++_i) \
;         __builtin_amdgcn_global_load_lds((const unsigned*)((const char*)(gbase) + (voff)[_i]), (LAS unsigned*)(lds + (bufoff) + ldsw + _i * 8192), 16, 0, 0); } while (0)
; #define PG8_LDA(dst, b, h) do { _Pragma("unroll") for (int m = 0; m < 4; ++m) _Pragma("unroll") for (int k = 0; k < 2; ++k) dst[m][k] = *(const LAS bf16x8*)(lds + PG8_SA(b, h) + aoff + m * 2048 + k * 1024); } while (0)
; #define PG8_LDB(dst, b, h) do { _Pragma("unroll") for (int n = 0; n < 2; ++n) _Pragma("unroll") for (int k = 0; k < 2; ++k) dst[n][k] = *(const LAS bf16x8*)(lds + PG8_SB(b, h) + boff + n * 2048 + k * 1024); } while (0)
; #define PG8_MMA(ai, bj, At, Bt) do { __builtin_amdgcn_s_setprio(1); _Pragma("unroll") for (int m = 0; m < 4; ++m) _Pragma("unroll") for (int n = 0; n < 2; ++n) _Pragma("unroll") for (int k = 0; k < 2; ++k) \
;         acc[ai][bj][m][n] = __builtin_amdgcn_mfma_f32_16x16x32_bf16(Bt[n][k], At[m][k], acc[ai][bj][m][n], 0, 0, 0); __builtin_amdgcn_s_setprio(0); } while (0)
; #define PG8_WAIT_V(n) asm volatile("s_waitcnt vmcnt(" #n ")" ::: "memory")
; #define PG8_WAIT_L(n) asm volatile("s_waitcnt lgkmcnt(" #n ")" ::: "memory")
; #define PG8_BAR __builtin_amdgcn_s_barrier()
; #define PG8_SCHED __builtin_amdgcn_sched_barrier(0)
; template <class Epi, class Sched, bool ALIGN_EPI = true>
; __device__ __forceinline__ void gemm_phase(LAS unsigned char* lds, const Gemm g, const Sched& S, const Epi& E) {
;     ...
;             PG8_WAIT_V(8); PG8_WAIT_L(0); PG8_BAR; PG8_MMA(1, 0, At, B0); PG8_MMA(1, 1, At, B1); PG8_BAR; PG8_SCHED;
;             PG8_LDB(B0, 1, 0); PG8_LDB(B1, 1, 1); PG8_SCHED; PG8_LDA(At, 1, 0); PG8_STAGE(PG8_SA(0, 1), a2 + hA, voffA);
;             PG8_WAIT_V(8); PG8_WAIT_L(0); PG8_BAR; PG8_MMA(0, 0, At, B0); PG8_MMA(0, 1, At, B1); PG8_BAR; PG8_SCHED;
	v_mfma_f32_16x16x32_bf16 v[4:7], v[176:179], v[216:219], v[4:7]
	v_mfma_f32_16x16x32_bf16 v[4:7], v[180:183], v[220:223], v[4:7]
	s_setprio 0
	s_add_i32 s27, 0, 0x18000
	v_add_u32_e32 v158, s27, v145
	s_add_i32 s65, 0, 0x1c000
	ds_read_b128 v[140:143], v158
	ds_read_b128 v[148:151], v158 offset:1024
	ds_read_b128 v[152:155], v158 offset:2048
	ds_read_b128 v[164:167], v158 offset:3072
	v_add_u32_e32 v158, s65, v145
	ds_read_b128 v[168:171], v158
	ds_read_b128 v[172:175], v158 offset:1024
	ds_read_b128 v[176:179], v158 offset:2048
	ds_read_b128 v[180:183], v158 offset:3072
	s_add_u32 s30, s42, 0x80000
	s_addc_u32 s31, s43, 0
	s_mov_b32 m0, s60
	v_lshl_add_u64 v[228:229], s[30:31], 0, v[134:135]
	ds_read_b128 v[184:187], v147 offset:32768
	ds_read_b128 v[188:191], v147 offset:33792
	ds_read_b128 v[192:195], v147 offset:34816
	ds_read_b128 v[204:207], v147 offset:35840
	ds_read_b128 v[208:211], v147 offset:36864
	ds_read_b128 v[212:215], v147 offset:37888
	ds_read_b128 v[216:219], v147 offset:38912
	ds_read_b128 v[220:223], v147 offset:39936
	global_load_lds_dwordx4 v[228:229], off
	v_lshl_add_u64 v[228:229], s[30:31], 0, v[132:133]
	s_mov_b32 m0, s61
	s_nop 0
	global_load_lds_dwordx4 v[228:229], off
	s_waitcnt vmcnt(8)
	s_waitcnt lgkmcnt(0)
	s_barrier
	s_setprio 1
	s_waitcnt lgkmcnt(0)
	v_mfma_f32_16x16x32_bf16 v[128:131], v[140:143], v[184:187], v[128:131]
	v_mfma_f32_16x16x32_bf16 v[128:131], v[148:151], v[188:191], v[128:131]
	v_mfma_f32_16x16x32_bf16 v[124:127], v[152:155], v[184:187], v[124:127]
	v_mfma_f32_16x16x32_bf16 v[124:127], v[164:167], v[188:191], v[124:127]
	v_mfma_f32_16x16x32_bf16 v[120:123], v[140:143], v[192:195], v[120:123]
	v_mfma_f32_16x16x32_bf16 v[120:123], v[148:151], v[204:207], v[120:123]
	v_mfma_f32_16x16x32_bf16 v[112:115], v[152:155], v[192:195], v[112:115]
	v_mfma_f32_16x16x32_bf16 v[112:115], v[164:167], v[204:207], v[112:115]
	v_mfma_f32_16x16x32_bf16 v[104:107], v[140:143], v[208:211], v[104:107]
	v_mfma_f32_16x16x32_bf16 v[104:107], v[148:151], v[212:215], v[104:107]
	v_mfma_f32_16x16x32_bf16 v[96:99], v[152:155], v[208:211], v[96:99]
	v_mfma_f32_16x16x32_bf16 v[96:99], v[164:167], v[212:215], v[96:99]
	v_mfma_f32_16x16x32_bf16 v[88:91], v[140:143], v[216:219], v[88:91]
	v_mfma_f32_16x16x32_bf16 v[88:91], v[148:151], v[220:223], v[88:91]
	v_mfma_f32_16x16x32_bf16 v[80:83], v[152:155], v[216:219], v[80:83]
	v_mfma_f32_16x16x32_bf16 v[80:83], v[164:167], v[220:223], v[80:83]
	v_mfma_f32_16x16x32_bf16 v[116:119], v[168:171], v[184:187], v[116:119]
	v_mfma_f32_16x16x32_bf16 v[116:119], v[172:175], v[188:191], v[116:119]
	v_mfma_f32_16x16x32_bf16 v[108:111], v[176:179], v[184:187], v[108:111]
	v_mfma_f32_16x16x32_bf16 v[108:111], v[180:183], v[188:191], v[108:111]
	v_mfma_f32_16x16x32_bf16 v[100:103], v[168:171], v[192:195], v[100:103]
	v_mfma_f32_16x16x32_bf16 v[100:103], v[172:175], v[204:207], v[100:103]
	v_mfma_f32_16x16x32_bf16 v[92:95], v[176:179], v[192:195], v[92:95]
	v_mfma_f32_16x16x32_bf16 v[92:95], v[180:183], v[204:207], v[92:95]
	v_mfma_f32_16x16x32_bf16 v[84:87], v[168:171], v[208:211], v[84:87]
	v_mfma_f32_16x16x32_bf16 v[84:87], v[172:175], v[212:215], v[84:87]
	v_mfma_f32_16x16x32_bf16 v[76:79], v[176:179], v[208:211], v[76:79]
	v_mfma_f32_16x16x32_bf16 v[76:79], v[180:183], v[212:215], v[76:79]
	v_mfma_f32_16x16x32_bf16 v[72:75], v[168:171], v[216:219], v[72:75]
	v_mfma_f32_16x16x32_bf16 v[72:75], v[172:175], v[220:223], v[72:75]
	s_setprio 3
	s_barrier
; #define PG8_STAGE(bufoff, gbase, voff) do { _Pragma("unroll") for (int _i = 0; _i < 2; ++_i) \
;         __builtin_amdgcn_global_load_lds((const unsigned*)((const char*)(gbase) + (voff)[_i]), (LAS unsigned*)(lds + (bufoff) + ldsw + _i * 8192), 16, 0, 0); } while (0)
; #define PG8_LDA(dst, b, h) do { _Pragma("unroll") for (int m = 0; m < 4; ++m) _Pragma("unroll") for (int k = 0; k < 2; ++k) dst[m][k] = *(const LAS bf16x8*)(lds + PG8_SA(b, h) + aoff + m * 2048 + k * 1024); } while (0)
; #define PG8_LDB(dst, b, h) do { _Pragma("unroll") for (int n = 0; n < 2; ++n) _Pragma("unroll") for (int k = 0; k < 2; ++k) dst[n][k] = *(const LAS bf16x8*)(lds + PG8_SB(b, h) + boff + n * 2048 + k * 1024); } while (0)
; #define PG8_WAIT_V(n) asm volatile("s_waitcnt vmcnt(" #n ")" ::: "memory")
; #define PG8_WAIT_L(n) asm volatile("s_waitcnt lgkmcnt(" #n ")" ::: "memory")
; template <class Epi, class Sched, bool ALIGN_EPI = true>
; __device__ __forceinline__ void gemm_phase(LAS unsigned char* lds, const Gemm g, const Sched& S, const Epi& E) {
;     ...
;             const bool last = (t == nt - 2);
;             const char* a1 = cA + (size_t)(t + 1) * kstep;
;             const char* a2 = last ? nA : cA + (size_t)(t + 2) * kstep; const char* b2 = last ? nB : cB + (size_t)(t + 2) * kstep;
;             const char* a3 = a2 + kstep; const char* b3 = b2 + kstep;
;             PG8_LDB(B0, 0, 0); PG8_LDB(B1, 0, 1); PG8_SCHED; PG8_LDA(At, 0, 0); PG8_STAGE(PG8_SA(1, 1), a1 + hA, voffA);
;             PG8_WAIT_V(8); PG8_WAIT_L(0); PG8_BAR; PG8_MMA(0, 0, At, B0); PG8_MMA(0, 1, At, B1); PG8_BAR; PG8_SCHED;
;             PG8_LDA(At, 0, 1); PG8_STAGE(PG8_SB(0, 0), b2, voffB); PG8_STAGE(PG8_SB(0, 1), b2 + hB, voffB); PG8_STAGE(PG8_SA(0, 0), a2, voffA);
;             PG8_WAIT_V(8); PG8_WAIT_L(0); PG8_BAR; PG8_MMA(1, 0, At, B0); PG8_MMA(1, 1, At, B1); PG8_BAR; PG8_SCHED;
;             PG8_LDB(B0, 1, 0); PG8_LDB(B1, 1, 1); PG8_SCHED; PG8_LDA(At, 1, 0); PG8_STAGE(PG8_SA(0, 1), a2 + hA, voffA);
;             PG8_WAIT_V(8); PG8_WAIT_L(0); PG8_BAR; PG8_MMA(0, 0, At, B0); PG8_MMA(0, 1, At, B1); PG8_BAR; PG8_SCHED;
;             PG8_LDA(At, 1, 1); PG8_STAGE(PG8_SB(1, 0), b3, voffB); PG8_STAGE(PG8_SB(1, 1), b3 + hB, voffB); PG8_STAGE(PG8_SA(1, 0), a3, voffA);
;             PG8_WAIT_V(8); PG8_WAIT_L(0); PG8_BAR; PG8_MMA(1, 0, At, B0); PG8_MMA(1, 1, At, B1); PG8_BAR; PG8_SCHED;
	v_mfma_f32_16x16x32_bf16 v[68:71], v[176:179], v[216:219], v[68:71]
	v_mfma_f32_16x16x32_bf16 v[68:71], v[180:183], v[220:223], v[68:71]
	s_setprio 0
	s_add_i32 s27, s27, s53
	v_lshl_add_u64 v[156:157], v[156:157], 0, s[86:87]
	s_mov_b32 m0, s27
	ds_read_b128 v[184:187], v147 offset:49152
	ds_read_b128 v[188:191], v147 offset:50176
	ds_read_b128 v[192:195], v147 offset:51200
	ds_read_b128 v[204:207], v147 offset:52224
	ds_read_b128 v[208:211], v147 offset:53248
	ds_read_b128 v[212:215], v147 offset:54272
	ds_read_b128 v[216:219], v147 offset:55296
	ds_read_b128 v[220:223], v147 offset:56320
	global_load_lds_dwordx4 v[156:157], off
	s_add_i32 m0, s27, 0x2000
	s_add_u32 s30, s40, 0x80080
	v_lshl_add_u64 v[156:157], v[196:197], 0, s[86:87]
	s_addc_u32 s31, s41, 0
	s_add_i32 s27, s65, s53
	global_load_lds_dwordx4 v[156:157], off
	v_lshl_add_u64 v[156:157], s[30:31], 0, v[2:3]
	s_mov_b32 m0, s27
	s_nop 0
	global_load_lds_dwordx4 v[156:157], off
	v_lshl_add_u64 v[156:157], s[30:31], 0, v[0:1]
	s_add_i32 m0, s27, 0x2000
	s_nop 0
	global_load_lds_dwordx4 v[156:157], off
	v_lshl_add_u64 v[156:157], v[224:225], 0, s[86:87]
	s_mov_b32 m0, s62
	s_nop 0
	global_load_lds_dwordx4 v[156:157], off
	v_lshl_add_u64 v[156:157], v[226:227], 0, s[86:87]
	s_mov_b32 m0, s63
	s_nop 0
	global_load_lds_dwordx4 v[156:157], off
	s_waitcnt vmcnt(8)
	s_waitcnt lgkmcnt(0)
	s_barrier
	s_setprio 1
	s_waitcnt lgkmcnt(0)
	v_mfma_f32_16x16x32_bf16 v[64:67], v[140:143], v[184:187], v[64:67]
	v_mfma_f32_16x16x32_bf16 v[64:67], v[148:151], v[188:191], v[64:67]
	s_add_i32 s26, s26, 2
	s_add_u32 s38, s38, 0x100
	v_mfma_f32_16x16x32_bf16 v[60:63], v[152:155], v[184:187], v[60:63]
	v_mfma_f32_16x16x32_bf16 v[60:63], v[164:167], v[188:191], v[60:63]
	s_addc_u32 s39, s39, 0
	s_add_u32 s24, s24, 0x100
	v_mfma_f32_16x16x32_bf16 v[56:59], v[140:143], v[192:195], v[56:59]
	v_mfma_f32_16x16x32_bf16 v[56:59], v[148:151], v[204:207], v[56:59]
	s_addc_u32 s25, s25, 0
	s_add_u32 s27, s38, 0xfff80080
	v_mfma_f32_16x16x32_bf16 v[48:51], v[152:155], v[192:195], v[48:51]
	v_mfma_f32_16x16x32_bf16 v[48:51], v[164:167], v[204:207], v[48:51]
	s_addc_u32 s30, s39, -1
	s_add_i32 s31, 0, 0x10000
	v_mfma_f32_16x16x32_bf16 v[40:43], v[140:143], v[208:211], v[40:43]
	v_mfma_f32_16x16x32_bf16 v[40:43], v[148:151], v[212:215], v[40:43]
	s_cmp_eq_u32 s26, 28
	s_cselect_b32 s43, s11, s30
	v_mfma_f32_16x16x32_bf16 v[32:35], v[152:155], v[208:211], v[32:35]
	v_mfma_f32_16x16x32_bf16 v[32:35], v[164:167], v[212:215], v[32:35]
	s_cselect_b32 s42, s18, s27
	s_cselect_b32 s41, s9, s25
	v_mfma_f32_16x16x32_bf16 v[24:27], v[140:143], v[216:219], v[24:27]
	v_mfma_f32_16x16x32_bf16 v[24:27], v[148:151], v[220:223], v[24:27]
	s_cselect_b32 s40, s19, s24
	s_add_i32 s27, 0, 0x14000
	v_mfma_f32_16x16x32_bf16 v[16:19], v[152:155], v[216:219], v[16:19]
	v_mfma_f32_16x16x32_bf16 v[16:19], v[164:167], v[220:223], v[16:19]
	v_mfma_f32_16x16x32_bf16 v[52:55], v[168:171], v[184:187], v[52:55]
	v_mfma_f32_16x16x32_bf16 v[52:55], v[172:175], v[188:191], v[52:55]
	v_mfma_f32_16x16x32_bf16 v[44:47], v[176:179], v[184:187], v[44:47]
	v_mfma_f32_16x16x32_bf16 v[44:47], v[180:183], v[188:191], v[44:47]
	v_mfma_f32_16x16x32_bf16 v[36:39], v[168:171], v[192:195], v[36:39]
	v_mfma_f32_16x16x32_bf16 v[36:39], v[172:175], v[204:207], v[36:39]
	v_mfma_f32_16x16x32_bf16 v[28:31], v[176:179], v[192:195], v[28:31]
	v_mfma_f32_16x16x32_bf16 v[28:31], v[180:183], v[204:207], v[28:31]
	v_mfma_f32_16x16x32_bf16 v[20:23], v[168:171], v[208:211], v[20:23]
	v_mfma_f32_16x16x32_bf16 v[20:23], v[172:175], v[212:215], v[20:23]
	v_mfma_f32_16x16x32_bf16 v[12:15], v[176:179], v[208:211], v[12:15]
	v_mfma_f32_16x16x32_bf16 v[12:15], v[180:183], v[212:215], v[12:15]
	v_mfma_f32_16x16x32_bf16 v[8:11], v[168:171], v[216:219], v[8:11]
	v_mfma_f32_16x16x32_bf16 v[8:11], v[172:175], v[220:223], v[8:11]
	s_setprio 3
	s_barrier
	v_mfma_f32_16x16x32_bf16 v[4:7], v[176:179], v[216:219], v[4:7]
	v_mfma_f32_16x16x32_bf16 v[4:7], v[180:183], v[220:223], v[4:7]
	s_setprio 0
	s_cmp_gt_u32 s26, 29
	s_cbranch_scc0 .LBB0_218

;     __device__ bool next(int i, Unit& u) const { if (i >= 2) return false; const int x = c & 7, j = c >> 3; u.pm = 32 * i + 4 * x + (j & 3); u.pn = j >> 2; return true; }
; #define PG8_STAGE(bufoff, gbase, voff) do { _Pragma("unroll") for (int _i = 0; _i < 2; ++_i) \
;         __builtin_amdgcn_global_load_lds((const unsigned*)((const char*)(gbase) + (voff)[_i]), (LAS unsigned*)(lds + (bufoff) + ldsw + _i * 8192), 16, 0, 0); } while (0)
; #define PG8_LDA(dst, b, h) do { _Pragma("unroll") for (int m = 0; m < 4; ++m) _Pragma("unroll") for (int k = 0; k < 2; ++k) dst[m][k] = *(const LAS bf16x8*)(lds + PG8_SA(b, h) + aoff + m * 2048 + k * 1024); } while (0)
; #define PG8_LDB(dst, b, h) do { _Pragma("unroll") for (int n = 0; n < 2; ++n) _Pragma("unroll") for (int k = 0; k < 2; ++k) dst[n][k] = *(const LAS bf16x8*)(lds + PG8_SB(b, h) + boff + n * 2048 + k * 1024); } while (0)
; #define PG8_WAIT_V(n) asm volatile("s_waitcnt vmcnt(" #n ")" ::: "memory")
; #define PG8_WAIT_L(n) asm volatile("s_waitcnt lgkmcnt(" #n ")" ::: "memory")
; #define PG8_BAR __builtin_amdgcn_s_barrier()
; #define PG8_SCHED __builtin_amdgcn_sched_barrier(0)
; template <class Epi, class Sched, bool ALIGN_EPI = true>
; __device__ __forceinline__ void gemm_phase(LAS unsigned char* lds, const Gemm g, const Sched& S, const Epi& E) {
;     ...
;         const bool has_next = S.next(ui + 1, nxt);
;         const char* nA = has_next ? (const char*)g.A + ((size_t)nxt.pm * BM * g.lda + (size_t)nxt.pn * g.a_pn_off) * 2 : cA; const char* nB = has_next ? (const char*)g.Bt + (size_t)nxt.pn * BM * g.ldb * 2 : cB;
;         for (int t = 0; t < nt; t += 2) {
;             const bool last = (t == nt - 2);
;             const char* a1 = cA + (size_t)(t + 1) * kstep;
;             const char* a2 = last ? nA : cA + (size_t)(t + 2) * kstep; const char* b2 = last ? nB : cB + (size_t)(t + 2) * kstep;
;             const char* a3 = a2 + kstep; const char* b3 = b2 + kstep;
;             PG8_LDB(B0, 0, 0); PG8_LDB(B1, 0, 1); PG8_SCHED; PG8_LDA(At, 0, 0); PG8_STAGE(PG8_SA(1, 1), a1 + hA, voffA);
;             PG8_WAIT_V(8); PG8_WAIT_L(0); PG8_BAR; PG8_MMA(0, 0, At, B0); PG8_MMA(0, 1, At, B1); PG8_BAR; PG8_SCHED;
;             PG8_LDA(At, 0, 1); PG8_STAGE(PG8_SB(0, 0), b2, voffB); PG8_STAGE(PG8_SB(0, 1), b2 + hB, voffB); PG8_STAGE(PG8_SA(0, 0), a2, voffA);
.LBB0_666:
	s_mov_b32 s82, s81
	s_or_b32 s81, s17, s68
	s_mov_b64 s[10:11], s[12:13]
	s_lshl_b32 s12, s81, 20
	s_add_u32 s12, s28, s12
	s_addc_u32 s13, s29, 0
	s_and_b64 s[16:17], s[38:39], exec
	s_cselect_b32 s16, s13, s11
	s_cselect_b32 s17, s12, s10
	s_add_u32 s18, s10, 0x100
	s_addc_u32 s19, s11, 0
	s_add_u32 s10, s10, 0x80080
	s_addc_u32 s11, s11, 0
	v_lshl_add_u64 v[132:133], s[10:11], 0, v[166:167]
	v_lshl_add_u64 v[134:135], s[10:11], 0, v[168:169]
	s_mov_b32 s24, -2
	s_mov_b64 s[10:11], 0
	s_add_u32 vcc_lo, s10, 0x100
	s_addc_u32 vcc_hi, s11, 0
	s_add_u32 s25, s18, s10
	s_addc_u32 s26, s19, s11
	s_add_i32 s27, 0, 0x10000
	s_cmp_eq_u32 s24, 28
	s_cselect_b32 s65, s16, s26
	s_cselect_b32 s26, 0, vcc_lo
	s_cselect_b32 s64, s17, s25
	s_cselect_b32 s25, 0, vcc_hi
	s_add_u32 s62, s14, s26
	v_add_u32_e32 v160, s27, v186
	s_addc_u32 s63, s15, s25
	s_add_i32 s25, 0, 0x14000
	ds_read_b128 v[136:139], v160
	ds_read_b128 v[140:143], v160 offset:1024
	ds_read_b128 v[144:147], v160 offset:2048
	ds_read_b128 v[170:173], v160 offset:3072
	v_add_u32_e32 v160, s25, v186
	ds_read_b128 v[174:177], v160
	ds_read_b128 v[178:181], v160 offset:1024
	ds_read_b128 v[182:185], v160 offset:2048
	ds_read_b128 v[208:211], v160 offset:3072
	v_lshl_add_u64 v[244:245], v[132:133], 0, s[10:11]
	s_add_i32 m0, s53, 0xc000
	ds_read_b128 v[212:215], v197
	ds_read_b128 v[216:219], v197 offset:1024
	ds_read_b128 v[220:223], v197 offset:2048
	ds_read_b128 v[224:227], v197 offset:3072
	ds_read_b128 v[228:231], v197 offset:4096
	ds_read_b128 v[232:235], v197 offset:5120
	ds_read_b128 v[236:239], v197 offset:6144
	ds_read_b128 v[240:243], v197 offset:7168
	global_load_lds_dwordx4 v[244:245], off
	v_lshl_add_u64 v[244:245], v[134:135], 0, s[10:11]
	s_add_i32 m0, s53, 0xe000
	s_nop 0
	global_load_lds_dwordx4 v[244:245], off
	s_waitcnt vmcnt(8)
	s_waitcnt lgkmcnt(0)
	s_barrier
	s_setprio 1
	s_waitcnt lgkmcnt(0)
	v_mfma_f32_16x16x32_bf16 v[36:39], v[136:139], v[212:215], 0
	v_mfma_f32_16x16x32_bf16 v[36:39], v[140:143], v[216:219], v[36:39]
	v_mfma_f32_16x16x32_bf16 v[40:43], v[144:147], v[212:215], 0
	v_mfma_f32_16x16x32_bf16 v[40:43], v[170:173], v[216:219], v[40:43]
	v_mfma_f32_16x16x32_bf16 v[68:71], v[136:139], v[220:223], 0
	v_mfma_f32_16x16x32_bf16 v[68:71], v[140:143], v[224:227], v[68:71]
	v_mfma_f32_16x16x32_bf16 v[72:75], v[144:147], v[220:223], 0
	v_mfma_f32_16x16x32_bf16 v[72:75], v[170:173], v[224:227], v[72:75]
	v_mfma_f32_16x16x32_bf16 v[100:103], v[136:139], v[228:231], 0
	v_mfma_f32_16x16x32_bf16 v[100:103], v[140:143], v[232:235], v[100:103]
	v_mfma_f32_16x16x32_bf16 v[104:107], v[144:147], v[228:231], 0
	v_mfma_f32_16x16x32_bf16 v[104:107], v[170:173], v[232:235], v[104:107]
	v_mfma_f32_16x16x32_bf16 v[128:131], v[136:139], v[236:239], 0
	v_mfma_f32_16x16x32_bf16 v[128:131], v[140:143], v[240:243], v[128:131]
	v_mfma_f32_16x16x32_bf16 v[124:127], v[144:147], v[236:239], 0
	v_mfma_f32_16x16x32_bf16 v[124:127], v[170:173], v[240:243], v[124:127]
	v_mfma_f32_16x16x32_bf16 v[8:11], v[174:177], v[212:215], 0
	v_mfma_f32_16x16x32_bf16 v[8:11], v[178:181], v[216:219], v[8:11]
	v_mfma_f32_16x16x32_bf16 v[4:7], v[182:185], v[212:215], 0
	v_mfma_f32_16x16x32_bf16 v[4:7], v[208:211], v[216:219], v[4:7]
	v_mfma_f32_16x16x32_bf16 v[32:35], v[174:177], v[220:223], 0
	v_mfma_f32_16x16x32_bf16 v[32:35], v[178:181], v[224:227], v[32:35]
	v_mfma_f32_16x16x32_bf16 v[28:31], v[182:185], v[220:223], 0
	v_mfma_f32_16x16x32_bf16 v[28:31], v[208:211], v[224:227], v[28:31]
	v_mfma_f32_16x16x32_bf16 v[56:59], v[174:177], v[228:231], 0
	v_mfma_f32_16x16x32_bf16 v[56:59], v[178:181], v[232:235], v[56:59]
	v_mfma_f32_16x16x32_bf16 v[52:55], v[182:185], v[228:231], 0
	v_mfma_f32_16x16x32_bf16 v[52:55], v[208:211], v[232:235], v[52:55]
	v_mfma_f32_16x16x32_bf16 v[80:83], v[174:177], v[236:239], 0
	v_mfma_f32_16x16x32_bf16 v[80:83], v[178:181], v[240:243], v[80:83]
	s_setprio 3
	s_barrier
	v_mfma_f32_16x16x32_bf16 v[76:79], v[182:185], v[236:239], 0
	v_mfma_f32_16x16x32_bf16 v[76:79], v[208:211], v[240:243], v[76:79]
	s_setprio 0
	s_add_i32 s10, s27, s67
	v_lshl_add_u64 v[244:245], s[62:63], 0, v[2:3]
	s_mov_b32 m0, s10
	ds_read_b128 v[212:215], v197 offset:16384
	ds_read_b128 v[216:219], v197 offset:17408
	ds_read_b128 v[220:223], v197 offset:18432
	ds_read_b128 v[224:227], v197 offset:19456
	ds_read_b128 v[228:231], v197 offset:20480
	ds_read_b128 v[232:235], v197 offset:21504
	ds_read_b128 v[236:239], v197 offset:22528
	ds_read_b128 v[240:243], v197 offset:23552
	global_load_lds_dwordx4 v[244:245], off
	s_add_i32 m0, s10, 0x2000
	s_add_u32 s10, s62, 0x80000
	v_lshl_add_u64 v[246:247], s[62:63], 0, v[150:151]
	s_addc_u32 s11, s63, 0
	s_add_i32 s25, s25, s67
	global_load_lds_dwordx4 v[246:247], off
	v_lshl_add_u64 v[248:249], s[10:11], 0, v[2:3]
	s_mov_b32 m0, s25
	v_lshl_add_u64 v[160:161], s[64:65], 0, v[148:149]
	global_load_lds_dwordx4 v[248:249], off
	v_lshl_add_u64 v[248:249], s[10:11], 0, v[150:151]
	s_add_i32 m0, s25, 0x2000
	s_nop 0
	global_load_lds_dwordx4 v[248:249], off
	v_lshl_add_u64 v[248:249], s[64:65], 0, v[0:1]
	s_mov_b32 m0, s53
	s_nop 0
	global_load_lds_dwordx4 v[248:249], off
	s_mov_b32 m0, s66
	s_nop 0
	global_load_lds_dwordx4 v[160:161], off
	s_waitcnt vmcnt(8)
	s_waitcnt lgkmcnt(0)
	s_barrier
; #define PG8_STAGE(bufoff, gbase, voff) do { _Pragma("unroll") for (int _i = 0; _i < 2; ++_i) \
;         __builtin_amdgcn_global_load_lds((const unsigned*)((const char*)(gbase) + (voff)[_i]), (LAS unsigned*)(lds + (bufoff) + ldsw + _i * 8192), 16, 0, 0); } while (0)
; #define PG8_LDA(dst, b, h) do { _Pragma("unroll") for (int m = 0; m < 4; ++m) _Pragma("unroll") for (int k = 0; k < 2; ++k) dst[m][k] = *(const LAS bf16x8*)(lds + PG8_SA(b, h) + aoff + m * 2048 + k * 1024); } while (0)
; #define PG8_LDB(dst, b, h) do { _Pragma("unroll") for (int n = 0; n < 2; ++n) _Pragma("unroll") for (int k = 0; k < 2; ++k) dst[n][k] = *(const LAS bf16x8*)(lds + PG8_SB(b, h) + boff + n * 2048 + k * 1024); } while (0)
; #define PG8_MMA(ai, bj, At, Bt) do { __builtin_amdgcn_s_setprio(1); _Pragma("unroll") for (int m = 0; m < 4; ++m) _Pragma("unroll") for (int n = 0; n < 2; ++n) _Pragma("unroll") for (int k = 0; k < 2; ++k) \
;         acc[ai][bj][m][n] = __builtin_amdgcn_mfma_f32_16x16x32_bf16(Bt[n][k], At[m][k], acc[ai][bj][m][n], 0, 0, 0); __builtin_amdgcn_s_setprio(0); } while (0)
; #define PG8_WAIT_V(n) asm volatile("s_waitcnt vmcnt(" #n ")" ::: "memory")
; #define PG8_WAIT_L(n) asm volatile("s_waitcnt lgkmcnt(" #n ")" ::: "memory")
; #define PG8_BAR __builtin_amdgcn_s_barrier()
; #define PG8_SCHED __builtin_amdgcn_sched_barrier(0)
; template <class Epi, class Sched, bool ALIGN_EPI = true>
; __device__ __forceinline__ void gemm_phase(LAS unsigned char* lds, const Gemm g, const Sched& S, const Epi& E) {
;     ...
;             PG8_WAIT_V(8); PG8_WAIT_L(0); PG8_BAR; PG8_MMA(1, 0, At, B0); PG8_MMA(1, 1, At, B1); PG8_BAR; PG8_SCHED;
;             PG8_LDB(B0, 1, 0); PG8_LDB(B1, 1, 1); PG8_SCHED; PG8_LDA(At, 1, 0); PG8_STAGE(PG8_SA(0, 1), a2 + hA, voffA);
;             PG8_WAIT_V(8); PG8_WAIT_L(0); PG8_BAR; PG8_MMA(0, 0, At, B0); PG8_MMA(0, 1, At, B1); PG8_BAR; PG8_SCHED;
	s_setprio 1
	s_waitcnt lgkmcnt(0)
	v_mfma_f32_16x16x32_bf16 v[120:123], v[136:139], v[212:215], 0
	v_mfma_f32_16x16x32_bf16 v[120:123], v[140:143], v[216:219], v[120:123]
	v_mfma_f32_16x16x32_bf16 v[116:119], v[144:147], v[212:215], 0
	v_mfma_f32_16x16x32_bf16 v[116:119], v[170:173], v[216:219], v[116:119]
	v_mfma_f32_16x16x32_bf16 v[96:99], v[136:139], v[220:223], 0
	v_mfma_f32_16x16x32_bf16 v[96:99], v[140:143], v[224:227], v[96:99]
	v_mfma_f32_16x16x32_bf16 v[92:95], v[144:147], v[220:223], 0
	v_mfma_f32_16x16x32_bf16 v[92:95], v[170:173], v[224:227], v[92:95]
	v_mfma_f32_16x16x32_bf16 v[64:67], v[136:139], v[228:231], 0
	v_mfma_f32_16x16x32_bf16 v[64:67], v[140:143], v[232:235], v[64:67]
	v_mfma_f32_16x16x32_bf16 v[60:63], v[144:147], v[228:231], 0
	v_mfma_f32_16x16x32_bf16 v[60:63], v[170:173], v[232:235], v[60:63]
	v_mfma_f32_16x16x32_bf16 v[24:27], v[136:139], v[236:239], 0
	v_mfma_f32_16x16x32_bf16 v[24:27], v[140:143], v[240:243], v[24:27]
	v_mfma_f32_16x16x32_bf16 v[20:23], v[144:147], v[236:239], 0
	v_mfma_f32_16x16x32_bf16 v[20:23], v[170:173], v[240:243], v[20:23]
	v_mfma_f32_16x16x32_bf16 v[112:115], v[174:177], v[212:215], 0
	v_mfma_f32_16x16x32_bf16 v[112:115], v[178:181], v[216:219], v[112:115]
	v_mfma_f32_16x16x32_bf16 v[108:111], v[182:185], v[212:215], 0
	v_mfma_f32_16x16x32_bf16 v[108:111], v[208:211], v[216:219], v[108:111]
	v_mfma_f32_16x16x32_bf16 v[88:91], v[174:177], v[220:223], 0
	v_mfma_f32_16x16x32_bf16 v[88:91], v[178:181], v[224:227], v[88:91]
	v_mfma_f32_16x16x32_bf16 v[84:87], v[182:185], v[220:223], 0
	v_mfma_f32_16x16x32_bf16 v[84:87], v[208:211], v[224:227], v[84:87]
	v_mfma_f32_16x16x32_bf16 v[48:51], v[174:177], v[228:231], 0
	v_mfma_f32_16x16x32_bf16 v[48:51], v[178:181], v[232:235], v[48:51]
	v_mfma_f32_16x16x32_bf16 v[44:47], v[182:185], v[228:231], 0
	v_mfma_f32_16x16x32_bf16 v[44:47], v[208:211], v[232:235], v[44:47]
	v_mfma_f32_16x16x32_bf16 v[16:19], v[174:177], v[236:239], 0
	v_mfma_f32_16x16x32_bf16 v[16:19], v[178:181], v[240:243], v[16:19]
	s_setprio 3
	s_barrier
	v_mfma_f32_16x16x32_bf16 v[12:15], v[182:185], v[236:239], 0
	v_mfma_f32_16x16x32_bf16 v[12:15], v[208:211], v[240:243], v[12:15]
	s_setprio 0
	s_add_i32 s25, 0, 0x18000
	v_add_u32_e32 v162, s25, v186
	s_add_i32 s26, 0, 0x1c000
	ds_read_b128 v[136:139], v162
	ds_read_b128 v[140:143], v162 offset:1024
	ds_read_b128 v[144:147], v162 offset:2048
	ds_read_b128 v[170:173], v162 offset:3072
	v_add_u32_e32 v162, s26, v186
	ds_read_b128 v[174:177], v162
	ds_read_b128 v[178:181], v162 offset:1024
	ds_read_b128 v[182:185], v162 offset:2048
	ds_read_b128 v[208:211], v162 offset:3072
	s_add_u32 s10, s64, 0x80000
	s_addc_u32 s11, s65, 0
	s_mov_b32 m0, s75
	v_lshl_add_u64 v[162:163], s[10:11], 0, v[0:1]
	ds_read_b128 v[212:215], v197 offset:32768
	ds_read_b128 v[216:219], v197 offset:33792
	ds_read_b128 v[220:223], v197 offset:34816
	ds_read_b128 v[224:227], v197 offset:35840
	ds_read_b128 v[228:231], v197 offset:36864
	ds_read_b128 v[232:235], v197 offset:37888
	ds_read_b128 v[236:239], v197 offset:38912
	ds_read_b128 v[240:243], v197 offset:39936
	global_load_lds_dwordx4 v[162:163], off
	v_lshl_add_u64 v[162:163], s[10:11], 0, v[148:149]
	s_mov_b32 m0, s76
	s_nop 0
	global_load_lds_dwordx4 v[162:163], off
	s_waitcnt vmcnt(8)
	s_waitcnt lgkmcnt(0)
	s_barrier
	s_setprio 1
	s_waitcnt lgkmcnt(0)
	v_mfma_f32_16x16x32_bf16 v[36:39], v[136:139], v[212:215], v[36:39]
	v_mfma_f32_16x16x32_bf16 v[36:39], v[140:143], v[216:219], v[36:39]
	v_mfma_f32_16x16x32_bf16 v[40:43], v[144:147], v[212:215], v[40:43]
	v_mfma_f32_16x16x32_bf16 v[40:43], v[170:173], v[216:219], v[40:43]
	v_mfma_f32_16x16x32_bf16 v[68:71], v[136:139], v[220:223], v[68:71]
	v_mfma_f32_16x16x32_bf16 v[68:71], v[140:143], v[224:227], v[68:71]
	v_mfma_f32_16x16x32_bf16 v[72:75], v[144:147], v[220:223], v[72:75]
	v_mfma_f32_16x16x32_bf16 v[72:75], v[170:173], v[224:227], v[72:75]
	v_mfma_f32_16x16x32_bf16 v[100:103], v[136:139], v[228:231], v[100:103]
	v_mfma_f32_16x16x32_bf16 v[100:103], v[140:143], v[232:235], v[100:103]
	v_mfma_f32_16x16x32_bf16 v[104:107], v[144:147], v[228:231], v[104:107]
	v_mfma_f32_16x16x32_bf16 v[104:107], v[170:173], v[232:235], v[104:107]
	v_mfma_f32_16x16x32_bf16 v[128:131], v[136:139], v[236:239], v[128:131]
	v_mfma_f32_16x16x32_bf16 v[128:131], v[140:143], v[240:243], v[128:131]
	v_mfma_f32_16x16x32_bf16 v[124:127], v[144:147], v[236:239], v[124:127]
	v_mfma_f32_16x16x32_bf16 v[124:127], v[170:173], v[240:243], v[124:127]
	v_mfma_f32_16x16x32_bf16 v[8:11], v[174:177], v[212:215], v[8:11]
	v_mfma_f32_16x16x32_bf16 v[8:11], v[178:181], v[216:219], v[8:11]
	v_mfma_f32_16x16x32_bf16 v[4:7], v[182:185], v[212:215], v[4:7]
	v_mfma_f32_16x16x32_bf16 v[4:7], v[208:211], v[216:219], v[4:7]
	v_mfma_f32_16x16x32_bf16 v[32:35], v[174:177], v[220:223], v[32:35]
	v_mfma_f32_16x16x32_bf16 v[32:35], v[178:181], v[224:227], v[32:35]
	v_mfma_f32_16x16x32_bf16 v[28:31], v[182:185], v[220:223], v[28:31]
	v_mfma_f32_16x16x32_bf16 v[28:31], v[208:211], v[224:227], v[28:31]
	v_mfma_f32_16x16x32_bf16 v[56:59], v[174:177], v[228:231], v[56:59]
	v_mfma_f32_16x16x32_bf16 v[56:59], v[178:181], v[232:235], v[56:59]
	v_mfma_f32_16x16x32_bf16 v[52:55], v[182:185], v[228:231], v[52:55]
	v_mfma_f32_16x16x32_bf16 v[52:55], v[208:211], v[232:235], v[52:55]
	v_mfma_f32_16x16x32_bf16 v[80:83], v[174:177], v[236:239], v[80:83]
	v_mfma_f32_16x16x32_bf16 v[80:83], v[178:181], v[240:243], v[80:83]
	s_setprio 3
	s_barrier
; #define PG8_STAGE(bufoff, gbase, voff) do { _Pragma("unroll") for (int _i = 0; _i < 2; ++_i) \
;         __builtin_amdgcn_global_load_lds((const unsigned*)((const char*)(gbase) + (voff)[_i]), (LAS unsigned*)(lds + (bufoff) + ldsw + _i * 8192), 16, 0, 0); } while (0)
; #define PG8_LDA(dst, b, h) do { _Pragma("unroll") for (int m = 0; m < 4; ++m) _Pragma("unroll") for (int k = 0; k < 2; ++k) dst[m][k] = *(const LAS bf16x8*)(lds + PG8_SA(b, h) + aoff + m * 2048 + k * 1024); } while (0)
; #define PG8_LDB(dst, b, h) do { _Pragma("unroll") for (int n = 0; n < 2; ++n) _Pragma("unroll") for (int k = 0; k < 2; ++k) dst[n][k] = *(const LAS bf16x8*)(lds + PG8_SB(b, h) + boff + n * 2048 + k * 1024); } while (0)
; #define PG8_WAIT_V(n) asm volatile("s_waitcnt vmcnt(" #n ")" ::: "memory")
; #define PG8_WAIT_L(n) asm volatile("s_waitcnt lgkmcnt(" #n ")" ::: "memory")
; template <class Epi, class Sched, bool ALIGN_EPI = true>
; __device__ __forceinline__ void gemm_phase(LAS unsigned char* lds, const Gemm g, const Sched& S, const Epi& E) {
;     ...
;             const bool last = (t == nt - 2);
;             const char* a1 = cA + (size_t)(t + 1) * kstep;
;             const char* a2 = last ? nA : cA + (size_t)(t + 2) * kstep; const char* b2 = last ? nB : cB + (size_t)(t + 2) * kstep;
;             const char* a3 = a2 + kstep; const char* b3 = b2 + kstep;
;             PG8_LDB(B0, 0, 0); PG8_LDB(B1, 0, 1); PG8_SCHED; PG8_LDA(At, 0, 0); PG8_STAGE(PG8_SA(1, 1), a1 + hA, voffA);
;             PG8_WAIT_V(8); PG8_WAIT_L(0); PG8_BAR; PG8_MMA(0, 0, At, B0); PG8_MMA(0, 1, At, B1); PG8_BAR; PG8_SCHED;
;             PG8_LDA(At, 0, 1); PG8_STAGE(PG8_SB(0, 0), b2, voffB); PG8_STAGE(PG8_SB(0, 1), b2 + hB, voffB); PG8_STAGE(PG8_SA(0, 0), a2, voffA);
;             PG8_WAIT_V(8); PG8_WAIT_L(0); PG8_BAR; PG8_MMA(1, 0, At, B0); PG8_MMA(1, 1, At, B1); PG8_BAR; PG8_SCHED;
;             PG8_LDB(B0, 1, 0); PG8_LDB(B1, 1, 1); PG8_SCHED; PG8_LDA(At, 1, 0); PG8_STAGE(PG8_SA(0, 1), a2 + hA, voffA);
;             PG8_WAIT_V(8); PG8_WAIT_L(0); PG8_BAR; PG8_MMA(0, 0, At, B0); PG8_MMA(0, 1, At, B1); PG8_BAR; PG8_SCHED;
;             PG8_LDA(At, 1, 1); PG8_STAGE(PG8_SB(1, 0), b3, voffB); PG8_STAGE(PG8_SB(1, 1), b3 + hB, voffB); PG8_STAGE(PG8_SA(1, 0), a3, voffA);
;             PG8_WAIT_V(8); PG8_WAIT_L(0); PG8_BAR; PG8_MMA(1, 0, At, B0); PG8_MMA(1, 1, At, B1); PG8_BAR; PG8_SCHED;
	v_mfma_f32_16x16x32_bf16 v[76:79], v[182:185], v[236:239], v[76:79]
	v_mfma_f32_16x16x32_bf16 v[76:79], v[208:211], v[240:243], v[76:79]
	s_setprio 0
	s_add_i32 s10, s25, s67
	v_lshl_add_u64 v[162:163], v[244:245], 0, s[86:87]
	s_mov_b32 m0, s10
	ds_read_b128 v[212:215], v197 offset:49152
	ds_read_b128 v[216:219], v197 offset:50176
	ds_read_b128 v[220:223], v197 offset:51200
	ds_read_b128 v[224:227], v197 offset:52224
	ds_read_b128 v[228:231], v197 offset:53248
	ds_read_b128 v[232:235], v197 offset:54272
	ds_read_b128 v[236:239], v197 offset:55296
	ds_read_b128 v[240:243], v197 offset:56320
	global_load_lds_dwordx4 v[162:163], off
	s_add_i32 m0, s10, 0x2000
	s_add_u32 s10, s62, 0x80080
	v_lshl_add_u64 v[162:163], v[246:247], 0, s[86:87]
	s_addc_u32 s11, s63, 0
	s_add_i32 s25, s26, s67
	global_load_lds_dwordx4 v[162:163], off
	v_lshl_add_u64 v[162:163], s[10:11], 0, v[2:3]
	s_mov_b32 m0, s25
	v_lshl_add_u64 v[160:161], v[160:161], 0, s[86:87]
	global_load_lds_dwordx4 v[162:163], off
	v_lshl_add_u64 v[162:163], s[10:11], 0, v[150:151]
	s_add_i32 m0, s25, 0x2000
	s_nop 0
	global_load_lds_dwordx4 v[162:163], off
	v_lshl_add_u64 v[162:163], v[248:249], 0, s[86:87]
	s_mov_b32 m0, s79
	s_nop 0
	global_load_lds_dwordx4 v[162:163], off
	s_mov_b32 m0, s80
	s_nop 0
	global_load_lds_dwordx4 v[160:161], off
	s_waitcnt vmcnt(8)
	s_waitcnt lgkmcnt(0)
	s_barrier
	s_setprio 1
	s_waitcnt lgkmcnt(0)
	v_mfma_f32_16x16x32_bf16 v[120:123], v[136:139], v[212:215], v[120:123]
	v_mfma_f32_16x16x32_bf16 v[120:123], v[140:143], v[216:219], v[120:123]
	v_mfma_f32_16x16x32_bf16 v[116:119], v[144:147], v[212:215], v[116:119]
	v_mfma_f32_16x16x32_bf16 v[116:119], v[170:173], v[216:219], v[116:119]
	v_mfma_f32_16x16x32_bf16 v[96:99], v[136:139], v[220:223], v[96:99]
	v_mfma_f32_16x16x32_bf16 v[96:99], v[140:143], v[224:227], v[96:99]
	v_mfma_f32_16x16x32_bf16 v[92:95], v[144:147], v[220:223], v[92:95]
	v_mfma_f32_16x16x32_bf16 v[92:95], v[170:173], v[224:227], v[92:95]
	v_mfma_f32_16x16x32_bf16 v[64:67], v[136:139], v[228:231], v[64:67]
	v_mfma_f32_16x16x32_bf16 v[64:67], v[140:143], v[232:235], v[64:67]
	v_mfma_f32_16x16x32_bf16 v[60:63], v[144:147], v[228:231], v[60:63]
	v_mfma_f32_16x16x32_bf16 v[60:63], v[170:173], v[232:235], v[60:63]
	v_mfma_f32_16x16x32_bf16 v[24:27], v[136:139], v[236:239], v[24:27]
	v_mfma_f32_16x16x32_bf16 v[24:27], v[140:143], v[240:243], v[24:27]
	v_mfma_f32_16x16x32_bf16 v[20:23], v[144:147], v[236:239], v[20:23]
	v_mfma_f32_16x16x32_bf16 v[20:23], v[170:173], v[240:243], v[20:23]
	v_mfma_f32_16x16x32_bf16 v[112:115], v[174:177], v[212:215], v[112:115]
	v_mfma_f32_16x16x32_bf16 v[112:115], v[178:181], v[216:219], v[112:115]
	v_mfma_f32_16x16x32_bf16 v[108:111], v[182:185], v[212:215], v[108:111]
	v_mfma_f32_16x16x32_bf16 v[108:111], v[208:211], v[216:219], v[108:111]
	v_mfma_f32_16x16x32_bf16 v[88:91], v[174:177], v[220:223], v[88:91]
	v_mfma_f32_16x16x32_bf16 v[88:91], v[178:181], v[224:227], v[88:91]
	v_mfma_f32_16x16x32_bf16 v[84:87], v[182:185], v[220:223], v[84:87]
	v_mfma_f32_16x16x32_bf16 v[84:87], v[208:211], v[224:227], v[84:87]
	v_mfma_f32_16x16x32_bf16 v[48:51], v[174:177], v[228:231], v[48:51]
	v_mfma_f32_16x16x32_bf16 v[48:51], v[178:181], v[232:235], v[48:51]
	v_mfma_f32_16x16x32_bf16 v[44:47], v[182:185], v[228:231], v[44:47]
	v_mfma_f32_16x16x32_bf16 v[44:47], v[208:211], v[232:235], v[44:47]
	v_mfma_f32_16x16x32_bf16 v[16:19], v[174:177], v[236:239], v[16:19]
	v_mfma_f32_16x16x32_bf16 v[16:19], v[178:181], v[240:243], v[16:19]
	s_setprio 3
	s_barrier
	v_mfma_f32_16x16x32_bf16 v[12:15], v[182:185], v[236:239], v[12:15]
	v_mfma_f32_16x16x32_bf16 v[12:15], v[208:211], v[240:243], v[12:15]
	s_setprio 0
	s_add_i32 s24, s24, 2
	s_cmp_gt_u32 s24, 29
	s_mov_b64 s[10:11], vcc
	s_cbranch_scc1 .Lpeel_exit_667
.LBB0_667:
	s_add_u32 vcc_lo, s10, 0x100
	s_addc_u32 vcc_hi, s11, 0
	s_add_u32 s25, s18, s10
	s_addc_u32 s26, s19, s11
	s_add_i32 s27, 0, 0x10000
	s_cmp_eq_u32 s24, 28
	s_cselect_b32 s65, s16, s26
	s_cselect_b32 s26, 0, vcc_lo
	s_cselect_b32 s64, s17, s25
	s_cselect_b32 s25, 0, vcc_hi
	s_add_u32 s62, s14, s26
	v_add_u32_e32 v160, s27, v186
	s_addc_u32 s63, s15, s25
	s_add_i32 s25, 0, 0x14000
	ds_read_b128 v[136:139], v160
	ds_read_b128 v[140:143], v160 offset:1024
	ds_read_b128 v[144:147], v160 offset:2048
	ds_read_b128 v[170:173], v160 offset:3072
	v_add_u32_e32 v160, s25, v186
	ds_read_b128 v[174:177], v160
	ds_read_b128 v[178:181], v160 offset:1024
	ds_read_b128 v[182:185], v160 offset:2048
	ds_read_b128 v[208:211], v160 offset:3072
	v_lshl_add_u64 v[244:245], v[132:133], 0, s[10:11]
	s_add_i32 m0, s53, 0xc000
	ds_read_b128 v[212:215], v197
	ds_read_b128 v[216:219], v197 offset:1024
	ds_read_b128 v[220:223], v197 offset:2048
	ds_read_b128 v[224:227], v197 offset:3072
	ds_read_b128 v[228:231], v197 offset:4096
	ds_read_b128 v[232:235], v197 offset:5120
	ds_read_b128 v[236:239], v197 offset:6144
	ds_read_b128 v[240:243], v197 offset:7168
	global_load_lds_dwordx4 v[244:245], off
	v_lshl_add_u64 v[244:245], v[134:135], 0, s[10:11]
	s_add_i32 m0, s53, 0xe000
	s_nop 0
	global_load_lds_dwordx4 v[244:245], off
	s_waitcnt vmcnt(8)
	s_waitcnt lgkmcnt(0)
	s_barrier
; #define PG8_STAGE(bufoff, gbase, voff) do { _Pragma("unroll") for (int _i = 0; _i < 2; ++_i) \
;         __builtin_amdgcn_global_load_lds((const unsigned*)((const char*)(gbase) + (voff)[_i]), (LAS unsigned*)(lds + (bufoff) + ldsw + _i * 8192), 16, 0, 0); } while (0)
; #define PG8_LDA(dst, b, h) do { _Pragma("unroll") for (int m = 0; m < 4; ++m) _Pragma("unroll") for (int k = 0; k < 2; ++k) dst[m][k] = *(const LAS bf16x8*)(lds + PG8_SA(b, h) + aoff + m * 2048 + k * 1024); } while (0)
; #define PG8_MMA(ai, bj, At, Bt) do { __builtin_amdgcn_s_setprio(1); _Pragma("unroll") for (int m = 0; m < 4; ++m) _Pragma("unroll") for (int n = 0; n < 2; ++n) _Pragma("unroll") for (int k = 0; k < 2; ++k) \
;         acc[ai][bj][m][n] = __builtin_amdgcn_mfma_f32_16x16x32_bf16(Bt[n][k], At[m][k], acc[ai][bj][m][n], 0, 0, 0); __builtin_amdgcn_s_setprio(0); } while (0)
; #define PG8_WAIT_V(n) asm volatile("s_waitcnt vmcnt(" #n ")" ::: "memory")
; #define PG8_WAIT_L(n) asm volatile("s_waitcnt lgkmcnt(" #n ")" ::: "memory")
; #define PG8_BAR __builtin_amdgcn_s_barrier()
; #define PG8_SCHED __builtin_amdgcn_sched_barrier(0)
; template <class Epi, class Sched, bool ALIGN_EPI = true>
; __device__ __forceinline__ void gemm_phase(LAS unsigned char* lds, const Gemm g, const Sched& S, const Epi& E) {
;     ...
;             PG8_WAIT_V(8); PG8_WAIT_L(0); PG8_BAR; PG8_MMA(0, 0, At, B0); PG8_MMA(0, 1, At, B1); PG8_BAR; PG8_SCHED;
;             PG8_LDA(At, 0, 1); PG8_STAGE(PG8_SB(0, 0), b2, voffB); PG8_STAGE(PG8_SB(0, 1), b2 + hB, voffB); PG8_STAGE(PG8_SA(0, 0), a2, voffA);
;             PG8_WAIT_V(8); PG8_WAIT_L(0); PG8_BAR; PG8_MMA(1, 0, At, B0); PG8_MMA(1, 1, At, B1); PG8_BAR; PG8_SCHED;
	s_setprio 1
	s_waitcnt lgkmcnt(0)
	v_mfma_f32_16x16x32_bf16 v[36:39], v[136:139], v[212:215], v[36:39]
	v_mfma_f32_16x16x32_bf16 v[36:39], v[140:143], v[216:219], v[36:39]
	v_mfma_f32_16x16x32_bf16 v[40:43], v[144:147], v[212:215], v[40:43]
	v_mfma_f32_16x16x32_bf16 v[40:43], v[170:173], v[216:219], v[40:43]
	v_mfma_f32_16x16x32_bf16 v[68:71], v[136:139], v[220:223], v[68:71]
	v_mfma_f32_16x16x32_bf16 v[68:71], v[140:143], v[224:227], v[68:71]
	v_mfma_f32_16x16x32_bf16 v[72:75], v[144:147], v[220:223], v[72:75]
	v_mfma_f32_16x16x32_bf16 v[72:75], v[170:173], v[224:227], v[72:75]
	v_mfma_f32_16x16x32_bf16 v[100:103], v[136:139], v[228:231], v[100:103]
	v_mfma_f32_16x16x32_bf16 v[100:103], v[140:143], v[232:235], v[100:103]
	v_mfma_f32_16x16x32_bf16 v[104:107], v[144:147], v[228:231], v[104:107]
	v_mfma_f32_16x16x32_bf16 v[104:107], v[170:173], v[232:235], v[104:107]
	v_mfma_f32_16x16x32_bf16 v[128:131], v[136:139], v[236:239], v[128:131]
	v_mfma_f32_16x16x32_bf16 v[128:131], v[140:143], v[240:243], v[128:131]
	v_mfma_f32_16x16x32_bf16 v[124:127], v[144:147], v[236:239], v[124:127]
	v_mfma_f32_16x16x32_bf16 v[124:127], v[170:173], v[240:243], v[124:127]
	v_mfma_f32_16x16x32_bf16 v[8:11], v[174:177], v[212:215], v[8:11]
	v_mfma_f32_16x16x32_bf16 v[8:11], v[178:181], v[216:219], v[8:11]
	v_mfma_f32_16x16x32_bf16 v[4:7], v[182:185], v[212:215], v[4:7]
	v_mfma_f32_16x16x32_bf16 v[4:7], v[208:211], v[216:219], v[4:7]
	v_mfma_f32_16x16x32_bf16 v[32:35], v[174:177], v[220:223], v[32:35]
	v_mfma_f32_16x16x32_bf16 v[32:35], v[178:181], v[224:227], v[32:35]
	v_mfma_f32_16x16x32_bf16 v[28:31], v[182:185], v[220:223], v[28:31]
	v_mfma_f32_16x16x32_bf16 v[28:31], v[208:211], v[224:227], v[28:31]
	v_mfma_f32_16x16x32_bf16 v[56:59], v[174:177], v[228:231], v[56:59]
	v_mfma_f32_16x16x32_bf16 v[56:59], v[178:181], v[232:235], v[56:59]
	v_mfma_f32_16x16x32_bf16 v[52:55], v[182:185], v[228:231], v[52:55]
	v_mfma_f32_16x16x32_bf16 v[52:55], v[208:211], v[232:235], v[52:55]
	v_mfma_f32_16x16x32_bf16 v[80:83], v[174:177], v[236:239], v[80:83]
	v_mfma_f32_16x16x32_bf16 v[80:83], v[178:181], v[240:243], v[80:83]
	s_setprio 3
	s_barrier
	v_mfma_f32_16x16x32_bf16 v[76:79], v[182:185], v[236:239], v[76:79]
	v_mfma_f32_16x16x32_bf16 v[76:79], v[208:211], v[240:243], v[76:79]
	s_setprio 0
	s_add_i32 s10, s27, s67
	v_lshl_add_u64 v[244:245], s[62:63], 0, v[2:3]
	s_mov_b32 m0, s10
	ds_read_b128 v[212:215], v197 offset:16384
	ds_read_b128 v[216:219], v197 offset:17408
	ds_read_b128 v[220:223], v197 offset:18432
	ds_read_b128 v[224:227], v197 offset:19456
	ds_read_b128 v[228:231], v197 offset:20480
	ds_read_b128 v[232:235], v197 offset:21504
	ds_read_b128 v[236:239], v197 offset:22528
	ds_read_b128 v[240:243], v197 offset:23552
	global_load_lds_dwordx4 v[244:245], off
	s_add_i32 m0, s10, 0x2000
	s_add_u32 s10, s62, 0x80000
	v_lshl_add_u64 v[246:247], s[62:63], 0, v[150:151]
	s_addc_u32 s11, s63, 0
	s_add_i32 s25, s25, s67
	global_load_lds_dwordx4 v[246:247], off
	v_lshl_add_u64 v[248:249], s[10:11], 0, v[2:3]
	s_mov_b32 m0, s25
	v_lshl_add_u64 v[160:161], s[64:65], 0, v[148:149]
	global_load_lds_dwordx4 v[248:249], off
	v_lshl_add_u64 v[248:249], s[10:11], 0, v[150:151]
	s_add_i32 m0, s25, 0x2000
	s_nop 0
	global_load_lds_dwordx4 v[248:249], off
	v_lshl_add_u64 v[248:249], s[64:65], 0, v[0:1]
	s_mov_b32 m0, s53
	s_nop 0
	global_load_lds_dwordx4 v[248:249], off
	s_mov_b32 m0, s66
	s_nop 0
	global_load_lds_dwordx4 v[160:161], off
	s_waitcnt vmcnt(8)
	s_waitcnt lgkmcnt(0)
	s_barrier
	s_setprio 1
	s_waitcnt lgkmcnt(0)
	v_mfma_f32_16x16x32_bf16 v[120:123], v[136:139], v[212:215], v[120:123]
	v_mfma_f32_16x16x32_bf16 v[120:123], v[140:143], v[216:219], v[120:123]
	v_mfma_f32_16x16x32_bf16 v[116:119], v[144:147], v[212:215], v[116:119]
	v_mfma_f32_16x16x32_bf16 v[116:119], v[170:173], v[216:219], v[116:119]
	v_mfma_f32_16x16x32_bf16 v[96:99], v[136:139], v[220:223], v[96:99]
	v_mfma_f32_16x16x32_bf16 v[96:99], v[140:143], v[224:227], v[96:99]
	v_mfma_f32_16x16x32_bf16 v[92:95], v[144:147], v[220:223], v[92:95]
	v_mfma_f32_16x16x32_bf16 v[92:95], v[170:173], v[224:227], v[92:95]
	v_mfma_f32_16x16x32_bf16 v[64:67], v[136:139], v[228:231], v[64:67]
	v_mfma_f32_16x16x32_bf16 v[64:67], v[140:143], v[232:235], v[64:67]
	v_mfma_f32_16x16x32_bf16 v[60:63], v[144:147], v[228:231], v[60:63]
	v_mfma_f32_16x16x32_bf16 v[60:63], v[170:173], v[232:235], v[60:63]
	v_mfma_f32_16x16x32_bf16 v[24:27], v[136:139], v[236:239], v[24:27]
	v_mfma_f32_16x16x32_bf16 v[24:27], v[140:143], v[240:243], v[24:27]
	v_mfma_f32_16x16x32_bf16 v[20:23], v[144:147], v[236:239], v[20:23]
	v_mfma_f32_16x16x32_bf16 v[20:23], v[170:173], v[240:243], v[20:23]
	v_mfma_f32_16x16x32_bf16 v[112:115], v[174:177], v[212:215], v[112:115]
	v_mfma_f32_16x16x32_bf16 v[112:115], v[178:181], v[216:219], v[112:115]
	v_mfma_f32_16x16x32_bf16 v[108:111], v[182:185], v[212:215], v[108:111]
	v_mfma_f32_16x16x32_bf16 v[108:111], v[208:211], v[216:219], v[108:111]
	v_mfma_f32_16x16x32_bf16 v[88:91], v[174:177], v[220:223], v[88:91]
	v_mfma_f32_16x16x32_bf16 v[88:91], v[178:181], v[224:227], v[88:91]
	v_mfma_f32_16x16x32_bf16 v[84:87], v[182:185], v[220:223], v[84:87]
	v_mfma_f32_16x16x32_bf16 v[84:87], v[208:211], v[224:227], v[84:87]
	v_mfma_f32_16x16x32_bf16 v[48:51], v[174:177], v[228:231], v[48:51]
	v_mfma_f32_16x16x32_bf16 v[48:51], v[178:181], v[232:235], v[48:51]
	v_mfma_f32_16x16x32_bf16 v[44:47], v[182:185], v[228:231], v[44:47]
	v_mfma_f32_16x16x32_bf16 v[44:47], v[208:211], v[232:235], v[44:47]
	v_mfma_f32_16x16x32_bf16 v[16:19], v[174:177], v[236:239], v[16:19]
	v_mfma_f32_16x16x32_bf16 v[16:19], v[178:181], v[240:243], v[16:19]
	s_setprio 3
	s_barrier
; #define PG8_STAGE(bufoff, gbase, voff) do { _Pragma("unroll") for (int _i = 0; _i < 2; ++_i) \
;         __builtin_amdgcn_global_load_lds((const unsigned*)((const char*)(gbase) + (voff)[_i]), (LAS unsigned*)(lds + (bufoff) + ldsw + _i * 8192), 16, 0, 0); } while (0)
; #define PG8_LDA(dst, b, h) do { _Pragma("unroll") for (int m = 0; m < 4; ++m) _Pragma("unroll") for (int k = 0; k < 2; ++k) dst[m][k] = *(const LAS bf16x8*)(lds + PG8_SA(b, h) + aoff + m * 2048 + k * 1024); } while (0)
; #define PG8_LDB(dst, b, h) do { _Pragma("unroll") for (int n = 0; n < 2; ++n) _Pragma("unroll") for (int k = 0; k < 2; ++k) dst[n][k] = *(const LAS bf16x8*)(lds + PG8_SB(b, h) + boff + n * 2048 + k * 1024); } while (0)
; #define PG8_MMA(ai, bj, At, Bt) do { __builtin_amdgcn_s_setprio(1); _Pragma("unroll") for (int m = 0; m < 4; ++m) _Pragma("unroll") for (int n = 0; n < 2; ++n) _Pragma("unroll") for (int k = 0; k < 2; ++k) \
;         acc[ai][bj][m][n] = __builtin_amdgcn_mfma_f32_16x16x32_bf16(Bt[n][k], At[m][k], acc[ai][bj][m][n], 0, 0, 0); __builtin_amdgcn_s_setprio(0); } while (0)
; #define PG8_WAIT_V(n) asm volatile("s_waitcnt vmcnt(" #n ")" ::: "memory")
; #define PG8_WAIT_L(n) asm volatile("s_waitcnt lgkmcnt(" #n ")" ::: "memory")
; #define PG8_BAR __builtin_amdgcn_s_barrier()
; #define PG8_SCHED __builtin_amdgcn_sched_barrier(0)
; template <class Epi, class Sched, bool ALIGN_EPI = true>
; __device__ __forceinline__ void gemm_phase(LAS unsigned char* lds, const Gemm g, const Sched& S, const Epi& E) {
;     ...
;             PG8_WAIT_V(8); PG8_WAIT_L(0); PG8_BAR; PG8_MMA(1, 0, At, B0); PG8_MMA(1, 1, At, B1); PG8_BAR; PG8_SCHED;
;             PG8_LDB(B0, 1, 0); PG8_LDB(B1, 1, 1); PG8_SCHED; PG8_LDA(At, 1, 0); PG8_STAGE(PG8_SA(0, 1), a2 + hA, voffA);
;             PG8_WAIT_V(8); PG8_WAIT_L(0); PG8_BAR; PG8_MMA(0, 0, At, B0); PG8_MMA(0, 1, At, B1); PG8_BAR; PG8_SCHED;
	v_mfma_f32_16x16x32_bf16 v[12:15], v[182:185], v[236:239], v[12:15]
	v_mfma_f32_16x16x32_bf16 v[12:15], v[208:211], v[240:243], v[12:15]
	s_setprio 0
	s_add_i32 s25, 0, 0x18000
	v_add_u32_e32 v162, s25, v186
	s_add_i32 s26, 0, 0x1c000
	ds_read_b128 v[136:139], v162
	ds_read_b128 v[140:143], v162 offset:1024
	ds_read_b128 v[144:147], v162 offset:2048
	ds_read_b128 v[170:173], v162 offset:3072
	v_add_u32_e32 v162, s26, v186
	ds_read_b128 v[174:177], v162
	ds_read_b128 v[178:181], v162 offset:1024
	ds_read_b128 v[182:185], v162 offset:2048
	ds_read_b128 v[208:211], v162 offset:3072
	s_add_u32 s10, s64, 0x80000
	s_addc_u32 s11, s65, 0
	s_mov_b32 m0, s75
	v_lshl_add_u64 v[162:163], s[10:11], 0, v[0:1]
	ds_read_b128 v[212:215], v197 offset:32768
	ds_read_b128 v[216:219], v197 offset:33792
	ds_read_b128 v[220:223], v197 offset:34816
	ds_read_b128 v[224:227], v197 offset:35840
	ds_read_b128 v[228:231], v197 offset:36864
	ds_read_b128 v[232:235], v197 offset:37888
	ds_read_b128 v[236:239], v197 offset:38912
	ds_read_b128 v[240:243], v197 offset:39936
	global_load_lds_dwordx4 v[162:163], off
	v_lshl_add_u64 v[162:163], s[10:11], 0, v[148:149]
	s_mov_b32 m0, s76
	s_nop 0
	global_load_lds_dwordx4 v[162:163], off
	s_waitcnt vmcnt(8)
	s_waitcnt lgkmcnt(0)
	s_barrier
	s_setprio 1
	s_waitcnt lgkmcnt(0)
	v_mfma_f32_16x16x32_bf16 v[36:39], v[136:139], v[212:215], v[36:39]
	v_mfma_f32_16x16x32_bf16 v[36:39], v[140:143], v[216:219], v[36:39]
	v_mfma_f32_16x16x32_bf16 v[40:43], v[144:147], v[212:215], v[40:43]
	v_mfma_f32_16x16x32_bf16 v[40:43], v[170:173], v[216:219], v[40:43]
	v_mfma_f32_16x16x32_bf16 v[68:71], v[136:139], v[220:223], v[68:71]
	v_mfma_f32_16x16x32_bf16 v[68:71], v[140:143], v[224:227], v[68:71]
	v_mfma_f32_16x16x32_bf16 v[72:75], v[144:147], v[220:223], v[72:75]
	v_mfma_f32_16x16x32_bf16 v[72:75], v[170:173], v[224:227], v[72:75]
	v_mfma_f32_16x16x32_bf16 v[100:103], v[136:139], v[228:231], v[100:103]
	v_mfma_f32_16x16x32_bf16 v[100:103], v[140:143], v[232:235], v[100:103]
	v_mfma_f32_16x16x32_bf16 v[104:107], v[144:147], v[228:231], v[104:107]
	v_mfma_f32_16x16x32_bf16 v[104:107], v[170:173], v[232:235], v[104:107]
	v_mfma_f32_16x16x32_bf16 v[128:131], v[136:139], v[236:239], v[128:131]
	v_mfma_f32_16x16x32_bf16 v[128:131], v[140:143], v[240:243], v[128:131]
	v_mfma_f32_16x16x32_bf16 v[124:127], v[144:147], v[236:239], v[124:127]
	v_mfma_f32_16x16x32_bf16 v[124:127], v[170:173], v[240:243], v[124:127]
	v_mfma_f32_16x16x32_bf16 v[8:11], v[174:177], v[212:215], v[8:11]
	v_mfma_f32_16x16x32_bf16 v[8:11], v[178:181], v[216:219], v[8:11]
	v_mfma_f32_16x16x32_bf16 v[4:7], v[182:185], v[212:215], v[4:7]
	v_mfma_f32_16x16x32_bf16 v[4:7], v[208:211], v[216:219], v[4:7]
	v_mfma_f32_16x16x32_bf16 v[32:35], v[174:177], v[220:223], v[32:35]
	v_mfma_f32_16x16x32_bf16 v[32:35], v[178:181], v[224:227], v[32:35]
	v_mfma_f32_16x16x32_bf16 v[28:31], v[182:185], v[220:223], v[28:31]
	v_mfma_f32_16x16x32_bf16 v[28:31], v[208:211], v[224:227], v[28:31]
	v_mfma_f32_16x16x32_bf16 v[56:59], v[174:177], v[228:231], v[56:59]
	v_mfma_f32_16x16x32_bf16 v[56:59], v[178:181], v[232:235], v[56:59]
	v_mfma_f32_16x16x32_bf16 v[52:55], v[182:185], v[228:231], v[52:55]
	v_mfma_f32_16x16x32_bf16 v[52:55], v[208:211], v[232:235], v[52:55]
	v_mfma_f32_16x16x32_bf16 v[80:83], v[174:177], v[236:239], v[80:83]
	v_mfma_f32_16x16x32_bf16 v[80:83], v[178:181], v[240:243], v[80:83]
	s_setprio 3
	s_barrier
; #define PG8_STAGE(bufoff, gbase, voff) do { _Pragma("unroll") for (int _i = 0; _i < 2; ++_i) \
;         __builtin_amdgcn_global_load_lds((const unsigned*)((const char*)(gbase) + (voff)[_i]), (LAS unsigned*)(lds + (bufoff) + ldsw + _i * 8192), 16, 0, 0); } while (0)
; #define PG8_LDA(dst, b, h) do { _Pragma("unroll") for (int m = 0; m < 4; ++m) _Pragma("unroll") for (int k = 0; k < 2; ++k) dst[m][k] = *(const LAS bf16x8*)(lds + PG8_SA(b, h) + aoff + m * 2048 + k * 1024); } while (0)
; #define PG8_LDB(dst, b, h) do { _Pragma("unroll") for (int n = 0; n < 2; ++n) _Pragma("unroll") for (int k = 0; k < 2; ++k) dst[n][k] = *(const LAS bf16x8*)(lds + PG8_SB(b, h) + boff + n * 2048 + k * 1024); } while (0)
; #define PG8_WAIT_V(n) asm volatile("s_waitcnt vmcnt(" #n ")" ::: "memory")
; #define PG8_WAIT_L(n) asm volatile("s_waitcnt lgkmcnt(" #n ")" ::: "memory")
; template <class Epi, class Sched, bool ALIGN_EPI = true>
; __device__ __forceinline__ void gemm_phase(LAS unsigned char* lds, const Gemm g, const Sched& S, const Epi& E) {
;     ...
;             const bool last = (t == nt - 2);
;             const char* a1 = cA + (size_t)(t + 1) * kstep;
;             const char* a2 = last ? nA : cA + (size_t)(t + 2) * kstep; const char* b2 = last ? nB : cB + (size_t)(t + 2) * kstep;
;             const char* a3 = a2 + kstep; const char* b3 = b2 + kstep;
;             PG8_LDB(B0, 0, 0); PG8_LDB(B1, 0, 1); PG8_SCHED; PG8_LDA(At, 0, 0); PG8_STAGE(PG8_SA(1, 1), a1 + hA, voffA);
;             PG8_WAIT_V(8); PG8_WAIT_L(0); PG8_BAR; PG8_MMA(0, 0, At, B0); PG8_MMA(0, 1, At, B1); PG8_BAR; PG8_SCHED;
;             PG8_LDA(At, 0, 1); PG8_STAGE(PG8_SB(0, 0), b2, voffB); PG8_STAGE(PG8_SB(0, 1), b2 + hB, voffB); PG8_STAGE(PG8_SA(0, 0), a2, voffA);
;             PG8_WAIT_V(8); PG8_WAIT_L(0); PG8_BAR; PG8_MMA(1, 0, At, B0); PG8_MMA(1, 1, At, B1); PG8_BAR; PG8_SCHED;
;             PG8_LDB(B0, 1, 0); PG8_LDB(B1, 1, 1); PG8_SCHED; PG8_LDA(At, 1, 0); PG8_STAGE(PG8_SA(0, 1), a2 + hA, voffA);
;             PG8_WAIT_V(8); PG8_WAIT_L(0); PG8_BAR; PG8_MMA(0, 0, At, B0); PG8_MMA(0, 1, At, B1); PG8_BAR; PG8_SCHED;
;             PG8_LDA(At, 1, 1); PG8_STAGE(PG8_SB(1, 0), b3, voffB); PG8_STAGE(PG8_SB(1, 1), b3 + hB, voffB); PG8_STAGE(PG8_SA(1, 0), a3, voffA);
;             PG8_WAIT_V(8); PG8_WAIT_L(0); PG8_BAR; PG8_MMA(1, 0, At, B0); PG8_MMA(1, 1, At, B1); PG8_BAR; PG8_SCHED;
	v_mfma_f32_16x16x32_bf16 v[76:79], v[182:185], v[236:239], v[76:79]
	v_mfma_f32_16x16x32_bf16 v[76:79], v[208:211], v[240:243], v[76:79]
	s_setprio 0
	s_add_i32 s10, s25, s67
	v_lshl_add_u64 v[162:163], v[244:245], 0, s[86:87]
	s_mov_b32 m0, s10
	ds_read_b128 v[212:215], v197 offset:49152
	ds_read_b128 v[216:219], v197 offset:50176
	ds_read_b128 v[220:223], v197 offset:51200
	ds_read_b128 v[224:227], v197 offset:52224
	ds_read_b128 v[228:231], v197 offset:53248
	ds_read_b128 v[232:235], v197 offset:54272
	ds_read_b128 v[236:239], v197 offset:55296
	ds_read_b128 v[240:243], v197 offset:56320
	global_load_lds_dwordx4 v[162:163], off
	s_add_i32 m0, s10, 0x2000
	s_add_u32 s10, s62, 0x80080
	v_lshl_add_u64 v[162:163], v[246:247], 0, s[86:87]
	s_addc_u32 s11, s63, 0
	s_add_i32 s25, s26, s67
	global_load_lds_dwordx4 v[162:163], off
	v_lshl_add_u64 v[162:163], s[10:11], 0, v[2:3]
	s_mov_b32 m0, s25
	v_lshl_add_u64 v[160:161], v[160:161], 0, s[86:87]
	global_load_lds_dwordx4 v[162:163], off
	v_lshl_add_u64 v[162:163], s[10:11], 0, v[150:151]
	s_add_i32 m0, s25, 0x2000
	s_nop 0
	global_load_lds_dwordx4 v[162:163], off
	v_lshl_add_u64 v[162:163], v[248:249], 0, s[86:87]
	s_mov_b32 m0, s79
	s_nop 0
	global_load_lds_dwordx4 v[162:163], off
	s_mov_b32 m0, s80
	s_nop 0
	global_load_lds_dwordx4 v[160:161], off
	s_waitcnt vmcnt(8)
	s_waitcnt lgkmcnt(0)
	s_barrier
	s_setprio 1
	s_waitcnt lgkmcnt(0)
	v_mfma_f32_16x16x32_bf16 v[120:123], v[136:139], v[212:215], v[120:123]
	v_mfma_f32_16x16x32_bf16 v[120:123], v[140:143], v[216:219], v[120:123]
	v_mfma_f32_16x16x32_bf16 v[116:119], v[144:147], v[212:215], v[116:119]
	v_mfma_f32_16x16x32_bf16 v[116:119], v[170:173], v[216:219], v[116:119]
	v_mfma_f32_16x16x32_bf16 v[96:99], v[136:139], v[220:223], v[96:99]
	v_mfma_f32_16x16x32_bf16 v[96:99], v[140:143], v[224:227], v[96:99]
	v_mfma_f32_16x16x32_bf16 v[92:95], v[144:147], v[220:223], v[92:95]
	v_mfma_f32_16x16x32_bf16 v[92:95], v[170:173], v[224:227], v[92:95]
	v_mfma_f32_16x16x32_bf16 v[64:67], v[136:139], v[228:231], v[64:67]
	v_mfma_f32_16x16x32_bf16 v[64:67], v[140:143], v[232:235], v[64:67]
	v_mfma_f32_16x16x32_bf16 v[60:63], v[144:147], v[228:231], v[60:63]
	v_mfma_f32_16x16x32_bf16 v[60:63], v[170:173], v[232:235], v[60:63]
	v_mfma_f32_16x16x32_bf16 v[24:27], v[136:139], v[236:239], v[24:27]
	v_mfma_f32_16x16x32_bf16 v[24:27], v[140:143], v[240:243], v[24:27]
	v_mfma_f32_16x16x32_bf16 v[20:23], v[144:147], v[236:239], v[20:23]
	v_mfma_f32_16x16x32_bf16 v[20:23], v[170:173], v[240:243], v[20:23]
	v_mfma_f32_16x16x32_bf16 v[112:115], v[174:177], v[212:215], v[112:115]
	v_mfma_f32_16x16x32_bf16 v[112:115], v[178:181], v[216:219], v[112:115]
	v_mfma_f32_16x16x32_bf16 v[108:111], v[182:185], v[212:215], v[108:111]
	v_mfma_f32_16x16x32_bf16 v[108:111], v[208:211], v[216:219], v[108:111]
	v_mfma_f32_16x16x32_bf16 v[88:91], v[174:177], v[220:223], v[88:91]
	v_mfma_f32_16x16x32_bf16 v[88:91], v[178:181], v[224:227], v[88:91]
	v_mfma_f32_16x16x32_bf16 v[84:87], v[182:185], v[220:223], v[84:87]
	v_mfma_f32_16x16x32_bf16 v[84:87], v[208:211], v[224:227], v[84:87]
	v_mfma_f32_16x16x32_bf16 v[48:51], v[174:177], v[228:231], v[48:51]
	v_mfma_f32_16x16x32_bf16 v[48:51], v[178:181], v[232:235], v[48:51]
	v_mfma_f32_16x16x32_bf16 v[44:47], v[182:185], v[228:231], v[44:47]
	v_mfma_f32_16x16x32_bf16 v[44:47], v[208:211], v[232:235], v[44:47]
	v_mfma_f32_16x16x32_bf16 v[16:19], v[174:177], v[236:239], v[16:19]
	v_mfma_f32_16x16x32_bf16 v[16:19], v[178:181], v[240:243], v[16:19]
	s_setprio 3
	s_barrier
	v_mfma_f32_16x16x32_bf16 v[12:15], v[182:185], v[236:239], v[12:15]
	v_mfma_f32_16x16x32_bf16 v[12:15], v[208:211], v[240:243], v[12:15]
	s_setprio 0
	s_add_i32 s24, s24, 2
	s_cmp_gt_u32 s24, 29
	s_mov_b64 s[10:11], vcc
	s_cbranch_scc0 .LBB0_667

;     __device__ bool next(int i, Unit& u) const { if (i >= 2) return false; const int x = c & 7, j = c >> 3; u.pm = 32 * i + 4 * x + (j & 3); u.pn = j >> 2; return true; }
; #define PG8_STAGE(bufoff, gbase, voff) do { _Pragma("unroll") for (int _i = 0; _i < 2; ++_i) \
;         __builtin_amdgcn_global_load_lds((const unsigned*)((const char*)(gbase) + (voff)[_i]), (LAS unsigned*)(lds + (bufoff) + ldsw + _i * 8192), 16, 0, 0); } while (0)
; #define PG8_LDA(dst, b, h) do { _Pragma("unroll") for (int m = 0; m < 4; ++m) _Pragma("unroll") for (int k = 0; k < 2; ++k) dst[m][k] = *(const LAS bf16x8*)(lds + PG8_SA(b, h) + aoff + m * 2048 + k * 1024); } while (0)
; #define PG8_WAIT_V(n) asm volatile("s_waitcnt vmcnt(" #n ")" ::: "memory")
;     __device__ __forceinline__ void operator()(f32x4 (&acc)[2][2][4][2], const Unit& u, int wr, int wc, int fr_, int fq_, int wid, int lane_) const {
;     ...
;             const int t = wid * 64 + lane, kind = t >> 6, pr = t & 63, bj = kind >> 2, tap = kind & 3;
;             const float* src = (tap < 3) ? (cw + (size_t)tap * FF2 + bj * FF + u.pn * 128 + 2 * pr) : (cb + bj * FF + u.pn * 128 + 2 * pr);
;             const f32x2 wv = *(const f32x2*)src;
; template <class Epi, class Sched, bool ALIGN_EPI = true>
; __device__ __forceinline__ void gemm_phase(LAS unsigned char* lds, const Gemm g, const Sched& S, const Epi& E) {
;     ...
;         const bool has_next = S.next(ui + 1, nxt);
;         const char* nA = has_next ? (const char*)g.A + ((size_t)nxt.pm * BM * g.lda + (size_t)nxt.pn * g.a_pn_off) * 2 : cA; const char* nB = has_next ? (const char*)g.Bt + (size_t)nxt.pn * BM * g.ldb * 2 : cB;
;         for (int t = 0; t < nt; t += 2) {
;             const bool last = (t == nt - 2);
;             const char* a1 = cA + (size_t)(t + 1) * kstep;
;             const char* a2 = last ? nA : cA + (size_t)(t + 2) * kstep; const char* b2 = last ? nB : cB + (size_t)(t + 2) * kstep;
;             const char* a3 = a2 + kstep; const char* b3 = b2 + kstep;
;             PG8_LDB(B0, 0, 0); PG8_LDB(B1, 0, 1); PG8_SCHED; PG8_LDA(At, 0, 0); PG8_STAGE(PG8_SA(1, 1), a1 + hA, voffA);
;             PG8_WAIT_V(8); PG8_WAIT_L(0); PG8_BAR; PG8_MMA(0, 0, At, B0); PG8_MMA(0, 1, At, B1); PG8_BAR; PG8_SCHED;
;             PG8_LDA(At, 0, 1); PG8_STAGE(PG8_SB(0, 0), b2, voffB); PG8_STAGE(PG8_SB(0, 1), b2 + hB, voffB); PG8_STAGE(PG8_SA(0, 0), a2, voffA);
.LBB0_827:
	s_ashr_i32 s39, s38, 31
	s_lshl_b64 s[16:17], s[38:39], 20
	s_add_u32 s40, s46, s16
	s_addc_u32 s41, s47, s17
	s_and_b64 s[16:17], s[4:5], exec
	s_cselect_b32 s16, s41, s7
	s_cselect_b32 s17, s40, s6
	s_ashr_i32 s15, s14, 31
	s_lshl_b64 s[18:19], s[14:15], 20
	s_add_u32 s42, s53, s18
	s_addc_u32 s43, s60, s19
	s_and_b64 s[18:19], s[4:5], exec
	s_cselect_b32 s15, s43, s45
	s_cselect_b32 s18, s42, s44
	s_add_u32 s6, s6, 0x80080
	s_addc_u32 s7, s7, 0
	s_add_u32 s19, s44, 0x100
	s_addc_u32 s24, s45, 0
	s_mov_b32 s25, -2
	v_add_u32_e32 v228, s77, v158
	v_ashrrev_i32_e32 v229, 6, v228
	v_and_b32_e32 v230, 3, v229
	v_lshrrev_b32_e32 v231, 8, v228
	v_mul_u32_u24_e32 v228, 0x2c00, v230
	v_lshlrev_b32_e32 v228, 2, v228
	v_mov_b32_e32 v229, 0
	v_lshl_add_u64 v[232:233], s[2:3], 0, v[228:229]
	v_mov_b32_e32 v228, s9
	v_cmp_eq_u32_e32 vcc, 3, v230
	v_mul_i32_i24_e32 v234, 0x1600, v231
	v_ashrrev_i32_e32 v235, 31, v234
	v_cndmask_b32_e32 v233, v233, v228, vcc
	v_mov_b32_e32 v228, s8
	v_cndmask_b32_e32 v232, v232, v228, vcc
	v_lshl_add_u64 v[232:233], v[234:235], 2, v[232:233]
	s_lshl_b32 s26, s82, 7
	s_ashr_i32 s27, s26, 31
	v_lshl_add_u64 v[232:233], s[26:27], 2, v[232:233]
	v_and_b32_e32 v228, 63, v158
	v_lshlrev_b32_e32 v228, 3, v228
	v_mov_b32_e32 v229, 0
	v_lshl_add_u64 v[232:233], v[232:233], 0, v[228:229]
	global_load_dwordx2 v[226:227], v[232:233], off
	s_add_u32 s26, s6, 0xfff80080
	s_addc_u32 s27, s7, -1
	s_add_i32 s30, 0, 0x10000
	s_cmp_eq_u32 s25, 28
	s_cselect_b32 s59, s16, s27
	s_cselect_b32 s58, s17, s26
	v_add_u32_e32 v2, s30, v204
	s_cselect_b32 s45, s15, s24
	s_cselect_b32 s44, s18, s19
	s_add_i32 s31, 0, 0x14000
	ds_read_b128 v[132:135], v2
	ds_read_b128 v[136:139], v2 offset:1024
	ds_read_b128 v[140:143], v2 offset:2048
	ds_read_b128 v[144:147], v2 offset:3072
	v_add_u32_e32 v2, s31, v204
	ds_read_b128 v[148:151], v2
	ds_read_b128 v[152:155], v2 offset:1024
	ds_read_b128 v[174:177], v2 offset:2048
	ds_read_b128 v[178:181], v2 offset:3072
	v_lshl_add_u64 v[156:157], s[6:7], 0, v[170:171]
	s_add_i32 m0, s62, 0xc000
	ds_read_b128 v[182:185], v205
	ds_read_b128 v[186:189], v205 offset:1024
	ds_read_b128 v[190:193], v205 offset:2048
	ds_read_b128 v[194:197], v205 offset:3072
	ds_read_b128 v[206:209], v205 offset:4096
	ds_read_b128 v[210:213], v205 offset:5120
	ds_read_b128 v[214:217], v205 offset:6144
	ds_read_b128 v[218:221], v205 offset:7168
	global_load_lds_dwordx4 v[156:157], off
	v_lshl_add_u64 v[156:157], s[6:7], 0, v[172:173]
	s_add_i32 m0, s62, 0xe000
	s_nop 0
	global_load_lds_dwordx4 v[156:157], off
	s_waitcnt vmcnt(8)
	s_waitcnt lgkmcnt(0)
	s_barrier
	s_setprio 1
	s_waitcnt lgkmcnt(0)
	v_mfma_f32_16x16x32_bf16 v[116:119], v[132:135], v[182:185], 0
	v_mfma_f32_16x16x32_bf16 v[116:119], v[136:139], v[186:189], v[116:119]
	v_mfma_f32_16x16x32_bf16 v[100:103], v[140:143], v[182:185], 0
	v_mfma_f32_16x16x32_bf16 v[100:103], v[144:147], v[186:189], v[100:103]
	v_mfma_f32_16x16x32_bf16 v[108:111], v[132:135], v[190:193], 0
	v_mfma_f32_16x16x32_bf16 v[108:111], v[136:139], v[194:197], v[108:111]
	v_mfma_f32_16x16x32_bf16 v[96:99], v[140:143], v[190:193], 0
	v_mfma_f32_16x16x32_bf16 v[96:99], v[144:147], v[194:197], v[96:99]
	v_mfma_f32_16x16x32_bf16 v[88:91], v[132:135], v[206:209], 0
	v_mfma_f32_16x16x32_bf16 v[88:91], v[136:139], v[210:213], v[88:91]
	v_mfma_f32_16x16x32_bf16 v[84:87], v[140:143], v[206:209], 0
	v_mfma_f32_16x16x32_bf16 v[84:87], v[144:147], v[210:213], v[84:87]
	v_mfma_f32_16x16x32_bf16 v[72:75], v[132:135], v[214:217], 0
	v_mfma_f32_16x16x32_bf16 v[72:75], v[136:139], v[218:221], v[72:75]
	v_mfma_f32_16x16x32_bf16 v[80:83], v[140:143], v[214:217], 0
	v_mfma_f32_16x16x32_bf16 v[80:83], v[144:147], v[218:221], v[80:83]
	v_mfma_f32_16x16x32_bf16 v[128:131], v[148:151], v[182:185], 0
	v_mfma_f32_16x16x32_bf16 v[128:131], v[152:155], v[186:189], v[128:131]
	v_mfma_f32_16x16x32_bf16 v[44:47], v[174:177], v[182:185], 0
	v_mfma_f32_16x16x32_bf16 v[44:47], v[178:181], v[186:189], v[44:47]
	v_mfma_f32_16x16x32_bf16 v[124:127], v[148:151], v[190:193], 0
	v_mfma_f32_16x16x32_bf16 v[124:127], v[152:155], v[194:197], v[124:127]
	v_mfma_f32_16x16x32_bf16 v[36:39], v[174:177], v[190:193], 0
	v_mfma_f32_16x16x32_bf16 v[36:39], v[178:181], v[194:197], v[36:39]
	v_mfma_f32_16x16x32_bf16 v[120:123], v[148:151], v[206:209], 0
	v_mfma_f32_16x16x32_bf16 v[120:123], v[152:155], v[210:213], v[120:123]
	v_mfma_f32_16x16x32_bf16 v[32:35], v[174:177], v[206:209], 0
	v_mfma_f32_16x16x32_bf16 v[32:35], v[178:181], v[210:213], v[32:35]
	v_mfma_f32_16x16x32_bf16 v[112:115], v[148:151], v[214:217], 0
	v_mfma_f32_16x16x32_bf16 v[112:115], v[152:155], v[218:221], v[112:115]
	s_setprio 3
	s_barrier
	v_mfma_f32_16x16x32_bf16 v[28:31], v[174:177], v[214:217], 0
	v_mfma_f32_16x16x32_bf16 v[28:31], v[178:181], v[218:221], v[28:31]
	s_setprio 0
	s_add_i32 s26, s30, s61
	v_lshl_add_u64 v[156:157], s[44:45], 0, v[166:167]
	s_mov_b32 m0, s26
	ds_read_b128 v[182:185], v205 offset:16384
	ds_read_b128 v[186:189], v205 offset:17408
	ds_read_b128 v[190:193], v205 offset:18432
	ds_read_b128 v[194:197], v205 offset:19456
	ds_read_b128 v[206:209], v205 offset:20480
	ds_read_b128 v[210:213], v205 offset:21504
	ds_read_b128 v[214:217], v205 offset:22528
	ds_read_b128 v[218:221], v205 offset:23552
	global_load_lds_dwordx4 v[156:157], off
	s_add_i32 m0, s26, 0x2000
	s_add_u32 s26, s44, 0x80000
	v_lshl_add_u64 v[160:161], s[44:45], 0, v[0:1]
	s_addc_u32 s27, s45, 0
	s_add_i32 s30, s31, s61
	global_load_lds_dwordx4 v[160:161], off
	v_lshl_add_u64 v[162:163], s[26:27], 0, v[166:167]
	s_mov_b32 m0, s30
	v_lshl_add_u64 v[222:223], s[58:59], 0, v[164:165]
	global_load_lds_dwordx4 v[162:163], off
	v_lshl_add_u64 v[162:163], s[26:27], 0, v[0:1]
	s_add_i32 m0, s30, 0x2000
	s_nop 0
	global_load_lds_dwordx4 v[162:163], off
	v_lshl_add_u64 v[162:163], s[58:59], 0, v[168:169]
	s_mov_b32 m0, s62
	s_nop 0
	global_load_lds_dwordx4 v[162:163], off
	s_mov_b32 m0, s63
	s_nop 0
	global_load_lds_dwordx4 v[222:223], off
	s_waitcnt vmcnt(8)
	s_waitcnt lgkmcnt(0)
	s_barrier
; #define PG8_STAGE(bufoff, gbase, voff) do { _Pragma("unroll") for (int _i = 0; _i < 2; ++_i) \
;         __builtin_amdgcn_global_load_lds((const unsigned*)((const char*)(gbase) + (voff)[_i]), (LAS unsigned*)(lds + (bufoff) + ldsw + _i * 8192), 16, 0, 0); } while (0)
; #define PG8_LDA(dst, b, h) do { _Pragma("unroll") for (int m = 0; m < 4; ++m) _Pragma("unroll") for (int k = 0; k < 2; ++k) dst[m][k] = *(const LAS bf16x8*)(lds + PG8_SA(b, h) + aoff + m * 2048 + k * 1024); } while (0)
; #define PG8_LDB(dst, b, h) do { _Pragma("unroll") for (int n = 0; n < 2; ++n) _Pragma("unroll") for (int k = 0; k < 2; ++k) dst[n][k] = *(const LAS bf16x8*)(lds + PG8_SB(b, h) + boff + n * 2048 + k * 1024); } while (0)
; #define PG8_MMA(ai, bj, At, Bt) do { __builtin_amdgcn_s_setprio(1); _Pragma("unroll") for (int m = 0; m < 4; ++m) _Pragma("unroll") for (int n = 0; n < 2; ++n) _Pragma("unroll") for (int k = 0; k < 2; ++k) \
;         acc[ai][bj][m][n] = __builtin_amdgcn_mfma_f32_16x16x32_bf16(Bt[n][k], At[m][k], acc[ai][bj][m][n], 0, 0, 0); __builtin_amdgcn_s_setprio(0); } while (0)
; #define PG8_WAIT_V(n) asm volatile("s_waitcnt vmcnt(" #n ")" ::: "memory")
; #define PG8_WAIT_L(n) asm volatile("s_waitcnt lgkmcnt(" #n ")" ::: "memory")
; #define PG8_BAR __builtin_amdgcn_s_barrier()
; #define PG8_SCHED __builtin_amdgcn_sched_barrier(0)
; template <class Epi, class Sched, bool ALIGN_EPI = true>
; __device__ __forceinline__ void gemm_phase(LAS unsigned char* lds, const Gemm g, const Sched& S, const Epi& E) {
;     ...
;             PG8_WAIT_V(8); PG8_WAIT_L(0); PG8_BAR; PG8_MMA(1, 0, At, B0); PG8_MMA(1, 1, At, B1); PG8_BAR; PG8_SCHED;
;             PG8_LDB(B0, 1, 0); PG8_LDB(B1, 1, 1); PG8_SCHED; PG8_LDA(At, 1, 0); PG8_STAGE(PG8_SA(0, 1), a2 + hA, voffA);
;             PG8_WAIT_V(8); PG8_WAIT_L(0); PG8_BAR; PG8_MMA(0, 0, At, B0); PG8_MMA(0, 1, At, B1); PG8_BAR; PG8_SCHED;
	s_setprio 1
	s_waitcnt lgkmcnt(0)
	v_mfma_f32_16x16x32_bf16 v[60:63], v[132:135], v[182:185], 0
	v_mfma_f32_16x16x32_bf16 v[60:63], v[136:139], v[186:189], v[60:63]
	v_mfma_f32_16x16x32_bf16 v[68:71], v[140:143], v[182:185], 0
	v_mfma_f32_16x16x32_bf16 v[68:71], v[144:147], v[186:189], v[68:71]
	v_mfma_f32_16x16x32_bf16 v[40:43], v[132:135], v[190:193], 0
	v_mfma_f32_16x16x32_bf16 v[40:43], v[136:139], v[194:197], v[40:43]
	v_mfma_f32_16x16x32_bf16 v[64:67], v[140:143], v[190:193], 0
	v_mfma_f32_16x16x32_bf16 v[64:67], v[144:147], v[194:197], v[64:67]
	v_mfma_f32_16x16x32_bf16 v[24:27], v[132:135], v[206:209], 0
	v_mfma_f32_16x16x32_bf16 v[24:27], v[136:139], v[210:213], v[24:27]
	v_mfma_f32_16x16x32_bf16 v[56:59], v[140:143], v[206:209], 0
	v_mfma_f32_16x16x32_bf16 v[56:59], v[144:147], v[210:213], v[56:59]
	v_mfma_f32_16x16x32_bf16 v[12:15], v[132:135], v[214:217], 0
	v_mfma_f32_16x16x32_bf16 v[12:15], v[136:139], v[218:221], v[12:15]
	v_mfma_f32_16x16x32_bf16 v[48:51], v[140:143], v[214:217], 0
	v_mfma_f32_16x16x32_bf16 v[48:51], v[144:147], v[218:221], v[48:51]
	v_mfma_f32_16x16x32_bf16 v[104:107], v[148:151], v[182:185], 0
	v_mfma_f32_16x16x32_bf16 v[104:107], v[152:155], v[186:189], v[104:107]
	v_mfma_f32_16x16x32_bf16 v[20:23], v[174:177], v[182:185], 0
	v_mfma_f32_16x16x32_bf16 v[20:23], v[178:181], v[186:189], v[20:23]
	v_mfma_f32_16x16x32_bf16 v[92:95], v[148:151], v[190:193], 0
	v_mfma_f32_16x16x32_bf16 v[92:95], v[152:155], v[194:197], v[92:95]
	v_mfma_f32_16x16x32_bf16 v[16:19], v[174:177], v[190:193], 0
	v_mfma_f32_16x16x32_bf16 v[16:19], v[178:181], v[194:197], v[16:19]
	v_mfma_f32_16x16x32_bf16 v[76:79], v[148:151], v[206:209], 0
	v_mfma_f32_16x16x32_bf16 v[76:79], v[152:155], v[210:213], v[76:79]
	v_mfma_f32_16x16x32_bf16 v[8:11], v[174:177], v[206:209], 0
	v_mfma_f32_16x16x32_bf16 v[8:11], v[178:181], v[210:213], v[8:11]
	v_mfma_f32_16x16x32_bf16 v[52:55], v[148:151], v[214:217], 0
	v_mfma_f32_16x16x32_bf16 v[52:55], v[152:155], v[218:221], v[52:55]
	s_setprio 3
	s_barrier
	v_mfma_f32_16x16x32_bf16 v[4:7], v[174:177], v[214:217], 0
	v_mfma_f32_16x16x32_bf16 v[4:7], v[178:181], v[218:221], v[4:7]
	s_setprio 0
	s_add_i32 s30, 0, 0x18000
	v_add_u32_e32 v2, s30, v204
	s_add_i32 s31, 0, 0x1c000
	ds_read_b128 v[132:135], v2
	ds_read_b128 v[136:139], v2 offset:1024
	ds_read_b128 v[140:143], v2 offset:2048
	ds_read_b128 v[144:147], v2 offset:3072
	v_add_u32_e32 v2, s31, v204
	ds_read_b128 v[148:151], v2
	ds_read_b128 v[152:155], v2 offset:1024
	ds_read_b128 v[174:177], v2 offset:2048
	ds_read_b128 v[178:181], v2 offset:3072
	s_add_u32 s26, s58, 0x80000
	s_addc_u32 s27, s59, 0
	s_mov_b32 m0, s64
	v_lshl_add_u64 v[224:225], s[26:27], 0, v[168:169]
	ds_read_b128 v[182:185], v205 offset:32768
	ds_read_b128 v[186:189], v205 offset:33792
	ds_read_b128 v[190:193], v205 offset:34816
	ds_read_b128 v[194:197], v205 offset:35840
	ds_read_b128 v[206:209], v205 offset:36864
	ds_read_b128 v[210:213], v205 offset:37888
	ds_read_b128 v[214:217], v205 offset:38912
	ds_read_b128 v[218:221], v205 offset:39936
	global_load_lds_dwordx4 v[224:225], off
	v_lshl_add_u64 v[224:225], s[26:27], 0, v[164:165]
	s_mov_b32 m0, s65
	s_nop 0
	global_load_lds_dwordx4 v[224:225], off
	s_waitcnt vmcnt(8)
	s_waitcnt lgkmcnt(0)
	s_barrier
	s_setprio 1
	s_waitcnt lgkmcnt(0)
	v_mfma_f32_16x16x32_bf16 v[116:119], v[132:135], v[182:185], v[116:119]
	v_mfma_f32_16x16x32_bf16 v[116:119], v[136:139], v[186:189], v[116:119]
	v_mfma_f32_16x16x32_bf16 v[100:103], v[140:143], v[182:185], v[100:103]
	v_mfma_f32_16x16x32_bf16 v[100:103], v[144:147], v[186:189], v[100:103]
	v_mfma_f32_16x16x32_bf16 v[108:111], v[132:135], v[190:193], v[108:111]
	v_mfma_f32_16x16x32_bf16 v[108:111], v[136:139], v[194:197], v[108:111]
	v_mfma_f32_16x16x32_bf16 v[96:99], v[140:143], v[190:193], v[96:99]
	v_mfma_f32_16x16x32_bf16 v[96:99], v[144:147], v[194:197], v[96:99]
	v_mfma_f32_16x16x32_bf16 v[88:91], v[132:135], v[206:209], v[88:91]
	v_mfma_f32_16x16x32_bf16 v[88:91], v[136:139], v[210:213], v[88:91]
	v_mfma_f32_16x16x32_bf16 v[84:87], v[140:143], v[206:209], v[84:87]
	v_mfma_f32_16x16x32_bf16 v[84:87], v[144:147], v[210:213], v[84:87]
	v_mfma_f32_16x16x32_bf16 v[72:75], v[132:135], v[214:217], v[72:75]
	v_mfma_f32_16x16x32_bf16 v[72:75], v[136:139], v[218:221], v[72:75]
	v_mfma_f32_16x16x32_bf16 v[80:83], v[140:143], v[214:217], v[80:83]
	v_mfma_f32_16x16x32_bf16 v[80:83], v[144:147], v[218:221], v[80:83]
	v_mfma_f32_16x16x32_bf16 v[128:131], v[148:151], v[182:185], v[128:131]
	v_mfma_f32_16x16x32_bf16 v[128:131], v[152:155], v[186:189], v[128:131]
	v_mfma_f32_16x16x32_bf16 v[44:47], v[174:177], v[182:185], v[44:47]
	v_mfma_f32_16x16x32_bf16 v[44:47], v[178:181], v[186:189], v[44:47]
	v_mfma_f32_16x16x32_bf16 v[124:127], v[148:151], v[190:193], v[124:127]
	v_mfma_f32_16x16x32_bf16 v[124:127], v[152:155], v[194:197], v[124:127]
	v_mfma_f32_16x16x32_bf16 v[36:39], v[174:177], v[190:193], v[36:39]
	v_mfma_f32_16x16x32_bf16 v[36:39], v[178:181], v[194:197], v[36:39]
	v_mfma_f32_16x16x32_bf16 v[120:123], v[148:151], v[206:209], v[120:123]
	v_mfma_f32_16x16x32_bf16 v[120:123], v[152:155], v[210:213], v[120:123]
	v_mfma_f32_16x16x32_bf16 v[32:35], v[174:177], v[206:209], v[32:35]
	v_mfma_f32_16x16x32_bf16 v[32:35], v[178:181], v[210:213], v[32:35]
	v_mfma_f32_16x16x32_bf16 v[112:115], v[148:151], v[214:217], v[112:115]
	v_mfma_f32_16x16x32_bf16 v[112:115], v[152:155], v[218:221], v[112:115]
	s_setprio 3
	s_barrier
; #define PG8_STAGE(bufoff, gbase, voff) do { _Pragma("unroll") for (int _i = 0; _i < 2; ++_i) \
;         __builtin_amdgcn_global_load_lds((const unsigned*)((const char*)(gbase) + (voff)[_i]), (LAS unsigned*)(lds + (bufoff) + ldsw + _i * 8192), 16, 0, 0); } while (0)
; #define PG8_LDA(dst, b, h) do { _Pragma("unroll") for (int m = 0; m < 4; ++m) _Pragma("unroll") for (int k = 0; k < 2; ++k) dst[m][k] = *(const LAS bf16x8*)(lds + PG8_SA(b, h) + aoff + m * 2048 + k * 1024); } while (0)
; #define PG8_LDB(dst, b, h) do { _Pragma("unroll") for (int n = 0; n < 2; ++n) _Pragma("unroll") for (int k = 0; k < 2; ++k) dst[n][k] = *(const LAS bf16x8*)(lds + PG8_SB(b, h) + boff + n * 2048 + k * 1024); } while (0)
; #define PG8_WAIT_V(n) asm volatile("s_waitcnt vmcnt(" #n ")" ::: "memory")
; #define PG8_WAIT_L(n) asm volatile("s_waitcnt lgkmcnt(" #n ")" ::: "memory")
; template <class Epi, class Sched, bool ALIGN_EPI = true>
; __device__ __forceinline__ void gemm_phase(LAS unsigned char* lds, const Gemm g, const Sched& S, const Epi& E) {
;     ...
;             const bool last = (t == nt - 2);
;             const char* a1 = cA + (size_t)(t + 1) * kstep;
;             const char* a2 = last ? nA : cA + (size_t)(t + 2) * kstep; const char* b2 = last ? nB : cB + (size_t)(t + 2) * kstep;
;             const char* a3 = a2 + kstep; const char* b3 = b2 + kstep;
;             PG8_LDB(B0, 0, 0); PG8_LDB(B1, 0, 1); PG8_SCHED; PG8_LDA(At, 0, 0); PG8_STAGE(PG8_SA(1, 1), a1 + hA, voffA);
;             PG8_WAIT_V(8); PG8_WAIT_L(0); PG8_BAR; PG8_MMA(0, 0, At, B0); PG8_MMA(0, 1, At, B1); PG8_BAR; PG8_SCHED;
;             PG8_LDA(At, 0, 1); PG8_STAGE(PG8_SB(0, 0), b2, voffB); PG8_STAGE(PG8_SB(0, 1), b2 + hB, voffB); PG8_STAGE(PG8_SA(0, 0), a2, voffA);
;             PG8_WAIT_V(8); PG8_WAIT_L(0); PG8_BAR; PG8_MMA(1, 0, At, B0); PG8_MMA(1, 1, At, B1); PG8_BAR; PG8_SCHED;
;             PG8_LDB(B0, 1, 0); PG8_LDB(B1, 1, 1); PG8_SCHED; PG8_LDA(At, 1, 0); PG8_STAGE(PG8_SA(0, 1), a2 + hA, voffA);
;             PG8_WAIT_V(8); PG8_WAIT_L(0); PG8_BAR; PG8_MMA(0, 0, At, B0); PG8_MMA(0, 1, At, B1); PG8_BAR; PG8_SCHED;
;             PG8_LDA(At, 1, 1); PG8_STAGE(PG8_SB(1, 0), b3, voffB); PG8_STAGE(PG8_SB(1, 1), b3 + hB, voffB); PG8_STAGE(PG8_SA(1, 0), a3, voffA);
;             PG8_WAIT_V(8); PG8_WAIT_L(0); PG8_BAR; PG8_MMA(1, 0, At, B0); PG8_MMA(1, 1, At, B1); PG8_BAR; PG8_SCHED;
	v_mfma_f32_16x16x32_bf16 v[28:31], v[174:177], v[214:217], v[28:31]
	v_mfma_f32_16x16x32_bf16 v[28:31], v[178:181], v[218:221], v[28:31]
	s_setprio 0
	s_add_i32 s26, s30, s61
	v_lshl_add_u64 v[156:157], v[156:157], 0, s[86:87]
	s_mov_b32 m0, s26
	ds_read_b128 v[182:185], v205 offset:49152
	ds_read_b128 v[186:189], v205 offset:50176
	ds_read_b128 v[190:193], v205 offset:51200
	ds_read_b128 v[194:197], v205 offset:52224
	ds_read_b128 v[206:209], v205 offset:53248
	ds_read_b128 v[210:213], v205 offset:54272
	ds_read_b128 v[214:217], v205 offset:55296
	ds_read_b128 v[218:221], v205 offset:56320
	global_load_lds_dwordx4 v[156:157], off
	s_add_i32 m0, s26, 0x2000
	s_add_u32 s26, s44, 0x80080
	v_lshl_add_u64 v[156:157], v[160:161], 0, s[86:87]
	s_addc_u32 s27, s45, 0
	s_add_i32 s30, s31, s61
	global_load_lds_dwordx4 v[156:157], off
	v_lshl_add_u64 v[156:157], s[26:27], 0, v[166:167]
	s_mov_b32 m0, s30
	s_nop 0
	global_load_lds_dwordx4 v[156:157], off
	v_lshl_add_u64 v[156:157], s[26:27], 0, v[0:1]
	s_add_i32 m0, s30, 0x2000
	s_nop 0
	global_load_lds_dwordx4 v[156:157], off
	v_lshl_add_u64 v[156:157], v[162:163], 0, s[86:87]
	s_mov_b32 m0, s75
	s_nop 0
	global_load_lds_dwordx4 v[156:157], off
	v_lshl_add_u64 v[156:157], v[222:223], 0, s[86:87]
	s_mov_b32 m0, s76
	s_nop 0
	global_load_lds_dwordx4 v[156:157], off
	s_waitcnt vmcnt(8)
	s_waitcnt lgkmcnt(0)
	s_barrier
	s_setprio 1
	s_waitcnt lgkmcnt(0)
	v_mfma_f32_16x16x32_bf16 v[60:63], v[132:135], v[182:185], v[60:63]
	v_mfma_f32_16x16x32_bf16 v[60:63], v[136:139], v[186:189], v[60:63]
	s_add_i32 s25, s25, 2
	s_add_u32 s6, s6, 0x100
	v_mfma_f32_16x16x32_bf16 v[68:71], v[140:143], v[182:185], v[68:71]
	v_mfma_f32_16x16x32_bf16 v[68:71], v[144:147], v[186:189], v[68:71]
	s_addc_u32 s7, s7, 0
	s_add_u32 s19, s19, 0x100
	v_mfma_f32_16x16x32_bf16 v[40:43], v[132:135], v[190:193], v[40:43]
	v_mfma_f32_16x16x32_bf16 v[40:43], v[136:139], v[194:197], v[40:43]
	s_addc_u32 s24, s24, 0
	s_add_u32 s26, s6, 0xfff80080
	v_mfma_f32_16x16x32_bf16 v[64:67], v[140:143], v[190:193], v[64:67]
	v_mfma_f32_16x16x32_bf16 v[64:67], v[144:147], v[194:197], v[64:67]
	s_addc_u32 s27, s7, -1
	s_add_i32 s30, 0, 0x10000
	v_mfma_f32_16x16x32_bf16 v[24:27], v[132:135], v[206:209], v[24:27]
	v_mfma_f32_16x16x32_bf16 v[24:27], v[136:139], v[210:213], v[24:27]
	s_cmp_eq_u32 s25, 28
	s_cselect_b32 s59, s16, s27
	v_mfma_f32_16x16x32_bf16 v[56:59], v[140:143], v[206:209], v[56:59]
	v_mfma_f32_16x16x32_bf16 v[56:59], v[144:147], v[210:213], v[56:59]
	s_cselect_b32 s58, s17, s26
	s_cselect_b32 s45, s15, s24
	v_mfma_f32_16x16x32_bf16 v[12:15], v[132:135], v[214:217], v[12:15]
	v_mfma_f32_16x16x32_bf16 v[12:15], v[136:139], v[218:221], v[12:15]
	s_cselect_b32 s44, s18, s19
	s_add_i32 s31, 0, 0x14000
	v_mfma_f32_16x16x32_bf16 v[48:51], v[140:143], v[214:217], v[48:51]
	v_mfma_f32_16x16x32_bf16 v[48:51], v[144:147], v[218:221], v[48:51]
	v_mfma_f32_16x16x32_bf16 v[104:107], v[148:151], v[182:185], v[104:107]
	v_mfma_f32_16x16x32_bf16 v[104:107], v[152:155], v[186:189], v[104:107]
	v_mfma_f32_16x16x32_bf16 v[20:23], v[174:177], v[182:185], v[20:23]
	v_mfma_f32_16x16x32_bf16 v[20:23], v[178:181], v[186:189], v[20:23]
	v_mfma_f32_16x16x32_bf16 v[92:95], v[148:151], v[190:193], v[92:95]
	v_mfma_f32_16x16x32_bf16 v[92:95], v[152:155], v[194:197], v[92:95]
	v_mfma_f32_16x16x32_bf16 v[16:19], v[174:177], v[190:193], v[16:19]
	v_mfma_f32_16x16x32_bf16 v[16:19], v[178:181], v[194:197], v[16:19]
	v_mfma_f32_16x16x32_bf16 v[76:79], v[148:151], v[206:209], v[76:79]
	v_mfma_f32_16x16x32_bf16 v[76:79], v[152:155], v[210:213], v[76:79]
	v_mfma_f32_16x16x32_bf16 v[8:11], v[174:177], v[206:209], v[8:11]
	v_mfma_f32_16x16x32_bf16 v[8:11], v[178:181], v[210:213], v[8:11]
	v_mfma_f32_16x16x32_bf16 v[52:55], v[148:151], v[214:217], v[52:55]
	v_mfma_f32_16x16x32_bf16 v[52:55], v[152:155], v[218:221], v[52:55]
	s_setprio 3
	s_barrier
	v_mfma_f32_16x16x32_bf16 v[4:7], v[174:177], v[214:217], v[4:7]
	v_mfma_f32_16x16x32_bf16 v[4:7], v[178:181], v[218:221], v[4:7]
	s_setprio 0
	s_cmp_gt_u32 s25, 29
	s_cbranch_scc1 .Lpeel_exit_828
.LBB0_828:
	v_add_u32_e32 v2, s30, v204
	ds_read_b128 v[132:135], v2
	ds_read_b128 v[136:139], v2 offset:1024
	ds_read_b128 v[140:143], v2 offset:2048
	ds_read_b128 v[144:147], v2 offset:3072
	v_add_u32_e32 v2, s31, v204
	ds_read_b128 v[148:151], v2
	ds_read_b128 v[152:155], v2 offset:1024
	ds_read_b128 v[174:177], v2 offset:2048
	ds_read_b128 v[178:181], v2 offset:3072
	v_lshl_add_u64 v[156:157], s[6:7], 0, v[170:171]
	s_add_i32 m0, s62, 0xc000
	ds_read_b128 v[182:185], v205
	ds_read_b128 v[186:189], v205 offset:1024
	ds_read_b128 v[190:193], v205 offset:2048
	ds_read_b128 v[194:197], v205 offset:3072
	ds_read_b128 v[206:209], v205 offset:4096
	ds_read_b128 v[210:213], v205 offset:5120
	ds_read_b128 v[214:217], v205 offset:6144
	ds_read_b128 v[218:221], v205 offset:7168
	global_load_lds_dwordx4 v[156:157], off
	v_lshl_add_u64 v[156:157], s[6:7], 0, v[172:173]
	s_add_i32 m0, s62, 0xe000
	s_nop 0
	global_load_lds_dwordx4 v[156:157], off
	s_waitcnt vmcnt(8)
	s_waitcnt lgkmcnt(0)
	s_barrier
; #define PG8_STAGE(bufoff, gbase, voff) do { _Pragma("unroll") for (int _i = 0; _i < 2; ++_i) \
;         __builtin_amdgcn_global_load_lds((const unsigned*)((const char*)(gbase) + (voff)[_i]), (LAS unsigned*)(lds + (bufoff) + ldsw + _i * 8192), 16, 0, 0); } while (0)
; #define PG8_LDA(dst, b, h) do { _Pragma("unroll") for (int m = 0; m < 4; ++m) _Pragma("unroll") for (int k = 0; k < 2; ++k) dst[m][k] = *(const LAS bf16x8*)(lds + PG8_SA(b, h) + aoff + m * 2048 + k * 1024); } while (0)
; #define PG8_MMA(ai, bj, At, Bt) do { __builtin_amdgcn_s_setprio(1); _Pragma("unroll") for (int m = 0; m < 4; ++m) _Pragma("unroll") for (int n = 0; n < 2; ++n) _Pragma("unroll") for (int k = 0; k < 2; ++k) \
;         acc[ai][bj][m][n] = __builtin_amdgcn_mfma_f32_16x16x32_bf16(Bt[n][k], At[m][k], acc[ai][bj][m][n], 0, 0, 0); __builtin_amdgcn_s_setprio(0); } while (0)
; #define PG8_WAIT_V(n) asm volatile("s_waitcnt vmcnt(" #n ")" ::: "memory")
; #define PG8_WAIT_L(n) asm volatile("s_waitcnt lgkmcnt(" #n ")" ::: "memory")
; #define PG8_BAR __builtin_amdgcn_s_barrier()
; #define PG8_SCHED __builtin_amdgcn_sched_barrier(0)
; template <class Epi, class Sched, bool ALIGN_EPI = true>
; __device__ __forceinline__ void gemm_phase(LAS unsigned char* lds, const Gemm g, const Sched& S, const Epi& E) {
;     ...
;             PG8_WAIT_V(8); PG8_WAIT_L(0); PG8_BAR; PG8_MMA(0, 0, At, B0); PG8_MMA(0, 1, At, B1); PG8_BAR; PG8_SCHED;
;             PG8_LDA(At, 0, 1); PG8_STAGE(PG8_SB(0, 0), b2, voffB); PG8_STAGE(PG8_SB(0, 1), b2 + hB, voffB); PG8_STAGE(PG8_SA(0, 0), a2, voffA);
;             PG8_WAIT_V(8); PG8_WAIT_L(0); PG8_BAR; PG8_MMA(1, 0, At, B0); PG8_MMA(1, 1, At, B1); PG8_BAR; PG8_SCHED;
	s_setprio 1
	s_waitcnt lgkmcnt(0)
	v_mfma_f32_16x16x32_bf16 v[116:119], v[132:135], v[182:185], v[116:119]
	v_mfma_f32_16x16x32_bf16 v[116:119], v[136:139], v[186:189], v[116:119]
	v_mfma_f32_16x16x32_bf16 v[100:103], v[140:143], v[182:185], v[100:103]
	v_mfma_f32_16x16x32_bf16 v[100:103], v[144:147], v[186:189], v[100:103]
	v_mfma_f32_16x16x32_bf16 v[108:111], v[132:135], v[190:193], v[108:111]
	v_mfma_f32_16x16x32_bf16 v[108:111], v[136:139], v[194:197], v[108:111]
	v_mfma_f32_16x16x32_bf16 v[96:99], v[140:143], v[190:193], v[96:99]
	v_mfma_f32_16x16x32_bf16 v[96:99], v[144:147], v[194:197], v[96:99]
	v_mfma_f32_16x16x32_bf16 v[88:91], v[132:135], v[206:209], v[88:91]
	v_mfma_f32_16x16x32_bf16 v[88:91], v[136:139], v[210:213], v[88:91]
	v_mfma_f32_16x16x32_bf16 v[84:87], v[140:143], v[206:209], v[84:87]
	v_mfma_f32_16x16x32_bf16 v[84:87], v[144:147], v[210:213], v[84:87]
	v_mfma_f32_16x16x32_bf16 v[72:75], v[132:135], v[214:217], v[72:75]
	v_mfma_f32_16x16x32_bf16 v[72:75], v[136:139], v[218:221], v[72:75]
	v_mfma_f32_16x16x32_bf16 v[80:83], v[140:143], v[214:217], v[80:83]
	v_mfma_f32_16x16x32_bf16 v[80:83], v[144:147], v[218:221], v[80:83]
	v_mfma_f32_16x16x32_bf16 v[128:131], v[148:151], v[182:185], v[128:131]
	v_mfma_f32_16x16x32_bf16 v[128:131], v[152:155], v[186:189], v[128:131]
	v_mfma_f32_16x16x32_bf16 v[44:47], v[174:177], v[182:185], v[44:47]
	v_mfma_f32_16x16x32_bf16 v[44:47], v[178:181], v[186:189], v[44:47]
	v_mfma_f32_16x16x32_bf16 v[124:127], v[148:151], v[190:193], v[124:127]
	v_mfma_f32_16x16x32_bf16 v[124:127], v[152:155], v[194:197], v[124:127]
	v_mfma_f32_16x16x32_bf16 v[36:39], v[174:177], v[190:193], v[36:39]
	v_mfma_f32_16x16x32_bf16 v[36:39], v[178:181], v[194:197], v[36:39]
	v_mfma_f32_16x16x32_bf16 v[120:123], v[148:151], v[206:209], v[120:123]
	v_mfma_f32_16x16x32_bf16 v[120:123], v[152:155], v[210:213], v[120:123]
	v_mfma_f32_16x16x32_bf16 v[32:35], v[174:177], v[206:209], v[32:35]
	v_mfma_f32_16x16x32_bf16 v[32:35], v[178:181], v[210:213], v[32:35]
	v_mfma_f32_16x16x32_bf16 v[112:115], v[148:151], v[214:217], v[112:115]
	v_mfma_f32_16x16x32_bf16 v[112:115], v[152:155], v[218:221], v[112:115]
	s_setprio 3
	s_barrier
	v_mfma_f32_16x16x32_bf16 v[28:31], v[174:177], v[214:217], v[28:31]
	v_mfma_f32_16x16x32_bf16 v[28:31], v[178:181], v[218:221], v[28:31]
	s_setprio 0
	s_add_i32 s26, s30, s61
	v_lshl_add_u64 v[156:157], s[44:45], 0, v[166:167]
	s_mov_b32 m0, s26
	ds_read_b128 v[182:185], v205 offset:16384
	ds_read_b128 v[186:189], v205 offset:17408
	ds_read_b128 v[190:193], v205 offset:18432
	ds_read_b128 v[194:197], v205 offset:19456
	ds_read_b128 v[206:209], v205 offset:20480
	ds_read_b128 v[210:213], v205 offset:21504
	ds_read_b128 v[214:217], v205 offset:22528
	ds_read_b128 v[218:221], v205 offset:23552
	global_load_lds_dwordx4 v[156:157], off
	s_add_i32 m0, s26, 0x2000
	s_add_u32 s26, s44, 0x80000
	v_lshl_add_u64 v[160:161], s[44:45], 0, v[0:1]
	s_addc_u32 s27, s45, 0
	s_add_i32 s30, s31, s61
	global_load_lds_dwordx4 v[160:161], off
	v_lshl_add_u64 v[162:163], s[26:27], 0, v[166:167]
	s_mov_b32 m0, s30
	v_lshl_add_u64 v[222:223], s[58:59], 0, v[164:165]
	global_load_lds_dwordx4 v[162:163], off
	v_lshl_add_u64 v[162:163], s[26:27], 0, v[0:1]
	s_add_i32 m0, s30, 0x2000
	s_nop 0
	global_load_lds_dwordx4 v[162:163], off
	v_lshl_add_u64 v[162:163], s[58:59], 0, v[168:169]
	s_mov_b32 m0, s62
	s_nop 0
	global_load_lds_dwordx4 v[162:163], off
	s_mov_b32 m0, s63
	s_nop 0
	global_load_lds_dwordx4 v[222:223], off
	s_waitcnt vmcnt(8)
	s_waitcnt lgkmcnt(0)
	s_barrier
	s_setprio 1
	s_waitcnt lgkmcnt(0)
	v_mfma_f32_16x16x32_bf16 v[60:63], v[132:135], v[182:185], v[60:63]
	v_mfma_f32_16x16x32_bf16 v[60:63], v[136:139], v[186:189], v[60:63]
	v_mfma_f32_16x16x32_bf16 v[68:71], v[140:143], v[182:185], v[68:71]
	v_mfma_f32_16x16x32_bf16 v[68:71], v[144:147], v[186:189], v[68:71]
	v_mfma_f32_16x16x32_bf16 v[40:43], v[132:135], v[190:193], v[40:43]
	v_mfma_f32_16x16x32_bf16 v[40:43], v[136:139], v[194:197], v[40:43]
	v_mfma_f32_16x16x32_bf16 v[64:67], v[140:143], v[190:193], v[64:67]
	v_mfma_f32_16x16x32_bf16 v[64:67], v[144:147], v[194:197], v[64:67]
	v_mfma_f32_16x16x32_bf16 v[24:27], v[132:135], v[206:209], v[24:27]
	v_mfma_f32_16x16x32_bf16 v[24:27], v[136:139], v[210:213], v[24:27]
	v_mfma_f32_16x16x32_bf16 v[56:59], v[140:143], v[206:209], v[56:59]
	v_mfma_f32_16x16x32_bf16 v[56:59], v[144:147], v[210:213], v[56:59]
	v_mfma_f32_16x16x32_bf16 v[12:15], v[132:135], v[214:217], v[12:15]
	v_mfma_f32_16x16x32_bf16 v[12:15], v[136:139], v[218:221], v[12:15]
	v_mfma_f32_16x16x32_bf16 v[48:51], v[140:143], v[214:217], v[48:51]
	v_mfma_f32_16x16x32_bf16 v[48:51], v[144:147], v[218:221], v[48:51]
	v_mfma_f32_16x16x32_bf16 v[104:107], v[148:151], v[182:185], v[104:107]
	v_mfma_f32_16x16x32_bf16 v[104:107], v[152:155], v[186:189], v[104:107]
	v_mfma_f32_16x16x32_bf16 v[20:23], v[174:177], v[182:185], v[20:23]
	v_mfma_f32_16x16x32_bf16 v[20:23], v[178:181], v[186:189], v[20:23]
	v_mfma_f32_16x16x32_bf16 v[92:95], v[148:151], v[190:193], v[92:95]
	v_mfma_f32_16x16x32_bf16 v[92:95], v[152:155], v[194:197], v[92:95]
	v_mfma_f32_16x16x32_bf16 v[16:19], v[174:177], v[190:193], v[16:19]
	v_mfma_f32_16x16x32_bf16 v[16:19], v[178:181], v[194:197], v[16:19]
	v_mfma_f32_16x16x32_bf16 v[76:79], v[148:151], v[206:209], v[76:79]
	v_mfma_f32_16x16x32_bf16 v[76:79], v[152:155], v[210:213], v[76:79]
	v_mfma_f32_16x16x32_bf16 v[8:11], v[174:177], v[206:209], v[8:11]
	v_mfma_f32_16x16x32_bf16 v[8:11], v[178:181], v[210:213], v[8:11]
	v_mfma_f32_16x16x32_bf16 v[52:55], v[148:151], v[214:217], v[52:55]
	v_mfma_f32_16x16x32_bf16 v[52:55], v[152:155], v[218:221], v[52:55]
	s_setprio 3
	s_barrier
; #define PG8_STAGE(bufoff, gbase, voff) do { _Pragma("unroll") for (int _i = 0; _i < 2; ++_i) \
;         __builtin_amdgcn_global_load_lds((const unsigned*)((const char*)(gbase) + (voff)[_i]), (LAS unsigned*)(lds + (bufoff) + ldsw + _i * 8192), 16, 0, 0); } while (0)
; #define PG8_LDA(dst, b, h) do { _Pragma("unroll") for (int m = 0; m < 4; ++m) _Pragma("unroll") for (int k = 0; k < 2; ++k) dst[m][k] = *(const LAS bf16x8*)(lds + PG8_SA(b, h) + aoff + m * 2048 + k * 1024); } while (0)
; #define PG8_LDB(dst, b, h) do { _Pragma("unroll") for (int n = 0; n < 2; ++n) _Pragma("unroll") for (int k = 0; k < 2; ++k) dst[n][k] = *(const LAS bf16x8*)(lds + PG8_SB(b, h) + boff + n * 2048 + k * 1024); } while (0)
; #define PG8_MMA(ai, bj, At, Bt) do { __builtin_amdgcn_s_setprio(1); _Pragma("unroll") for (int m = 0; m < 4; ++m) _Pragma("unroll") for (int n = 0; n < 2; ++n) _Pragma("unroll") for (int k = 0; k < 2; ++k) \
;         acc[ai][bj][m][n] = __builtin_amdgcn_mfma_f32_16x16x32_bf16(Bt[n][k], At[m][k], acc[ai][bj][m][n], 0, 0, 0); __builtin_amdgcn_s_setprio(0); } while (0)
; #define PG8_WAIT_V(n) asm volatile("s_waitcnt vmcnt(" #n ")" ::: "memory")
; #define PG8_WAIT_L(n) asm volatile("s_waitcnt lgkmcnt(" #n ")" ::: "memory")
; #define PG8_BAR __builtin_amdgcn_s_barrier()
; #define PG8_SCHED __builtin_amdgcn_sched_barrier(0)
; template <class Epi, class Sched, bool ALIGN_EPI = true>
; __device__ __forceinline__ void gemm_phase(LAS unsigned char* lds, const Gemm g, const Sched& S, const Epi& E) {
;     ...
;             PG8_WAIT_V(8); PG8_WAIT_L(0); PG8_BAR; PG8_MMA(1, 0, At, B0); PG8_MMA(1, 1, At, B1); PG8_BAR; PG8_SCHED;
;             PG8_LDB(B0, 1, 0); PG8_LDB(B1, 1, 1); PG8_SCHED; PG8_LDA(At, 1, 0); PG8_STAGE(PG8_SA(0, 1), a2 + hA, voffA);
;             PG8_WAIT_V(8); PG8_WAIT_L(0); PG8_BAR; PG8_MMA(0, 0, At, B0); PG8_MMA(0, 1, At, B1); PG8_BAR; PG8_SCHED;
	v_mfma_f32_16x16x32_bf16 v[4:7], v[174:177], v[214:217], v[4:7]
	v_mfma_f32_16x16x32_bf16 v[4:7], v[178:181], v[218:221], v[4:7]
	s_setprio 0
	s_add_i32 s30, 0, 0x18000
	v_add_u32_e32 v2, s30, v204
	s_add_i32 s31, 0, 0x1c000
	ds_read_b128 v[132:135], v2
	ds_read_b128 v[136:139], v2 offset:1024
	ds_read_b128 v[140:143], v2 offset:2048
	ds_read_b128 v[144:147], v2 offset:3072
	v_add_u32_e32 v2, s31, v204
	ds_read_b128 v[148:151], v2
	ds_read_b128 v[152:155], v2 offset:1024
	ds_read_b128 v[174:177], v2 offset:2048
	ds_read_b128 v[178:181], v2 offset:3072
	s_add_u32 s26, s58, 0x80000
	s_addc_u32 s27, s59, 0
	s_mov_b32 m0, s64
	v_lshl_add_u64 v[224:225], s[26:27], 0, v[168:169]
	ds_read_b128 v[182:185], v205 offset:32768
	ds_read_b128 v[186:189], v205 offset:33792
	ds_read_b128 v[190:193], v205 offset:34816
	ds_read_b128 v[194:197], v205 offset:35840
	ds_read_b128 v[206:209], v205 offset:36864
	ds_read_b128 v[210:213], v205 offset:37888
	ds_read_b128 v[214:217], v205 offset:38912
	ds_read_b128 v[218:221], v205 offset:39936
	global_load_lds_dwordx4 v[224:225], off
	v_lshl_add_u64 v[224:225], s[26:27], 0, v[164:165]
	s_mov_b32 m0, s65
	s_nop 0
	global_load_lds_dwordx4 v[224:225], off
	s_waitcnt vmcnt(8)
	s_waitcnt lgkmcnt(0)
	s_barrier
	s_setprio 1
	s_waitcnt lgkmcnt(0)
	v_mfma_f32_16x16x32_bf16 v[116:119], v[132:135], v[182:185], v[116:119]
	v_mfma_f32_16x16x32_bf16 v[116:119], v[136:139], v[186:189], v[116:119]
	v_mfma_f32_16x16x32_bf16 v[100:103], v[140:143], v[182:185], v[100:103]
	v_mfma_f32_16x16x32_bf16 v[100:103], v[144:147], v[186:189], v[100:103]
	v_mfma_f32_16x16x32_bf16 v[108:111], v[132:135], v[190:193], v[108:111]
	v_mfma_f32_16x16x32_bf16 v[108:111], v[136:139], v[194:197], v[108:111]
	v_mfma_f32_16x16x32_bf16 v[96:99], v[140:143], v[190:193], v[96:99]
	v_mfma_f32_16x16x32_bf16 v[96:99], v[144:147], v[194:197], v[96:99]
	v_mfma_f32_16x16x32_bf16 v[88:91], v[132:135], v[206:209], v[88:91]
	v_mfma_f32_16x16x32_bf16 v[88:91], v[136:139], v[210:213], v[88:91]
	v_mfma_f32_16x16x32_bf16 v[84:87], v[140:143], v[206:209], v[84:87]
	v_mfma_f32_16x16x32_bf16 v[84:87], v[144:147], v[210:213], v[84:87]
	v_mfma_f32_16x16x32_bf16 v[72:75], v[132:135], v[214:217], v[72:75]
	v_mfma_f32_16x16x32_bf16 v[72:75], v[136:139], v[218:221], v[72:75]
	v_mfma_f32_16x16x32_bf16 v[80:83], v[140:143], v[214:217], v[80:83]
	v_mfma_f32_16x16x32_bf16 v[80:83], v[144:147], v[218:221], v[80:83]
	v_mfma_f32_16x16x32_bf16 v[128:131], v[148:151], v[182:185], v[128:131]
	v_mfma_f32_16x16x32_bf16 v[128:131], v[152:155], v[186:189], v[128:131]
	v_mfma_f32_16x16x32_bf16 v[44:47], v[174:177], v[182:185], v[44:47]
	v_mfma_f32_16x16x32_bf16 v[44:47], v[178:181], v[186:189], v[44:47]
	v_mfma_f32_16x16x32_bf16 v[124:127], v[148:151], v[190:193], v[124:127]
	v_mfma_f32_16x16x32_bf16 v[124:127], v[152:155], v[194:197], v[124:127]
	v_mfma_f32_16x16x32_bf16 v[36:39], v[174:177], v[190:193], v[36:39]
	v_mfma_f32_16x16x32_bf16 v[36:39], v[178:181], v[194:197], v[36:39]
	v_mfma_f32_16x16x32_bf16 v[120:123], v[148:151], v[206:209], v[120:123]
	v_mfma_f32_16x16x32_bf16 v[120:123], v[152:155], v[210:213], v[120:123]
	v_mfma_f32_16x16x32_bf16 v[32:35], v[174:177], v[206:209], v[32:35]
	v_mfma_f32_16x16x32_bf16 v[32:35], v[178:181], v[210:213], v[32:35]
	v_mfma_f32_16x16x32_bf16 v[112:115], v[148:151], v[214:217], v[112:115]
	v_mfma_f32_16x16x32_bf16 v[112:115], v[152:155], v[218:221], v[112:115]
	s_setprio 3
	s_barrier
; #define PG8_STAGE(bufoff, gbase, voff) do { _Pragma("unroll") for (int _i = 0; _i < 2; ++_i) \
;         __builtin_amdgcn_global_load_lds((const unsigned*)((const char*)(gbase) + (voff)[_i]), (LAS unsigned*)(lds + (bufoff) + ldsw + _i * 8192), 16, 0, 0); } while (0)
; #define PG8_LDA(dst, b, h) do { _Pragma("unroll") for (int m = 0; m < 4; ++m) _Pragma("unroll") for (int k = 0; k < 2; ++k) dst[m][k] = *(const LAS bf16x8*)(lds + PG8_SA(b, h) + aoff + m * 2048 + k * 1024); } while (0)
; #define PG8_LDB(dst, b, h) do { _Pragma("unroll") for (int n = 0; n < 2; ++n) _Pragma("unroll") for (int k = 0; k < 2; ++k) dst[n][k] = *(const LAS bf16x8*)(lds + PG8_SB(b, h) + boff + n * 2048 + k * 1024); } while (0)
; #define PG8_WAIT_V(n) asm volatile("s_waitcnt vmcnt(" #n ")" ::: "memory")
; #define PG8_WAIT_L(n) asm volatile("s_waitcnt lgkmcnt(" #n ")" ::: "memory")
; template <class Epi, class Sched, bool ALIGN_EPI = true>
; __device__ __forceinline__ void gemm_phase(LAS unsigned char* lds, const Gemm g, const Sched& S, const Epi& E) {
;     ...
;             const bool last = (t == nt - 2);
;             const char* a1 = cA + (size_t)(t + 1) * kstep;
;             const char* a2 = last ? nA : cA + (size_t)(t + 2) * kstep; const char* b2 = last ? nB : cB + (size_t)(t + 2) * kstep;
;             const char* a3 = a2 + kstep; const char* b3 = b2 + kstep;
;             PG8_LDB(B0, 0, 0); PG8_LDB(B1, 0, 1); PG8_SCHED; PG8_LDA(At, 0, 0); PG8_STAGE(PG8_SA(1, 1), a1 + hA, voffA);
;             PG8_WAIT_V(8); PG8_WAIT_L(0); PG8_BAR; PG8_MMA(0, 0, At, B0); PG8_MMA(0, 1, At, B1); PG8_BAR; PG8_SCHED;
;             PG8_LDA(At, 0, 1); PG8_STAGE(PG8_SB(0, 0), b2, voffB); PG8_STAGE(PG8_SB(0, 1), b2 + hB, voffB); PG8_STAGE(PG8_SA(0, 0), a2, voffA);
;             PG8_WAIT_V(8); PG8_WAIT_L(0); PG8_BAR; PG8_MMA(1, 0, At, B0); PG8_MMA(1, 1, At, B1); PG8_BAR; PG8_SCHED;
;             PG8_LDB(B0, 1, 0); PG8_LDB(B1, 1, 1); PG8_SCHED; PG8_LDA(At, 1, 0); PG8_STAGE(PG8_SA(0, 1), a2 + hA, voffA);
;             PG8_WAIT_V(8); PG8_WAIT_L(0); PG8_BAR; PG8_MMA(0, 0, At, B0); PG8_MMA(0, 1, At, B1); PG8_BAR; PG8_SCHED;
;             PG8_LDA(At, 1, 1); PG8_STAGE(PG8_SB(1, 0), b3, voffB); PG8_STAGE(PG8_SB(1, 1), b3 + hB, voffB); PG8_STAGE(PG8_SA(1, 0), a3, voffA);
;             PG8_WAIT_V(8); PG8_WAIT_L(0); PG8_BAR; PG8_MMA(1, 0, At, B0); PG8_MMA(1, 1, At, B1); PG8_BAR; PG8_SCHED;
	v_mfma_f32_16x16x32_bf16 v[28:31], v[174:177], v[214:217], v[28:31]
	v_mfma_f32_16x16x32_bf16 v[28:31], v[178:181], v[218:221], v[28:31]
	s_setprio 0
	s_add_i32 s26, s30, s61
	v_lshl_add_u64 v[156:157], v[156:157], 0, s[86:87]
	s_mov_b32 m0, s26
	ds_read_b128 v[182:185], v205 offset:49152
	ds_read_b128 v[186:189], v205 offset:50176
	ds_read_b128 v[190:193], v205 offset:51200
	ds_read_b128 v[194:197], v205 offset:52224
	ds_read_b128 v[206:209], v205 offset:53248
	ds_read_b128 v[210:213], v205 offset:54272
	ds_read_b128 v[214:217], v205 offset:55296
	ds_read_b128 v[218:221], v205 offset:56320
	global_load_lds_dwordx4 v[156:157], off
	s_add_i32 m0, s26, 0x2000
	s_add_u32 s26, s44, 0x80080
	v_lshl_add_u64 v[156:157], v[160:161], 0, s[86:87]
	s_addc_u32 s27, s45, 0
	s_add_i32 s30, s31, s61
	global_load_lds_dwordx4 v[156:157], off
	v_lshl_add_u64 v[156:157], s[26:27], 0, v[166:167]
	s_mov_b32 m0, s30
	s_nop 0
	global_load_lds_dwordx4 v[156:157], off
	v_lshl_add_u64 v[156:157], s[26:27], 0, v[0:1]
	s_add_i32 m0, s30, 0x2000
	s_nop 0
	global_load_lds_dwordx4 v[156:157], off
	v_lshl_add_u64 v[156:157], v[162:163], 0, s[86:87]
	s_mov_b32 m0, s75
	s_nop 0
	global_load_lds_dwordx4 v[156:157], off
	v_lshl_add_u64 v[156:157], v[222:223], 0, s[86:87]
	s_mov_b32 m0, s76
	s_nop 0
	global_load_lds_dwordx4 v[156:157], off
	s_waitcnt vmcnt(8)
	s_waitcnt lgkmcnt(0)
	s_barrier
	s_setprio 1
	s_waitcnt lgkmcnt(0)
	v_mfma_f32_16x16x32_bf16 v[60:63], v[132:135], v[182:185], v[60:63]
	v_mfma_f32_16x16x32_bf16 v[60:63], v[136:139], v[186:189], v[60:63]
	s_add_i32 s25, s25, 2
	s_add_u32 s6, s6, 0x100
	v_mfma_f32_16x16x32_bf16 v[68:71], v[140:143], v[182:185], v[68:71]
	v_mfma_f32_16x16x32_bf16 v[68:71], v[144:147], v[186:189], v[68:71]
	s_addc_u32 s7, s7, 0
	s_add_u32 s19, s19, 0x100
	v_mfma_f32_16x16x32_bf16 v[40:43], v[132:135], v[190:193], v[40:43]
	v_mfma_f32_16x16x32_bf16 v[40:43], v[136:139], v[194:197], v[40:43]
	s_addc_u32 s24, s24, 0
	s_add_u32 s26, s6, 0xfff80080
	v_mfma_f32_16x16x32_bf16 v[64:67], v[140:143], v[190:193], v[64:67]
	v_mfma_f32_16x16x32_bf16 v[64:67], v[144:147], v[194:197], v[64:67]
	s_addc_u32 s27, s7, -1
	s_add_i32 s30, 0, 0x10000
	v_mfma_f32_16x16x32_bf16 v[24:27], v[132:135], v[206:209], v[24:27]
	v_mfma_f32_16x16x32_bf16 v[24:27], v[136:139], v[210:213], v[24:27]
	s_cmp_eq_u32 s25, 28
	s_cselect_b32 s59, s16, s27
	v_mfma_f32_16x16x32_bf16 v[56:59], v[140:143], v[206:209], v[56:59]
	v_mfma_f32_16x16x32_bf16 v[56:59], v[144:147], v[210:213], v[56:59]
	s_cselect_b32 s58, s17, s26
	s_cselect_b32 s45, s15, s24
	v_mfma_f32_16x16x32_bf16 v[12:15], v[132:135], v[214:217], v[12:15]
	v_mfma_f32_16x16x32_bf16 v[12:15], v[136:139], v[218:221], v[12:15]
	s_cselect_b32 s44, s18, s19
	s_add_i32 s31, 0, 0x14000
	v_mfma_f32_16x16x32_bf16 v[48:51], v[140:143], v[214:217], v[48:51]
	v_mfma_f32_16x16x32_bf16 v[48:51], v[144:147], v[218:221], v[48:51]
	v_mfma_f32_16x16x32_bf16 v[104:107], v[148:151], v[182:185], v[104:107]
	v_mfma_f32_16x16x32_bf16 v[104:107], v[152:155], v[186:189], v[104:107]
	v_mfma_f32_16x16x32_bf16 v[20:23], v[174:177], v[182:185], v[20:23]
	v_mfma_f32_16x16x32_bf16 v[20:23], v[178:181], v[186:189], v[20:23]
	v_mfma_f32_16x16x32_bf16 v[92:95], v[148:151], v[190:193], v[92:95]
	v_mfma_f32_16x16x32_bf16 v[92:95], v[152:155], v[194:197], v[92:95]
	v_mfma_f32_16x16x32_bf16 v[16:19], v[174:177], v[190:193], v[16:19]
	v_mfma_f32_16x16x32_bf16 v[16:19], v[178:181], v[194:197], v[16:19]
	v_mfma_f32_16x16x32_bf16 v[76:79], v[148:151], v[206:209], v[76:79]
	v_mfma_f32_16x16x32_bf16 v[76:79], v[152:155], v[210:213], v[76:79]
	v_mfma_f32_16x16x32_bf16 v[8:11], v[174:177], v[206:209], v[8:11]
	v_mfma_f32_16x16x32_bf16 v[8:11], v[178:181], v[210:213], v[8:11]
	v_mfma_f32_16x16x32_bf16 v[52:55], v[148:151], v[214:217], v[52:55]
	v_mfma_f32_16x16x32_bf16 v[52:55], v[152:155], v[218:221], v[52:55]
	s_setprio 3
	s_barrier
	v_mfma_f32_16x16x32_bf16 v[4:7], v[174:177], v[214:217], v[4:7]
	v_mfma_f32_16x16x32_bf16 v[4:7], v[178:181], v[218:221], v[4:7]
	s_setprio 0
	s_cmp_gt_u32 s25, 29
	s_cbranch_scc0 .LBB0_828

;     __device__ bool next(int i, Unit& u) const { if (i >= 2) return false; const int x = c & 7, j = c >> 3; u.pm = 32 * i + 4 * x + (j & 3); u.pn = j >> 2; return true; }
; #define PG8_STAGE(bufoff, gbase, voff) do { _Pragma("unroll") for (int _i = 0; _i < 2; ++_i) \
;         __builtin_amdgcn_global_load_lds((const unsigned*)((const char*)(gbase) + (voff)[_i]), (LAS unsigned*)(lds + (bufoff) + ldsw + _i * 8192), 16, 0, 0); } while (0)
; #define PG8_LDA(dst, b, h) do { _Pragma("unroll") for (int m = 0; m < 4; ++m) _Pragma("unroll") for (int k = 0; k < 2; ++k) dst[m][k] = *(const LAS bf16x8*)(lds + PG8_SA(b, h) + aoff + m * 2048 + k * 1024); } while (0)
; #define PG8_LDB(dst, b, h) do { _Pragma("unroll") for (int n = 0; n < 2; ++n) _Pragma("unroll") for (int k = 0; k < 2; ++k) dst[n][k] = *(const LAS bf16x8*)(lds + PG8_SB(b, h) + boff + n * 2048 + k * 1024); } while (0)
; #define PG8_WAIT_V(n) asm volatile("s_waitcnt vmcnt(" #n ")" ::: "memory")
; #define PG8_WAIT_L(n) asm volatile("s_waitcnt lgkmcnt(" #n ")" ::: "memory")
; #define PG8_BAR __builtin_amdgcn_s_barrier()
; #define PG8_SCHED __builtin_amdgcn_sched_barrier(0)
; template <class Epi, class Sched, bool ALIGN_EPI = true>
; __device__ __forceinline__ void gemm_phase(LAS unsigned char* lds, const Gemm g, const Sched& S, const Epi& E) {
;     ...
;         const bool has_next = S.next(ui + 1, nxt);
;         const char* nA = has_next ? (const char*)g.A + ((size_t)nxt.pm * BM * g.lda + (size_t)nxt.pn * g.a_pn_off) * 2 : cA; const char* nB = has_next ? (const char*)g.Bt + (size_t)nxt.pn * BM * g.ldb * 2 : cB;
;         for (int t = 0; t < nt; t += 2) {
;             const bool last = (t == nt - 2);
;             const char* a1 = cA + (size_t)(t + 1) * kstep;
;             const char* a2 = last ? nA : cA + (size_t)(t + 2) * kstep; const char* b2 = last ? nB : cB + (size_t)(t + 2) * kstep;
;             const char* a3 = a2 + kstep; const char* b3 = b2 + kstep;
;             PG8_LDB(B0, 0, 0); PG8_LDB(B1, 0, 1); PG8_SCHED; PG8_LDA(At, 0, 0); PG8_STAGE(PG8_SA(1, 1), a1 + hA, voffA);
;             PG8_WAIT_V(8); PG8_WAIT_L(0); PG8_BAR; PG8_MMA(0, 0, At, B0); PG8_MMA(0, 1, At, B1); PG8_BAR; PG8_SCHED;
;             PG8_LDA(At, 0, 1); PG8_STAGE(PG8_SB(0, 0), b2, voffB); PG8_STAGE(PG8_SB(0, 1), b2 + hB, voffB); PG8_STAGE(PG8_SA(0, 0), a2, voffA);
.LBB0_1110:
	s_add_u32 s16, s10, 0x100
	s_addc_u32 s17, s11, 0
	s_add_u32 s10, s10, 0x160080
	s_addc_u32 s11, s11, 0
	v_lshl_add_u64 v[132:133], s[10:11], 0, v[168:169]
	v_lshl_add_u64 v[134:135], s[10:11], 0, v[170:171]
	s_mov_b32 s18, -2
	s_mov_b64 s[10:11], 0
	s_add_u32 vcc_lo, s10, 0x100
	s_addc_u32 vcc_hi, s11, 0
	s_add_u32 s19, s16, s10
	s_addc_u32 s24, s17, s11
	s_add_i32 s25, 0, 0x10000
	s_cmpk_eq_i32 s18, 0x54
	s_cselect_b32 s65, s61, s24
	s_cselect_b32 s24, 0, vcc_lo
	s_cselect_b32 s64, s60, s19
	s_cselect_b32 s19, 0, vcc_hi
	s_add_u32 s62, s2, s24
	v_add_u32_e32 v160, s25, v188
	s_addc_u32 s63, s3, s19
	s_add_i32 s19, 0, 0x14000
	ds_read_b128 v[136:139], v160
	ds_read_b128 v[140:143], v160 offset:1024
	ds_read_b128 v[144:147], v160 offset:2048
	ds_read_b128 v[172:175], v160 offset:3072
	v_add_u32_e32 v160, s19, v188
	ds_read_b128 v[176:179], v160
	ds_read_b128 v[180:183], v160 offset:1024
	ds_read_b128 v[184:187], v160 offset:2048
	ds_read_b128 v[208:211], v160 offset:3072
	v_lshl_add_u64 v[160:161], v[132:133], 0, s[10:11]
	s_add_i32 m0, s67, 0xc000
	ds_read_b128 v[212:215], v197
	ds_read_b128 v[216:219], v197 offset:1024
	ds_read_b128 v[220:223], v197 offset:2048
	ds_read_b128 v[224:227], v197 offset:3072
	ds_read_b128 v[228:231], v197 offset:4096
	ds_read_b128 v[232:235], v197 offset:5120
	ds_read_b128 v[236:239], v197 offset:6144
	ds_read_b128 v[240:243], v197 offset:7168
	global_load_lds_dwordx4 v[160:161], off
	v_lshl_add_u64 v[160:161], v[134:135], 0, s[10:11]
	s_add_i32 m0, s67, 0xe000
	s_nop 0
	global_load_lds_dwordx4 v[160:161], off
	s_waitcnt vmcnt(8)
	s_waitcnt lgkmcnt(0)
	s_barrier
	s_setprio 1
	s_waitcnt lgkmcnt(0)
	v_mfma_f32_16x16x32_bf16 v[16:19], v[136:139], v[212:215], 0
	v_mfma_f32_16x16x32_bf16 v[16:19], v[140:143], v[216:219], v[16:19]
	v_mfma_f32_16x16x32_bf16 v[12:15], v[144:147], v[212:215], 0
	v_mfma_f32_16x16x32_bf16 v[12:15], v[172:175], v[216:219], v[12:15]
	v_mfma_f32_16x16x32_bf16 v[56:59], v[136:139], v[220:223], 0
	v_mfma_f32_16x16x32_bf16 v[56:59], v[140:143], v[224:227], v[56:59]
	v_mfma_f32_16x16x32_bf16 v[52:55], v[144:147], v[220:223], 0
	v_mfma_f32_16x16x32_bf16 v[52:55], v[172:175], v[224:227], v[52:55]
	v_mfma_f32_16x16x32_bf16 v[88:91], v[136:139], v[228:231], 0
	v_mfma_f32_16x16x32_bf16 v[88:91], v[140:143], v[232:235], v[88:91]
	v_mfma_f32_16x16x32_bf16 v[76:79], v[144:147], v[228:231], 0
	v_mfma_f32_16x16x32_bf16 v[76:79], v[172:175], v[232:235], v[76:79]
	v_mfma_f32_16x16x32_bf16 v[112:115], v[136:139], v[236:239], 0
	v_mfma_f32_16x16x32_bf16 v[112:115], v[140:143], v[240:243], v[112:115]
	v_mfma_f32_16x16x32_bf16 v[108:111], v[144:147], v[236:239], 0
	v_mfma_f32_16x16x32_bf16 v[108:111], v[172:175], v[240:243], v[108:111]
	v_mfma_f32_16x16x32_bf16 v[8:11], v[176:179], v[212:215], 0
	v_mfma_f32_16x16x32_bf16 v[8:11], v[180:183], v[216:219], v[8:11]
	v_mfma_f32_16x16x32_bf16 v[4:7], v[184:187], v[212:215], 0
	v_mfma_f32_16x16x32_bf16 v[4:7], v[208:211], v[216:219], v[4:7]
	v_mfma_f32_16x16x32_bf16 v[40:43], v[176:179], v[220:223], 0
	v_mfma_f32_16x16x32_bf16 v[40:43], v[180:183], v[224:227], v[40:43]
	v_mfma_f32_16x16x32_bf16 v[36:39], v[184:187], v[220:223], 0
	v_mfma_f32_16x16x32_bf16 v[36:39], v[208:211], v[224:227], v[36:39]
	v_mfma_f32_16x16x32_bf16 v[64:67], v[176:179], v[228:231], 0
	v_mfma_f32_16x16x32_bf16 v[64:67], v[180:183], v[232:235], v[64:67]
	v_mfma_f32_16x16x32_bf16 v[60:63], v[184:187], v[228:231], 0
	v_mfma_f32_16x16x32_bf16 v[60:63], v[208:211], v[232:235], v[60:63]
	v_mfma_f32_16x16x32_bf16 v[96:99], v[176:179], v[236:239], 0
	v_mfma_f32_16x16x32_bf16 v[96:99], v[180:183], v[240:243], v[96:99]
	s_setprio 3
	s_barrier
	v_mfma_f32_16x16x32_bf16 v[92:95], v[184:187], v[236:239], 0
	v_mfma_f32_16x16x32_bf16 v[92:95], v[208:211], v[240:243], v[92:95]
	s_setprio 0
	s_add_i32 s10, s25, s66
	v_lshl_add_u64 v[160:161], s[62:63], 0, v[2:3]
	s_mov_b32 m0, s10
	ds_read_b128 v[212:215], v197 offset:16384
	ds_read_b128 v[216:219], v197 offset:17408
	ds_read_b128 v[220:223], v197 offset:18432
	ds_read_b128 v[224:227], v197 offset:19456
	ds_read_b128 v[228:231], v197 offset:20480
	ds_read_b128 v[232:235], v197 offset:21504
	ds_read_b128 v[236:239], v197 offset:22528
	ds_read_b128 v[240:243], v197 offset:23552
	global_load_lds_dwordx4 v[160:161], off
	s_add_i32 m0, s10, 0x2000
	s_add_u32 s10, s62, 0x160000
	v_lshl_add_u64 v[162:163], s[62:63], 0, v[150:151]
	s_addc_u32 s11, s63, 0
	s_add_i32 s19, s19, s66
	global_load_lds_dwordx4 v[162:163], off
	v_lshl_add_u64 v[244:245], s[10:11], 0, v[2:3]
	s_mov_b32 m0, s19
	v_lshl_add_u64 v[246:247], s[64:65], 0, v[148:149]
	global_load_lds_dwordx4 v[244:245], off
	v_lshl_add_u64 v[244:245], s[10:11], 0, v[150:151]
	s_add_i32 m0, s19, 0x2000
	s_nop 0
	global_load_lds_dwordx4 v[244:245], off
	v_lshl_add_u64 v[244:245], s[64:65], 0, v[0:1]
	s_mov_b32 m0, s67
	s_nop 0
	global_load_lds_dwordx4 v[244:245], off
	s_mov_b32 m0, s75
	s_nop 0
	global_load_lds_dwordx4 v[246:247], off
	s_waitcnt vmcnt(8)
	s_waitcnt lgkmcnt(0)
	s_barrier
; #define PG8_STAGE(bufoff, gbase, voff) do { _Pragma("unroll") for (int _i = 0; _i < 2; ++_i) \
;         __builtin_amdgcn_global_load_lds((const unsigned*)((const char*)(gbase) + (voff)[_i]), (LAS unsigned*)(lds + (bufoff) + ldsw + _i * 8192), 16, 0, 0); } while (0)
; #define PG8_LDA(dst, b, h) do { _Pragma("unroll") for (int m = 0; m < 4; ++m) _Pragma("unroll") for (int k = 0; k < 2; ++k) dst[m][k] = *(const LAS bf16x8*)(lds + PG8_SA(b, h) + aoff + m * 2048 + k * 1024); } while (0)
; #define PG8_LDB(dst, b, h) do { _Pragma("unroll") for (int n = 0; n < 2; ++n) _Pragma("unroll") for (int k = 0; k < 2; ++k) dst[n][k] = *(const LAS bf16x8*)(lds + PG8_SB(b, h) + boff + n * 2048 + k * 1024); } while (0)
; #define PG8_MMA(ai, bj, At, Bt) do { __builtin_amdgcn_s_setprio(1); _Pragma("unroll") for (int m = 0; m < 4; ++m) _Pragma("unroll") for (int n = 0; n < 2; ++n) _Pragma("unroll") for (int k = 0; k < 2; ++k) \
;         acc[ai][bj][m][n] = __builtin_amdgcn_mfma_f32_16x16x32_bf16(Bt[n][k], At[m][k], acc[ai][bj][m][n], 0, 0, 0); __builtin_amdgcn_s_setprio(0); } while (0)
; #define PG8_WAIT_V(n) asm volatile("s_waitcnt vmcnt(" #n ")" ::: "memory")
; #define PG8_WAIT_L(n) asm volatile("s_waitcnt lgkmcnt(" #n ")" ::: "memory")
; #define PG8_BAR __builtin_amdgcn_s_barrier()
; #define PG8_SCHED __builtin_amdgcn_sched_barrier(0)
; template <class Epi, class Sched, bool ALIGN_EPI = true>
; __device__ __forceinline__ void gemm_phase(LAS unsigned char* lds, const Gemm g, const Sched& S, const Epi& E) {
;     ...
;             PG8_WAIT_V(8); PG8_WAIT_L(0); PG8_BAR; PG8_MMA(1, 0, At, B0); PG8_MMA(1, 1, At, B1); PG8_BAR; PG8_SCHED;
;             PG8_LDB(B0, 1, 0); PG8_LDB(B1, 1, 1); PG8_SCHED; PG8_LDA(At, 1, 0); PG8_STAGE(PG8_SA(0, 1), a2 + hA, voffA);
;             PG8_WAIT_V(8); PG8_WAIT_L(0); PG8_BAR; PG8_MMA(0, 0, At, B0); PG8_MMA(0, 1, At, B1); PG8_BAR; PG8_SCHED;
	s_setprio 1
	s_waitcnt lgkmcnt(0)
	v_mfma_f32_16x16x32_bf16 v[128:131], v[136:139], v[212:215], 0
	v_mfma_f32_16x16x32_bf16 v[128:131], v[140:143], v[216:219], v[128:131]
	v_mfma_f32_16x16x32_bf16 v[124:127], v[144:147], v[212:215], 0
	v_mfma_f32_16x16x32_bf16 v[124:127], v[172:175], v[216:219], v[124:127]
	v_mfma_f32_16x16x32_bf16 v[104:107], v[136:139], v[220:223], 0
	v_mfma_f32_16x16x32_bf16 v[104:107], v[140:143], v[224:227], v[104:107]
	v_mfma_f32_16x16x32_bf16 v[100:103], v[144:147], v[220:223], 0
	v_mfma_f32_16x16x32_bf16 v[100:103], v[172:175], v[224:227], v[100:103]
	v_mfma_f32_16x16x32_bf16 v[72:75], v[136:139], v[228:231], 0
	v_mfma_f32_16x16x32_bf16 v[72:75], v[140:143], v[232:235], v[72:75]
	v_mfma_f32_16x16x32_bf16 v[68:71], v[144:147], v[228:231], 0
	v_mfma_f32_16x16x32_bf16 v[68:71], v[172:175], v[232:235], v[68:71]
	v_mfma_f32_16x16x32_bf16 v[32:35], v[136:139], v[236:239], 0
	v_mfma_f32_16x16x32_bf16 v[32:35], v[140:143], v[240:243], v[32:35]
	v_mfma_f32_16x16x32_bf16 v[28:31], v[144:147], v[236:239], 0
	v_mfma_f32_16x16x32_bf16 v[28:31], v[172:175], v[240:243], v[28:31]
	v_mfma_f32_16x16x32_bf16 v[120:123], v[176:179], v[212:215], 0
	v_mfma_f32_16x16x32_bf16 v[120:123], v[180:183], v[216:219], v[120:123]
	v_mfma_f32_16x16x32_bf16 v[116:119], v[184:187], v[212:215], 0
	v_mfma_f32_16x16x32_bf16 v[116:119], v[208:211], v[216:219], v[116:119]
	v_mfma_f32_16x16x32_bf16 v[84:87], v[176:179], v[220:223], 0
	v_mfma_f32_16x16x32_bf16 v[84:87], v[180:183], v[224:227], v[84:87]
	v_mfma_f32_16x16x32_bf16 v[80:83], v[184:187], v[220:223], 0
	v_mfma_f32_16x16x32_bf16 v[80:83], v[208:211], v[224:227], v[80:83]
	v_mfma_f32_16x16x32_bf16 v[48:51], v[176:179], v[228:231], 0
	v_mfma_f32_16x16x32_bf16 v[48:51], v[180:183], v[232:235], v[48:51]
	v_mfma_f32_16x16x32_bf16 v[44:47], v[184:187], v[228:231], 0
	v_mfma_f32_16x16x32_bf16 v[44:47], v[208:211], v[232:235], v[44:47]
	v_mfma_f32_16x16x32_bf16 v[24:27], v[176:179], v[236:239], 0
	v_mfma_f32_16x16x32_bf16 v[24:27], v[180:183], v[240:243], v[24:27]
	s_setprio 3
	s_barrier
	v_mfma_f32_16x16x32_bf16 v[20:23], v[184:187], v[236:239], 0
	v_mfma_f32_16x16x32_bf16 v[20:23], v[208:211], v[240:243], v[20:23]
	s_setprio 0
	s_add_i32 s19, 0, 0x18000
	s_add_i32 s24, 0, 0x1c000
	v_add_u32_e32 v172, s19, v188
	v_add_u32_e32 v207, s24, v188
	ds_read_b128 v[136:139], v172
	ds_read_b128 v[140:143], v172 offset:1024
	ds_read_b128 v[144:147], v172 offset:2048
	ds_read_b128 v[172:175], v172 offset:3072
	ds_read_b128 v[176:179], v207
	ds_read_b128 v[180:183], v207 offset:1024
	ds_read_b128 v[184:187], v207 offset:2048
	ds_read_b128 v[208:211], v207 offset:3072
	s_add_u32 s10, s64, 0x160000
	s_addc_u32 s11, s65, 0
	s_mov_b32 m0, s76
	v_lshl_add_u64 v[248:249], s[10:11], 0, v[0:1]
	ds_read_b128 v[212:215], v197 offset:32768
	ds_read_b128 v[216:219], v197 offset:33792
	ds_read_b128 v[220:223], v197 offset:34816
	ds_read_b128 v[224:227], v197 offset:35840
	ds_read_b128 v[228:231], v197 offset:36864
	ds_read_b128 v[232:235], v197 offset:37888
	ds_read_b128 v[236:239], v197 offset:38912
	ds_read_b128 v[240:243], v197 offset:39936
	global_load_lds_dwordx4 v[248:249], off
	v_lshl_add_u64 v[248:249], s[10:11], 0, v[148:149]
	s_mov_b32 m0, s77
	s_nop 0
	global_load_lds_dwordx4 v[248:249], off
	s_waitcnt vmcnt(8)
	s_waitcnt lgkmcnt(0)
	s_barrier
	s_setprio 1
	s_waitcnt lgkmcnt(0)
	v_mfma_f32_16x16x32_bf16 v[16:19], v[136:139], v[212:215], v[16:19]
	v_mfma_f32_16x16x32_bf16 v[16:19], v[140:143], v[216:219], v[16:19]
	v_mfma_f32_16x16x32_bf16 v[12:15], v[144:147], v[212:215], v[12:15]
	v_mfma_f32_16x16x32_bf16 v[12:15], v[172:175], v[216:219], v[12:15]
	v_mfma_f32_16x16x32_bf16 v[56:59], v[136:139], v[220:223], v[56:59]
	v_mfma_f32_16x16x32_bf16 v[56:59], v[140:143], v[224:227], v[56:59]
	v_mfma_f32_16x16x32_bf16 v[52:55], v[144:147], v[220:223], v[52:55]
	v_mfma_f32_16x16x32_bf16 v[52:55], v[172:175], v[224:227], v[52:55]
	v_mfma_f32_16x16x32_bf16 v[88:91], v[136:139], v[228:231], v[88:91]
	v_mfma_f32_16x16x32_bf16 v[88:91], v[140:143], v[232:235], v[88:91]
	v_mfma_f32_16x16x32_bf16 v[76:79], v[144:147], v[228:231], v[76:79]
	v_mfma_f32_16x16x32_bf16 v[76:79], v[172:175], v[232:235], v[76:79]
	v_mfma_f32_16x16x32_bf16 v[112:115], v[136:139], v[236:239], v[112:115]
	v_mfma_f32_16x16x32_bf16 v[112:115], v[140:143], v[240:243], v[112:115]
	v_mfma_f32_16x16x32_bf16 v[108:111], v[144:147], v[236:239], v[108:111]
	v_mfma_f32_16x16x32_bf16 v[108:111], v[172:175], v[240:243], v[108:111]
	v_mfma_f32_16x16x32_bf16 v[8:11], v[176:179], v[212:215], v[8:11]
	v_mfma_f32_16x16x32_bf16 v[8:11], v[180:183], v[216:219], v[8:11]
	v_mfma_f32_16x16x32_bf16 v[4:7], v[184:187], v[212:215], v[4:7]
	v_mfma_f32_16x16x32_bf16 v[4:7], v[208:211], v[216:219], v[4:7]
	v_mfma_f32_16x16x32_bf16 v[40:43], v[176:179], v[220:223], v[40:43]
	v_mfma_f32_16x16x32_bf16 v[40:43], v[180:183], v[224:227], v[40:43]
	v_mfma_f32_16x16x32_bf16 v[36:39], v[184:187], v[220:223], v[36:39]
	v_mfma_f32_16x16x32_bf16 v[36:39], v[208:211], v[224:227], v[36:39]
	v_mfma_f32_16x16x32_bf16 v[64:67], v[176:179], v[228:231], v[64:67]
	v_mfma_f32_16x16x32_bf16 v[64:67], v[180:183], v[232:235], v[64:67]
	v_mfma_f32_16x16x32_bf16 v[60:63], v[184:187], v[228:231], v[60:63]
	v_mfma_f32_16x16x32_bf16 v[60:63], v[208:211], v[232:235], v[60:63]
	v_mfma_f32_16x16x32_bf16 v[96:99], v[176:179], v[236:239], v[96:99]
	v_mfma_f32_16x16x32_bf16 v[96:99], v[180:183], v[240:243], v[96:99]
	s_setprio 3
	s_barrier
; #define PG8_STAGE(bufoff, gbase, voff) do { _Pragma("unroll") for (int _i = 0; _i < 2; ++_i) \
;         __builtin_amdgcn_global_load_lds((const unsigned*)((const char*)(gbase) + (voff)[_i]), (LAS unsigned*)(lds + (bufoff) + ldsw + _i * 8192), 16, 0, 0); } while (0)
; #define PG8_LDA(dst, b, h) do { _Pragma("unroll") for (int m = 0; m < 4; ++m) _Pragma("unroll") for (int k = 0; k < 2; ++k) dst[m][k] = *(const LAS bf16x8*)(lds + PG8_SA(b, h) + aoff + m * 2048 + k * 1024); } while (0)
; #define PG8_LDB(dst, b, h) do { _Pragma("unroll") for (int n = 0; n < 2; ++n) _Pragma("unroll") for (int k = 0; k < 2; ++k) dst[n][k] = *(const LAS bf16x8*)(lds + PG8_SB(b, h) + boff + n * 2048 + k * 1024); } while (0)
; #define PG8_WAIT_V(n) asm volatile("s_waitcnt vmcnt(" #n ")" ::: "memory")
; #define PG8_WAIT_L(n) asm volatile("s_waitcnt lgkmcnt(" #n ")" ::: "memory")
; template <class Epi, class Sched, bool ALIGN_EPI = true>
; __device__ __forceinline__ void gemm_phase(LAS unsigned char* lds, const Gemm g, const Sched& S, const Epi& E) {
;     ...
;             const bool last = (t == nt - 2);
;             const char* a1 = cA + (size_t)(t + 1) * kstep;
;             const char* a2 = last ? nA : cA + (size_t)(t + 2) * kstep; const char* b2 = last ? nB : cB + (size_t)(t + 2) * kstep;
;             const char* a3 = a2 + kstep; const char* b3 = b2 + kstep;
;             PG8_LDB(B0, 0, 0); PG8_LDB(B1, 0, 1); PG8_SCHED; PG8_LDA(At, 0, 0); PG8_STAGE(PG8_SA(1, 1), a1 + hA, voffA);
;             PG8_WAIT_V(8); PG8_WAIT_L(0); PG8_BAR; PG8_MMA(0, 0, At, B0); PG8_MMA(0, 1, At, B1); PG8_BAR; PG8_SCHED;
;             PG8_LDA(At, 0, 1); PG8_STAGE(PG8_SB(0, 0), b2, voffB); PG8_STAGE(PG8_SB(0, 1), b2 + hB, voffB); PG8_STAGE(PG8_SA(0, 0), a2, voffA);
;             PG8_WAIT_V(8); PG8_WAIT_L(0); PG8_BAR; PG8_MMA(1, 0, At, B0); PG8_MMA(1, 1, At, B1); PG8_BAR; PG8_SCHED;
;             PG8_LDB(B0, 1, 0); PG8_LDB(B1, 1, 1); PG8_SCHED; PG8_LDA(At, 1, 0); PG8_STAGE(PG8_SA(0, 1), a2 + hA, voffA);
;             PG8_WAIT_V(8); PG8_WAIT_L(0); PG8_BAR; PG8_MMA(0, 0, At, B0); PG8_MMA(0, 1, At, B1); PG8_BAR; PG8_SCHED;
;             PG8_LDA(At, 1, 1); PG8_STAGE(PG8_SB(1, 0), b3, voffB); PG8_STAGE(PG8_SB(1, 1), b3 + hB, voffB); PG8_STAGE(PG8_SA(1, 0), a3, voffA);
;             PG8_WAIT_V(8); PG8_WAIT_L(0); PG8_BAR; PG8_MMA(1, 0, At, B0); PG8_MMA(1, 1, At, B1); PG8_BAR; PG8_SCHED;
	v_mfma_f32_16x16x32_bf16 v[92:95], v[184:187], v[236:239], v[92:95]
	v_mfma_f32_16x16x32_bf16 v[92:95], v[208:211], v[240:243], v[92:95]
	s_setprio 0
	s_add_i32 s10, s19, s66
	v_lshl_add_u64 v[160:161], v[160:161], 0, s[86:87]
	s_mov_b32 m0, s10
	ds_read_b128 v[212:215], v197 offset:49152
	ds_read_b128 v[216:219], v197 offset:50176
	ds_read_b128 v[220:223], v197 offset:51200
	ds_read_b128 v[224:227], v197 offset:52224
	ds_read_b128 v[228:231], v197 offset:53248
	ds_read_b128 v[232:235], v197 offset:54272
	ds_read_b128 v[236:239], v197 offset:55296
	ds_read_b128 v[240:243], v197 offset:56320
	global_load_lds_dwordx4 v[160:161], off
	s_add_i32 m0, s10, 0x2000
	s_add_u32 s10, s62, 0x160080
	v_lshl_add_u64 v[160:161], v[162:163], 0, s[86:87]
	s_addc_u32 s11, s63, 0
	s_add_i32 s19, s24, s66
	global_load_lds_dwordx4 v[160:161], off
	v_lshl_add_u64 v[160:161], s[10:11], 0, v[2:3]
	s_mov_b32 m0, s19
	s_nop 0
	global_load_lds_dwordx4 v[160:161], off
	v_lshl_add_u64 v[160:161], s[10:11], 0, v[150:151]
	s_add_i32 m0, s19, 0x2000
	s_nop 0
	global_load_lds_dwordx4 v[160:161], off
	v_lshl_add_u64 v[160:161], v[244:245], 0, s[86:87]
	s_mov_b32 m0, s80
	s_nop 0
	global_load_lds_dwordx4 v[160:161], off
	v_lshl_add_u64 v[160:161], v[246:247], 0, s[86:87]
	s_mov_b32 m0, s81
	s_nop 0
	global_load_lds_dwordx4 v[160:161], off
	s_waitcnt vmcnt(8)
	s_waitcnt lgkmcnt(0)
	s_barrier
	s_setprio 1
	s_waitcnt lgkmcnt(0)
	v_mfma_f32_16x16x32_bf16 v[128:131], v[136:139], v[212:215], v[128:131]
	v_mfma_f32_16x16x32_bf16 v[128:131], v[140:143], v[216:219], v[128:131]
	v_mfma_f32_16x16x32_bf16 v[124:127], v[144:147], v[212:215], v[124:127]
	v_mfma_f32_16x16x32_bf16 v[124:127], v[172:175], v[216:219], v[124:127]
	v_mfma_f32_16x16x32_bf16 v[104:107], v[136:139], v[220:223], v[104:107]
	v_mfma_f32_16x16x32_bf16 v[104:107], v[140:143], v[224:227], v[104:107]
	v_mfma_f32_16x16x32_bf16 v[100:103], v[144:147], v[220:223], v[100:103]
	v_mfma_f32_16x16x32_bf16 v[100:103], v[172:175], v[224:227], v[100:103]
	v_mfma_f32_16x16x32_bf16 v[72:75], v[136:139], v[228:231], v[72:75]
	v_mfma_f32_16x16x32_bf16 v[72:75], v[140:143], v[232:235], v[72:75]
	v_mfma_f32_16x16x32_bf16 v[68:71], v[144:147], v[228:231], v[68:71]
	v_mfma_f32_16x16x32_bf16 v[68:71], v[172:175], v[232:235], v[68:71]
	v_mfma_f32_16x16x32_bf16 v[32:35], v[136:139], v[236:239], v[32:35]
	v_mfma_f32_16x16x32_bf16 v[32:35], v[140:143], v[240:243], v[32:35]
	v_mfma_f32_16x16x32_bf16 v[28:31], v[144:147], v[236:239], v[28:31]
	v_mfma_f32_16x16x32_bf16 v[28:31], v[172:175], v[240:243], v[28:31]
	v_mfma_f32_16x16x32_bf16 v[120:123], v[176:179], v[212:215], v[120:123]
	v_mfma_f32_16x16x32_bf16 v[120:123], v[180:183], v[216:219], v[120:123]
	v_mfma_f32_16x16x32_bf16 v[116:119], v[184:187], v[212:215], v[116:119]
	v_mfma_f32_16x16x32_bf16 v[116:119], v[208:211], v[216:219], v[116:119]
	v_mfma_f32_16x16x32_bf16 v[84:87], v[176:179], v[220:223], v[84:87]
	v_mfma_f32_16x16x32_bf16 v[84:87], v[180:183], v[224:227], v[84:87]
	v_mfma_f32_16x16x32_bf16 v[80:83], v[184:187], v[220:223], v[80:83]
	v_mfma_f32_16x16x32_bf16 v[80:83], v[208:211], v[224:227], v[80:83]
	v_mfma_f32_16x16x32_bf16 v[48:51], v[176:179], v[228:231], v[48:51]
	v_mfma_f32_16x16x32_bf16 v[48:51], v[180:183], v[232:235], v[48:51]
	v_mfma_f32_16x16x32_bf16 v[44:47], v[184:187], v[228:231], v[44:47]
	v_mfma_f32_16x16x32_bf16 v[44:47], v[208:211], v[232:235], v[44:47]
	v_mfma_f32_16x16x32_bf16 v[24:27], v[176:179], v[236:239], v[24:27]
	v_mfma_f32_16x16x32_bf16 v[24:27], v[180:183], v[240:243], v[24:27]
	s_setprio 3
	s_barrier
	v_mfma_f32_16x16x32_bf16 v[20:23], v[184:187], v[236:239], v[20:23]
	v_mfma_f32_16x16x32_bf16 v[20:23], v[208:211], v[240:243], v[20:23]
	s_setprio 0
	s_add_i32 s18, s18, 2
	s_cmpk_gt_u32 s18, 0x55
	s_mov_b64 s[10:11], vcc
	s_cbranch_scc1 .Lpeel_exit_1111
.LBB0_1111:
	s_add_u32 vcc_lo, s10, 0x100
	s_addc_u32 vcc_hi, s11, 0
	s_add_u32 s19, s16, s10
	s_addc_u32 s24, s17, s11
	s_add_i32 s25, 0, 0x10000
	s_cmpk_eq_i32 s18, 0x54
	s_cselect_b32 s65, s61, s24
	s_cselect_b32 s24, 0, vcc_lo
	s_cselect_b32 s64, s60, s19
	s_cselect_b32 s19, 0, vcc_hi
	s_add_u32 s62, s2, s24
	v_add_u32_e32 v160, s25, v188
	s_addc_u32 s63, s3, s19
	s_add_i32 s19, 0, 0x14000
	ds_read_b128 v[136:139], v160
	ds_read_b128 v[140:143], v160 offset:1024
	ds_read_b128 v[144:147], v160 offset:2048
	ds_read_b128 v[172:175], v160 offset:3072
	v_add_u32_e32 v160, s19, v188
	ds_read_b128 v[176:179], v160
	ds_read_b128 v[180:183], v160 offset:1024
	ds_read_b128 v[184:187], v160 offset:2048
	ds_read_b128 v[208:211], v160 offset:3072
	v_lshl_add_u64 v[160:161], v[132:133], 0, s[10:11]
	s_add_i32 m0, s67, 0xc000
	ds_read_b128 v[212:215], v197
	ds_read_b128 v[216:219], v197 offset:1024
	ds_read_b128 v[220:223], v197 offset:2048
	ds_read_b128 v[224:227], v197 offset:3072
	ds_read_b128 v[228:231], v197 offset:4096
	ds_read_b128 v[232:235], v197 offset:5120
	ds_read_b128 v[236:239], v197 offset:6144
	ds_read_b128 v[240:243], v197 offset:7168
	global_load_lds_dwordx4 v[160:161], off
	v_lshl_add_u64 v[160:161], v[134:135], 0, s[10:11]
	s_add_i32 m0, s67, 0xe000
	s_nop 0
	global_load_lds_dwordx4 v[160:161], off
	s_waitcnt vmcnt(8)
	s_waitcnt lgkmcnt(0)
	s_barrier
; #define PG8_STAGE(bufoff, gbase, voff) do { _Pragma("unroll") for (int _i = 0; _i < 2; ++_i) \
;         __builtin_amdgcn_global_load_lds((const unsigned*)((const char*)(gbase) + (voff)[_i]), (LAS unsigned*)(lds + (bufoff) + ldsw + _i * 8192), 16, 0, 0); } while (0)
; #define PG8_LDA(dst, b, h) do { _Pragma("unroll") for (int m = 0; m < 4; ++m) _Pragma("unroll") for (int k = 0; k < 2; ++k) dst[m][k] = *(const LAS bf16x8*)(lds + PG8_SA(b, h) + aoff + m * 2048 + k * 1024); } while (0)
; #define PG8_MMA(ai, bj, At, Bt) do { __builtin_amdgcn_s_setprio(1); _Pragma("unroll") for (int m = 0; m < 4; ++m) _Pragma("unroll") for (int n = 0; n < 2; ++n) _Pragma("unroll") for (int k = 0; k < 2; ++k) \
;         acc[ai][bj][m][n] = __builtin_amdgcn_mfma_f32_16x16x32_bf16(Bt[n][k], At[m][k], acc[ai][bj][m][n], 0, 0, 0); __builtin_amdgcn_s_setprio(0); } while (0)
; #define PG8_WAIT_V(n) asm volatile("s_waitcnt vmcnt(" #n ")" ::: "memory")
; #define PG8_WAIT_L(n) asm volatile("s_waitcnt lgkmcnt(" #n ")" ::: "memory")
; #define PG8_BAR __builtin_amdgcn_s_barrier()
; #define PG8_SCHED __builtin_amdgcn_sched_barrier(0)
; template <class Epi, class Sched, bool ALIGN_EPI = true>
; __device__ __forceinline__ void gemm_phase(LAS unsigned char* lds, const Gemm g, const Sched& S, const Epi& E) {
;     ...
;             PG8_WAIT_V(8); PG8_WAIT_L(0); PG8_BAR; PG8_MMA(0, 0, At, B0); PG8_MMA(0, 1, At, B1); PG8_BAR; PG8_SCHED;
;             PG8_LDA(At, 0, 1); PG8_STAGE(PG8_SB(0, 0), b2, voffB); PG8_STAGE(PG8_SB(0, 1), b2 + hB, voffB); PG8_STAGE(PG8_SA(0, 0), a2, voffA);
;             PG8_WAIT_V(8); PG8_WAIT_L(0); PG8_BAR; PG8_MMA(1, 0, At, B0); PG8_MMA(1, 1, At, B1); PG8_BAR; PG8_SCHED;
	s_setprio 1
	s_waitcnt lgkmcnt(0)
	v_mfma_f32_16x16x32_bf16 v[16:19], v[136:139], v[212:215], v[16:19]
	v_mfma_f32_16x16x32_bf16 v[16:19], v[140:143], v[216:219], v[16:19]
	v_mfma_f32_16x16x32_bf16 v[12:15], v[144:147], v[212:215], v[12:15]
	v_mfma_f32_16x16x32_bf16 v[12:15], v[172:175], v[216:219], v[12:15]
	v_mfma_f32_16x16x32_bf16 v[56:59], v[136:139], v[220:223], v[56:59]
	v_mfma_f32_16x16x32_bf16 v[56:59], v[140:143], v[224:227], v[56:59]
	v_mfma_f32_16x16x32_bf16 v[52:55], v[144:147], v[220:223], v[52:55]
	v_mfma_f32_16x16x32_bf16 v[52:55], v[172:175], v[224:227], v[52:55]
	v_mfma_f32_16x16x32_bf16 v[88:91], v[136:139], v[228:231], v[88:91]
	v_mfma_f32_16x16x32_bf16 v[88:91], v[140:143], v[232:235], v[88:91]
	v_mfma_f32_16x16x32_bf16 v[76:79], v[144:147], v[228:231], v[76:79]
	v_mfma_f32_16x16x32_bf16 v[76:79], v[172:175], v[232:235], v[76:79]
	v_mfma_f32_16x16x32_bf16 v[112:115], v[136:139], v[236:239], v[112:115]
	v_mfma_f32_16x16x32_bf16 v[112:115], v[140:143], v[240:243], v[112:115]
	v_mfma_f32_16x16x32_bf16 v[108:111], v[144:147], v[236:239], v[108:111]
	v_mfma_f32_16x16x32_bf16 v[108:111], v[172:175], v[240:243], v[108:111]
	v_mfma_f32_16x16x32_bf16 v[8:11], v[176:179], v[212:215], v[8:11]
	v_mfma_f32_16x16x32_bf16 v[8:11], v[180:183], v[216:219], v[8:11]
	v_mfma_f32_16x16x32_bf16 v[4:7], v[184:187], v[212:215], v[4:7]
	v_mfma_f32_16x16x32_bf16 v[4:7], v[208:211], v[216:219], v[4:7]
	v_mfma_f32_16x16x32_bf16 v[40:43], v[176:179], v[220:223], v[40:43]
	v_mfma_f32_16x16x32_bf16 v[40:43], v[180:183], v[224:227], v[40:43]
	v_mfma_f32_16x16x32_bf16 v[36:39], v[184:187], v[220:223], v[36:39]
	v_mfma_f32_16x16x32_bf16 v[36:39], v[208:211], v[224:227], v[36:39]
	v_mfma_f32_16x16x32_bf16 v[64:67], v[176:179], v[228:231], v[64:67]
	v_mfma_f32_16x16x32_bf16 v[64:67], v[180:183], v[232:235], v[64:67]
	v_mfma_f32_16x16x32_bf16 v[60:63], v[184:187], v[228:231], v[60:63]
	v_mfma_f32_16x16x32_bf16 v[60:63], v[208:211], v[232:235], v[60:63]
	v_mfma_f32_16x16x32_bf16 v[96:99], v[176:179], v[236:239], v[96:99]
	v_mfma_f32_16x16x32_bf16 v[96:99], v[180:183], v[240:243], v[96:99]
	s_setprio 3
	s_barrier
	v_mfma_f32_16x16x32_bf16 v[92:95], v[184:187], v[236:239], v[92:95]
	v_mfma_f32_16x16x32_bf16 v[92:95], v[208:211], v[240:243], v[92:95]
	s_setprio 0
	s_add_i32 s10, s25, s66
	v_lshl_add_u64 v[160:161], s[62:63], 0, v[2:3]
	s_mov_b32 m0, s10
	ds_read_b128 v[212:215], v197 offset:16384
	ds_read_b128 v[216:219], v197 offset:17408
	ds_read_b128 v[220:223], v197 offset:18432
	ds_read_b128 v[224:227], v197 offset:19456
	ds_read_b128 v[228:231], v197 offset:20480
	ds_read_b128 v[232:235], v197 offset:21504
	ds_read_b128 v[236:239], v197 offset:22528
	ds_read_b128 v[240:243], v197 offset:23552
	global_load_lds_dwordx4 v[160:161], off
	s_add_i32 m0, s10, 0x2000
	s_add_u32 s10, s62, 0x160000
	v_lshl_add_u64 v[162:163], s[62:63], 0, v[150:151]
	s_addc_u32 s11, s63, 0
	s_add_i32 s19, s19, s66
	global_load_lds_dwordx4 v[162:163], off
	v_lshl_add_u64 v[244:245], s[10:11], 0, v[2:3]
	s_mov_b32 m0, s19
	v_lshl_add_u64 v[246:247], s[64:65], 0, v[148:149]
	global_load_lds_dwordx4 v[244:245], off
	v_lshl_add_u64 v[244:245], s[10:11], 0, v[150:151]
	s_add_i32 m0, s19, 0x2000
	s_nop 0
	global_load_lds_dwordx4 v[244:245], off
	v_lshl_add_u64 v[244:245], s[64:65], 0, v[0:1]
	s_mov_b32 m0, s67
	s_nop 0
	global_load_lds_dwordx4 v[244:245], off
	s_mov_b32 m0, s75
	s_nop 0
	global_load_lds_dwordx4 v[246:247], off
	s_waitcnt vmcnt(8)
	s_waitcnt lgkmcnt(0)
	s_barrier
	s_setprio 1
	s_waitcnt lgkmcnt(0)
	v_mfma_f32_16x16x32_bf16 v[128:131], v[136:139], v[212:215], v[128:131]
	v_mfma_f32_16x16x32_bf16 v[128:131], v[140:143], v[216:219], v[128:131]
	v_mfma_f32_16x16x32_bf16 v[124:127], v[144:147], v[212:215], v[124:127]
	v_mfma_f32_16x16x32_bf16 v[124:127], v[172:175], v[216:219], v[124:127]
	v_mfma_f32_16x16x32_bf16 v[104:107], v[136:139], v[220:223], v[104:107]
	v_mfma_f32_16x16x32_bf16 v[104:107], v[140:143], v[224:227], v[104:107]
	v_mfma_f32_16x16x32_bf16 v[100:103], v[144:147], v[220:223], v[100:103]
	v_mfma_f32_16x16x32_bf16 v[100:103], v[172:175], v[224:227], v[100:103]
	v_mfma_f32_16x16x32_bf16 v[72:75], v[136:139], v[228:231], v[72:75]
	v_mfma_f32_16x16x32_bf16 v[72:75], v[140:143], v[232:235], v[72:75]
	v_mfma_f32_16x16x32_bf16 v[68:71], v[144:147], v[228:231], v[68:71]
	v_mfma_f32_16x16x32_bf16 v[68:71], v[172:175], v[232:235], v[68:71]
	v_mfma_f32_16x16x32_bf16 v[32:35], v[136:139], v[236:239], v[32:35]
	v_mfma_f32_16x16x32_bf16 v[32:35], v[140:143], v[240:243], v[32:35]
	v_mfma_f32_16x16x32_bf16 v[28:31], v[144:147], v[236:239], v[28:31]
	v_mfma_f32_16x16x32_bf16 v[28:31], v[172:175], v[240:243], v[28:31]
	v_mfma_f32_16x16x32_bf16 v[120:123], v[176:179], v[212:215], v[120:123]
	v_mfma_f32_16x16x32_bf16 v[120:123], v[180:183], v[216:219], v[120:123]
	v_mfma_f32_16x16x32_bf16 v[116:119], v[184:187], v[212:215], v[116:119]
	v_mfma_f32_16x16x32_bf16 v[116:119], v[208:211], v[216:219], v[116:119]
	v_mfma_f32_16x16x32_bf16 v[84:87], v[176:179], v[220:223], v[84:87]
	v_mfma_f32_16x16x32_bf16 v[84:87], v[180:183], v[224:227], v[84:87]
	v_mfma_f32_16x16x32_bf16 v[80:83], v[184:187], v[220:223], v[80:83]
	v_mfma_f32_16x16x32_bf16 v[80:83], v[208:211], v[224:227], v[80:83]
	v_mfma_f32_16x16x32_bf16 v[48:51], v[176:179], v[228:231], v[48:51]
	v_mfma_f32_16x16x32_bf16 v[48:51], v[180:183], v[232:235], v[48:51]
	v_mfma_f32_16x16x32_bf16 v[44:47], v[184:187], v[228:231], v[44:47]
	v_mfma_f32_16x16x32_bf16 v[44:47], v[208:211], v[232:235], v[44:47]
	v_mfma_f32_16x16x32_bf16 v[24:27], v[176:179], v[236:239], v[24:27]
	v_mfma_f32_16x16x32_bf16 v[24:27], v[180:183], v[240:243], v[24:27]
	s_setprio 3
	s_barrier
; #define PG8_STAGE(bufoff, gbase, voff) do { _Pragma("unroll") for (int _i = 0; _i < 2; ++_i) \
;         __builtin_amdgcn_global_load_lds((const unsigned*)((const char*)(gbase) + (voff)[_i]), (LAS unsigned*)(lds + (bufoff) + ldsw + _i * 8192), 16, 0, 0); } while (0)
; #define PG8_LDA(dst, b, h) do { _Pragma("unroll") for (int m = 0; m < 4; ++m) _Pragma("unroll") for (int k = 0; k < 2; ++k) dst[m][k] = *(const LAS bf16x8*)(lds + PG8_SA(b, h) + aoff + m * 2048 + k * 1024); } while (0)
; #define PG8_LDB(dst, b, h) do { _Pragma("unroll") for (int n = 0; n < 2; ++n) _Pragma("unroll") for (int k = 0; k < 2; ++k) dst[n][k] = *(const LAS bf16x8*)(lds + PG8_SB(b, h) + boff + n * 2048 + k * 1024); } while (0)
; #define PG8_MMA(ai, bj, At, Bt) do { __builtin_amdgcn_s_setprio(1); _Pragma("unroll") for (int m = 0; m < 4; ++m) _Pragma("unroll") for (int n = 0; n < 2; ++n) _Pragma("unroll") for (int k = 0; k < 2; ++k) \
;         acc[ai][bj][m][n] = __builtin_amdgcn_mfma_f32_16x16x32_bf16(Bt[n][k], At[m][k], acc[ai][bj][m][n], 0, 0, 0); __builtin_amdgcn_s_setprio(0); } while (0)
; #define PG8_WAIT_V(n) asm volatile("s_waitcnt vmcnt(" #n ")" ::: "memory")
; #define PG8_WAIT_L(n) asm volatile("s_waitcnt lgkmcnt(" #n ")" ::: "memory")
; #define PG8_BAR __builtin_amdgcn_s_barrier()
; #define PG8_SCHED __builtin_amdgcn_sched_barrier(0)
; template <class Epi, class Sched, bool ALIGN_EPI = true>
; __device__ __forceinline__ void gemm_phase(LAS unsigned char* lds, const Gemm g, const Sched& S, const Epi& E) {
;     ...
;             PG8_LDB(B0, 0, 0); PG8_LDB(B1, 0, 1); PG8_SCHED; PG8_LDA(At, 0, 0); PG8_STAGE(PG8_SA(1, 1), a1 + hA, voffA);
;             PG8_WAIT_V(8); PG8_WAIT_L(0); PG8_BAR; PG8_MMA(0, 0, At, B0); PG8_MMA(0, 1, At, B1); PG8_BAR; PG8_SCHED;
;             PG8_LDA(At, 0, 1); PG8_STAGE(PG8_SB(0, 0), b2, voffB); PG8_STAGE(PG8_SB(0, 1), b2 + hB, voffB); PG8_STAGE(PG8_SA(0, 0), a2, voffA);
;             PG8_WAIT_V(8); PG8_WAIT_L(0); PG8_BAR; PG8_MMA(1, 0, At, B0); PG8_MMA(1, 1, At, B1); PG8_BAR; PG8_SCHED;
;             PG8_LDB(B0, 1, 0); PG8_LDB(B1, 1, 1); PG8_SCHED; PG8_LDA(At, 1, 0); PG8_STAGE(PG8_SA(0, 1), a2 + hA, voffA);
;             PG8_WAIT_V(8); PG8_WAIT_L(0); PG8_BAR; PG8_MMA(0, 0, At, B0); PG8_MMA(0, 1, At, B1); PG8_BAR; PG8_SCHED;
	v_mfma_f32_16x16x32_bf16 v[20:23], v[184:187], v[236:239], v[20:23]
	v_mfma_f32_16x16x32_bf16 v[20:23], v[208:211], v[240:243], v[20:23]
	s_setprio 0
	s_add_i32 s19, 0, 0x18000
	s_add_i32 s24, 0, 0x1c000
	v_add_u32_e32 v172, s19, v188
	v_add_u32_e32 v207, s24, v188
	ds_read_b128 v[136:139], v172
	ds_read_b128 v[140:143], v172 offset:1024
	ds_read_b128 v[144:147], v172 offset:2048
	ds_read_b128 v[172:175], v172 offset:3072
	ds_read_b128 v[176:179], v207
	ds_read_b128 v[180:183], v207 offset:1024
	ds_read_b128 v[184:187], v207 offset:2048
	ds_read_b128 v[208:211], v207 offset:3072
	s_add_u32 s10, s64, 0x160000
	s_addc_u32 s11, s65, 0
	s_mov_b32 m0, s76
	v_lshl_add_u64 v[248:249], s[10:11], 0, v[0:1]
	ds_read_b128 v[212:215], v197 offset:32768
	ds_read_b128 v[216:219], v197 offset:33792
	ds_read_b128 v[220:223], v197 offset:34816
	ds_read_b128 v[224:227], v197 offset:35840
	ds_read_b128 v[228:231], v197 offset:36864
	ds_read_b128 v[232:235], v197 offset:37888
	ds_read_b128 v[236:239], v197 offset:38912
	ds_read_b128 v[240:243], v197 offset:39936
	global_load_lds_dwordx4 v[248:249], off
	v_lshl_add_u64 v[248:249], s[10:11], 0, v[148:149]
	s_mov_b32 m0, s77
	s_nop 0
	global_load_lds_dwordx4 v[248:249], off
	s_waitcnt vmcnt(8)
	s_waitcnt lgkmcnt(0)
	s_barrier
	s_setprio 1
	s_waitcnt lgkmcnt(0)
	v_mfma_f32_16x16x32_bf16 v[16:19], v[136:139], v[212:215], v[16:19]
	v_mfma_f32_16x16x32_bf16 v[16:19], v[140:143], v[216:219], v[16:19]
	v_mfma_f32_16x16x32_bf16 v[12:15], v[144:147], v[212:215], v[12:15]
	v_mfma_f32_16x16x32_bf16 v[12:15], v[172:175], v[216:219], v[12:15]
	v_mfma_f32_16x16x32_bf16 v[56:59], v[136:139], v[220:223], v[56:59]
	v_mfma_f32_16x16x32_bf16 v[56:59], v[140:143], v[224:227], v[56:59]
	v_mfma_f32_16x16x32_bf16 v[52:55], v[144:147], v[220:223], v[52:55]
	v_mfma_f32_16x16x32_bf16 v[52:55], v[172:175], v[224:227], v[52:55]
	v_mfma_f32_16x16x32_bf16 v[88:91], v[136:139], v[228:231], v[88:91]
	v_mfma_f32_16x16x32_bf16 v[88:91], v[140:143], v[232:235], v[88:91]
	v_mfma_f32_16x16x32_bf16 v[76:79], v[144:147], v[228:231], v[76:79]
	v_mfma_f32_16x16x32_bf16 v[76:79], v[172:175], v[232:235], v[76:79]
	v_mfma_f32_16x16x32_bf16 v[112:115], v[136:139], v[236:239], v[112:115]
	v_mfma_f32_16x16x32_bf16 v[112:115], v[140:143], v[240:243], v[112:115]
	v_mfma_f32_16x16x32_bf16 v[108:111], v[144:147], v[236:239], v[108:111]
	v_mfma_f32_16x16x32_bf16 v[108:111], v[172:175], v[240:243], v[108:111]
	v_mfma_f32_16x16x32_bf16 v[8:11], v[176:179], v[212:215], v[8:11]
	v_mfma_f32_16x16x32_bf16 v[8:11], v[180:183], v[216:219], v[8:11]
	v_mfma_f32_16x16x32_bf16 v[4:7], v[184:187], v[212:215], v[4:7]
	v_mfma_f32_16x16x32_bf16 v[4:7], v[208:211], v[216:219], v[4:7]
	v_mfma_f32_16x16x32_bf16 v[40:43], v[176:179], v[220:223], v[40:43]
	v_mfma_f32_16x16x32_bf16 v[40:43], v[180:183], v[224:227], v[40:43]
	v_mfma_f32_16x16x32_bf16 v[36:39], v[184:187], v[220:223], v[36:39]
	v_mfma_f32_16x16x32_bf16 v[36:39], v[208:211], v[224:227], v[36:39]
	v_mfma_f32_16x16x32_bf16 v[64:67], v[176:179], v[228:231], v[64:67]
	v_mfma_f32_16x16x32_bf16 v[64:67], v[180:183], v[232:235], v[64:67]
	v_mfma_f32_16x16x32_bf16 v[60:63], v[184:187], v[228:231], v[60:63]
	v_mfma_f32_16x16x32_bf16 v[60:63], v[208:211], v[232:235], v[60:63]
	v_mfma_f32_16x16x32_bf16 v[96:99], v[176:179], v[236:239], v[96:99]
	v_mfma_f32_16x16x32_bf16 v[96:99], v[180:183], v[240:243], v[96:99]
	s_setprio 3
	s_barrier
; #define PG8_STAGE(bufoff, gbase, voff) do { _Pragma("unroll") for (int _i = 0; _i < 2; ++_i) \
;         __builtin_amdgcn_global_load_lds((const unsigned*)((const char*)(gbase) + (voff)[_i]), (LAS unsigned*)(lds + (bufoff) + ldsw + _i * 8192), 16, 0, 0); } while (0)
; #define PG8_LDA(dst, b, h) do { _Pragma("unroll") for (int m = 0; m < 4; ++m) _Pragma("unroll") for (int k = 0; k < 2; ++k) dst[m][k] = *(const LAS bf16x8*)(lds + PG8_SA(b, h) + aoff + m * 2048 + k * 1024); } while (0)
; #define PG8_MMA(ai, bj, At, Bt) do { __builtin_amdgcn_s_setprio(1); _Pragma("unroll") for (int m = 0; m < 4; ++m) _Pragma("unroll") for (int n = 0; n < 2; ++n) _Pragma("unroll") for (int k = 0; k < 2; ++k) \
;         acc[ai][bj][m][n] = __builtin_amdgcn_mfma_f32_16x16x32_bf16(Bt[n][k], At[m][k], acc[ai][bj][m][n], 0, 0, 0); __builtin_amdgcn_s_setprio(0); } while (0)
; #define PG8_WAIT_V(n) asm volatile("s_waitcnt vmcnt(" #n ")" ::: "memory")
; #define PG8_WAIT_L(n) asm volatile("s_waitcnt lgkmcnt(" #n ")" ::: "memory")
; #define PG8_BAR __builtin_amdgcn_s_barrier()
; #define PG8_SCHED __builtin_amdgcn_sched_barrier(0)
; template <class Epi, class Sched, bool ALIGN_EPI = true>
; __device__ __forceinline__ void gemm_phase(LAS unsigned char* lds, const Gemm g, const Sched& S, const Epi& E) {
;     ...
;         for (int t = 0; t < nt; t += 2) {
;     ...
;             PG8_LDA(At, 1, 1); PG8_STAGE(PG8_SB(1, 0), b3, voffB); PG8_STAGE(PG8_SB(1, 1), b3 + hB, voffB); PG8_STAGE(PG8_SA(1, 0), a3, voffA);
;             PG8_WAIT_V(8); PG8_WAIT_L(0); PG8_BAR; PG8_MMA(1, 0, At, B0); PG8_MMA(1, 1, At, B1); PG8_BAR; PG8_SCHED;
	v_mfma_f32_16x16x32_bf16 v[92:95], v[184:187], v[236:239], v[92:95]
	v_mfma_f32_16x16x32_bf16 v[92:95], v[208:211], v[240:243], v[92:95]
	s_setprio 0
	s_add_i32 s10, s19, s66
	v_lshl_add_u64 v[160:161], v[160:161], 0, s[86:87]
	s_mov_b32 m0, s10
	ds_read_b128 v[212:215], v197 offset:49152
	ds_read_b128 v[216:219], v197 offset:50176
	ds_read_b128 v[220:223], v197 offset:51200
	ds_read_b128 v[224:227], v197 offset:52224
	ds_read_b128 v[228:231], v197 offset:53248
	ds_read_b128 v[232:235], v197 offset:54272
	ds_read_b128 v[236:239], v197 offset:55296
	ds_read_b128 v[240:243], v197 offset:56320
	global_load_lds_dwordx4 v[160:161], off
	s_add_i32 m0, s10, 0x2000
	s_add_u32 s10, s62, 0x160080
	v_lshl_add_u64 v[160:161], v[162:163], 0, s[86:87]
	s_addc_u32 s11, s63, 0
	s_add_i32 s19, s24, s66
	global_load_lds_dwordx4 v[160:161], off
	v_lshl_add_u64 v[160:161], s[10:11], 0, v[2:3]
	s_mov_b32 m0, s19
	s_nop 0
	global_load_lds_dwordx4 v[160:161], off
	v_lshl_add_u64 v[160:161], s[10:11], 0, v[150:151]
	s_add_i32 m0, s19, 0x2000
	s_nop 0
	global_load_lds_dwordx4 v[160:161], off
	v_lshl_add_u64 v[160:161], v[244:245], 0, s[86:87]
	s_mov_b32 m0, s80
	s_nop 0
	global_load_lds_dwordx4 v[160:161], off
	v_lshl_add_u64 v[160:161], v[246:247], 0, s[86:87]
	s_mov_b32 m0, s81
	s_nop 0
	global_load_lds_dwordx4 v[160:161], off
	s_waitcnt vmcnt(8)
	s_waitcnt lgkmcnt(0)
	s_barrier
	s_setprio 1
	s_waitcnt lgkmcnt(0)
	v_mfma_f32_16x16x32_bf16 v[128:131], v[136:139], v[212:215], v[128:131]
	v_mfma_f32_16x16x32_bf16 v[128:131], v[140:143], v[216:219], v[128:131]
	v_mfma_f32_16x16x32_bf16 v[124:127], v[144:147], v[212:215], v[124:127]
	v_mfma_f32_16x16x32_bf16 v[124:127], v[172:175], v[216:219], v[124:127]
	v_mfma_f32_16x16x32_bf16 v[104:107], v[136:139], v[220:223], v[104:107]
	v_mfma_f32_16x16x32_bf16 v[104:107], v[140:143], v[224:227], v[104:107]
	v_mfma_f32_16x16x32_bf16 v[100:103], v[144:147], v[220:223], v[100:103]
	v_mfma_f32_16x16x32_bf16 v[100:103], v[172:175], v[224:227], v[100:103]
	v_mfma_f32_16x16x32_bf16 v[72:75], v[136:139], v[228:231], v[72:75]
	v_mfma_f32_16x16x32_bf16 v[72:75], v[140:143], v[232:235], v[72:75]
	v_mfma_f32_16x16x32_bf16 v[68:71], v[144:147], v[228:231], v[68:71]
	v_mfma_f32_16x16x32_bf16 v[68:71], v[172:175], v[232:235], v[68:71]
	v_mfma_f32_16x16x32_bf16 v[32:35], v[136:139], v[236:239], v[32:35]
	v_mfma_f32_16x16x32_bf16 v[32:35], v[140:143], v[240:243], v[32:35]
	v_mfma_f32_16x16x32_bf16 v[28:31], v[144:147], v[236:239], v[28:31]
	v_mfma_f32_16x16x32_bf16 v[28:31], v[172:175], v[240:243], v[28:31]
	v_mfma_f32_16x16x32_bf16 v[120:123], v[176:179], v[212:215], v[120:123]
	v_mfma_f32_16x16x32_bf16 v[120:123], v[180:183], v[216:219], v[120:123]
	v_mfma_f32_16x16x32_bf16 v[116:119], v[184:187], v[212:215], v[116:119]
	v_mfma_f32_16x16x32_bf16 v[116:119], v[208:211], v[216:219], v[116:119]
	v_mfma_f32_16x16x32_bf16 v[84:87], v[176:179], v[220:223], v[84:87]
	v_mfma_f32_16x16x32_bf16 v[84:87], v[180:183], v[224:227], v[84:87]
	v_mfma_f32_16x16x32_bf16 v[80:83], v[184:187], v[220:223], v[80:83]
	v_mfma_f32_16x16x32_bf16 v[80:83], v[208:211], v[224:227], v[80:83]
	v_mfma_f32_16x16x32_bf16 v[48:51], v[176:179], v[228:231], v[48:51]
	v_mfma_f32_16x16x32_bf16 v[48:51], v[180:183], v[232:235], v[48:51]
	v_mfma_f32_16x16x32_bf16 v[44:47], v[184:187], v[228:231], v[44:47]
	v_mfma_f32_16x16x32_bf16 v[44:47], v[208:211], v[232:235], v[44:47]
	v_mfma_f32_16x16x32_bf16 v[24:27], v[176:179], v[236:239], v[24:27]
	v_mfma_f32_16x16x32_bf16 v[24:27], v[180:183], v[240:243], v[24:27]
	s_setprio 3
	s_barrier
	v_mfma_f32_16x16x32_bf16 v[20:23], v[184:187], v[236:239], v[20:23]
	v_mfma_f32_16x16x32_bf16 v[20:23], v[208:211], v[240:243], v[20:23]
	s_setprio 0
	s_add_i32 s18, s18, 2
	s_cmpk_gt_u32 s18, 0x55
	s_mov_b64 s[10:11], vcc
	s_cbranch_scc0 .LBB0_1111
